# plus merge gate-GEMM k-loop (256x128 tiles) converted to LDS-DMA + W-stationary pipelined schedule; residual epilogues hand-written (batched loads)
# speedup vs baseline: 1.0188x; 1.0188x over previous
; DI void phase_resid(const Params& p, int from_x, const u16* A, int K, const u16* W, float* rowss_next, bool last,
;                     unsigned char* smem) {
;     ...
;   for (int it = vblock(); it < nfull; it += gridDim.x) {
.Lresid_next_outproj:
	s_add_i32 s49, s49, s10
	s_add_i32 s50, s50, s51
	s_add_i32 s52, s52, s53
	s_cmp_ge_i32 s49, s48
	s_cbranch_scc1 .LBB0_226

; DI f32x4 mfma16(bf16x8 a, bf16x8 b, f32x4 c) { return __builtin_amdgcn_mfma_f32_16x16x32_bf16(a, b, c, 0, 0, 0); }
; template <int MI, int NI>
; DI void gemm_kloop(const u16* Au, int lda, const u16* Bu, int ldb, int K, f32x4 (&acc)[NI][MI], unsigned char* smem) {
;     ...
;   for (int kt = 0; kt < nk; ++kt) {
;     __syncthreads();
;     if (kt + 1 < nk) {
;       SWRITE((kt + 1) & 1);
;       if (kt + 2 < nk) GLOAD((kt + 2) << 6);
;     }
;     {
;       const unsigned char* sa = smem + (kt & 1) * 65536;
;       const unsigned char* sb = sa + 32768;
; #pragma unroll
;       for (int ks = 0; ks < 2; ++ks) {
;         const int fo = ks ? fro1 : fro0;
;         bf16x8 af[MI];
; #pragma unroll
;         for (int i = 0; i < MI; ++i) af[i] = *(const bf16x8*)(sa + (wm * 16 * MI + i * 16) * 128 + fo);
; #pragma unroll
;         for (int nh = 0; nh < NI; nh += 4) {
;           bf16x8 wf[4];
; #pragma unroll
;           for (int i = 0; i < 4; ++i) wf[i] = *(const bf16x8*)(sb + (wn * 16 * NI + (nh + i) * 16) * 128 + fo);
; #pragma unroll
;           for (int ni = 0; ni < 4; ++ni)
; #pragma unroll
;             for (int mi = 0; mi < MI; ++mi) acc[nh + ni][mi] = mfma16(wf[ni], af[mi], acc[nh + ni][mi]);
;         }
;       }
;     }
.Lk_outproj:
	s_waitcnt vmcnt(0) lgkmcnt(0)
	s_barrier
	ds_read_b128 v[122:125], v183
	ds_read_b128 v[126:129], v183 offset:2048
	ds_read_b128 v[130:133], v183 offset:4096
	ds_read_b128 v[138:141], v183 offset:6144
	ds_read_b128 v[162:165], v227 offset:32768
	ds_read_b128 v[184:187], v227 offset:34816
	ds_read_b128 v[188:191], v227 offset:36864
	s_and_b32 s92, s95, 1
	s_xor_b32 s92, s92, 1
	s_lshl_b32 s92, s92, 16
	s_waitcnt lgkmcnt(2)
	v_mfma_f32_16x16x32_bf16 v[134:137], v[162:165], v[122:125], v[134:137]
	ds_read_b128 v[192:195], v227 offset:38912
	v_mfma_f32_16x16x32_bf16 v[118:121], v[162:165], v[126:129], v[118:121]
	v_mfma_f32_16x16x32_bf16 v[114:117], v[162:165], v[130:133], v[114:117]
	s_add_u32 m0, s92, s94
	s_nop 0
	global_load_lds_dwordx4 v255, s[88:89]
	v_mfma_f32_16x16x32_bf16 v[110:113], v[162:165], v[138:141], v[110:113]
	s_waitcnt lgkmcnt(2)
	v_mfma_f32_16x16x32_bf16 v[106:109], v[184:187], v[122:125], v[106:109]
	ds_read_b128 v[162:165], v227 offset:40960
	v_mfma_f32_16x16x32_bf16 v[102:105], v[184:187], v[126:129], v[102:105]
	ds_read_b128 v[142:145], v226
	v_mfma_f32_16x16x32_bf16 v[98:101], v[184:187], v[130:133], v[98:101]
	s_add_u32 m0, m0, 0x2000
	s_add_u32 s92, s88, 0x20000
	s_addc_u32 s93, s89, 0
	global_load_lds_dwordx4 v255, s[92:93]
	v_mfma_f32_16x16x32_bf16 v[94:97], v[184:187], v[138:141], v[94:97]
	s_waitcnt lgkmcnt(3)
	v_mfma_f32_16x16x32_bf16 v[90:93], v[188:191], v[122:125], v[90:93]
	ds_read_b128 v[184:187], v227 offset:43008
	v_mfma_f32_16x16x32_bf16 v[86:89], v[188:191], v[126:129], v[86:89]
	ds_read_b128 v[146:149], v226 offset:2048
	v_mfma_f32_16x16x32_bf16 v[78:81], v[188:191], v[130:133], v[78:81]
	s_add_u32 m0, m0, 0x2000
	s_add_u32 s92, s88, 0x40000
	s_addc_u32 s93, s89, 0
	global_load_lds_dwordx4 v255, s[92:93]
	v_mfma_f32_16x16x32_bf16 v[70:73], v[188:191], v[138:141], v[70:73]
	s_waitcnt lgkmcnt(4)
	v_mfma_f32_16x16x32_bf16 v[58:61], v[192:195], v[122:125], v[58:61]
	ds_read_b128 v[188:191], v227 offset:45056
	v_mfma_f32_16x16x32_bf16 v[54:57], v[192:195], v[126:129], v[54:57]
	ds_read_b128 v[150:153], v226 offset:4096
	v_mfma_f32_16x16x32_bf16 v[50:53], v[192:195], v[130:133], v[50:53]
	s_add_u32 m0, m0, 0x2000
	s_add_u32 s92, s88, 0x60000
	s_addc_u32 s93, s89, 0
	global_load_lds_dwordx4 v255, s[92:93]
	v_mfma_f32_16x16x32_bf16 v[46:49], v[192:195], v[138:141], v[46:49]
	s_waitcnt lgkmcnt(5)
	v_mfma_f32_16x16x32_bf16 v[42:45], v[162:165], v[122:125], v[42:45]
	ds_read_b128 v[192:195], v227 offset:47104
	v_mfma_f32_16x16x32_bf16 v[34:37], v[162:165], v[126:129], v[34:37]
	ds_read_b128 v[154:157], v226 offset:6144
	v_mfma_f32_16x16x32_bf16 v[22:25], v[162:165], v[130:133], v[22:25]
	s_add_u32 m0, m0, 0x2000
	s_nop 0
	global_load_lds_dwordx4 v255, s[90:91]
	v_mfma_f32_16x16x32_bf16 v[18:21], v[162:165], v[138:141], v[18:21]
	s_waitcnt lgkmcnt(5)
	v_mfma_f32_16x16x32_bf16 v[14:17], v[184:187], v[122:125], v[14:17]
	ds_read_b128 v[162:165], v254 offset:32768
	v_mfma_f32_16x16x32_bf16 v[6:9], v[184:187], v[126:129], v[6:9]
	v_mfma_f32_16x16x32_bf16 v[2:5], v[184:187], v[130:133], v[2:5]
	s_add_u32 m0, m0, 0x2000
	s_add_u32 s92, s90, 0x20000
	s_addc_u32 s93, s91, 0
	global_load_lds_dwordx4 v255, s[92:93]
	v_mfma_f32_16x16x32_bf16 v[30:33], v[184:187], v[138:141], v[30:33]
	s_waitcnt lgkmcnt(4)
	v_mfma_f32_16x16x32_bf16 v[10:13], v[188:191], v[122:125], v[10:13]
	ds_read_b128 v[184:187], v254 offset:34816
	v_mfma_f32_16x16x32_bf16 v[26:29], v[188:191], v[126:129], v[26:29]
	v_mfma_f32_16x16x32_bf16 v[38:41], v[188:191], v[130:133], v[38:41]
	s_add_u32 m0, m0, 0x2000
	s_add_u32 s92, s90, 0x40000
	s_addc_u32 s93, s91, 0
	global_load_lds_dwordx4 v255, s[92:93]
	v_mfma_f32_16x16x32_bf16 v[66:69], v[188:191], v[138:141], v[66:69]
	s_waitcnt lgkmcnt(3)
	v_mfma_f32_16x16x32_bf16 v[82:85], v[192:195], v[122:125], v[82:85]
	ds_read_b128 v[188:191], v254 offset:36864
	v_mfma_f32_16x16x32_bf16 v[74:77], v[192:195], v[126:129], v[74:77]
	v_mfma_f32_16x16x32_bf16 v[62:65], v[192:195], v[130:133], v[62:65]
	s_add_u32 m0, m0, 0x2000
	s_add_u32 s92, s90, 0x60000
	s_addc_u32 s93, s91, 0
	global_load_lds_dwordx4 v255, s[92:93]
	v_mfma_f32_16x16x32_bf16 v[158:161], v[192:195], v[138:141], v[158:161]
	s_waitcnt lgkmcnt(2)
	v_mfma_f32_16x16x32_bf16 v[134:137], v[162:165], v[142:145], v[134:137]
	ds_read_b128 v[192:195], v254 offset:38912
	v_mfma_f32_16x16x32_bf16 v[118:121], v[162:165], v[146:149], v[118:121]
	v_mfma_f32_16x16x32_bf16 v[114:117], v[162:165], v[150:153], v[114:117]
	v_mfma_f32_16x16x32_bf16 v[110:113], v[162:165], v[154:157], v[110:113]
	s_waitcnt lgkmcnt(2)
	v_mfma_f32_16x16x32_bf16 v[106:109], v[184:187], v[142:145], v[106:109]
	ds_read_b128 v[162:165], v254 offset:40960
	v_mfma_f32_16x16x32_bf16 v[102:105], v[184:187], v[146:149], v[102:105]
	v_mfma_f32_16x16x32_bf16 v[98:101], v[184:187], v[150:153], v[98:101]
	v_mfma_f32_16x16x32_bf16 v[94:97], v[184:187], v[154:157], v[94:97]
	s_waitcnt lgkmcnt(2)
	v_mfma_f32_16x16x32_bf16 v[90:93], v[188:191], v[142:145], v[90:93]
	ds_read_b128 v[184:187], v254 offset:43008
	v_mfma_f32_16x16x32_bf16 v[86:89], v[188:191], v[146:149], v[86:89]
	v_mfma_f32_16x16x32_bf16 v[78:81], v[188:191], v[150:153], v[78:81]
	v_mfma_f32_16x16x32_bf16 v[70:73], v[188:191], v[154:157], v[70:73]
	s_waitcnt lgkmcnt(2)
	v_mfma_f32_16x16x32_bf16 v[58:61], v[192:195], v[142:145], v[58:61]
	ds_read_b128 v[188:191], v254 offset:45056
	v_mfma_f32_16x16x32_bf16 v[54:57], v[192:195], v[146:149], v[54:57]
	v_mfma_f32_16x16x32_bf16 v[50:53], v[192:195], v[150:153], v[50:53]
	v_mfma_f32_16x16x32_bf16 v[46:49], v[192:195], v[154:157], v[46:49]
	s_waitcnt lgkmcnt(2)
; DI f32x4 mfma16(bf16x8 a, bf16x8 b, f32x4 c) { return __builtin_amdgcn_mfma_f32_16x16x32_bf16(a, b, c, 0, 0, 0); }
; template <int MI, int NI>
; DI void gemm_kloop(const u16* Au, int lda, const u16* Bu, int ldb, int K, f32x4 (&acc)[NI][MI], unsigned char* smem) {
;     ...
;   for (int kt = 0; kt < nk; ++kt) {
;     __syncthreads();
;     if (kt + 1 < nk) {
;       SWRITE((kt + 1) & 1);
;       if (kt + 2 < nk) GLOAD((kt + 2) << 6);
;     }
;     {
;       const unsigned char* sa = smem + (kt & 1) * 65536;
;       const unsigned char* sb = sa + 32768;
; #pragma unroll
;       for (int ks = 0; ks < 2; ++ks) {
;         const int fo = ks ? fro1 : fro0;
;         bf16x8 af[MI];
; #pragma unroll
;         for (int i = 0; i < MI; ++i) af[i] = *(const bf16x8*)(sa + (wm * 16 * MI + i * 16) * 128 + fo);
; #pragma unroll
;         for (int nh = 0; nh < NI; nh += 4) {
;           bf16x8 wf[4];
; #pragma unroll
;           for (int i = 0; i < 4; ++i) wf[i] = *(const bf16x8*)(sb + (wn * 16 * NI + (nh + i) * 16) * 128 + fo);
; #pragma unroll
;           for (int ni = 0; ni < 4; ++ni)
; #pragma unroll
;             for (int mi = 0; mi < MI; ++mi) acc[nh + ni][mi] = mfma16(wf[ni], af[mi], acc[nh + ni][mi]);
;         }
;       }
;     }
;   }
;   __syncthreads();
	v_mfma_f32_16x16x32_bf16 v[42:45], v[162:165], v[142:145], v[42:45]
	ds_read_b128 v[192:195], v254 offset:47104
	v_mfma_f32_16x16x32_bf16 v[34:37], v[162:165], v[146:149], v[34:37]
	v_mfma_f32_16x16x32_bf16 v[22:25], v[162:165], v[150:153], v[22:25]
	v_mfma_f32_16x16x32_bf16 v[18:21], v[162:165], v[154:157], v[18:21]
	s_waitcnt lgkmcnt(2)
	v_mfma_f32_16x16x32_bf16 v[14:17], v[184:187], v[142:145], v[14:17]
	v_mfma_f32_16x16x32_bf16 v[6:9], v[184:187], v[146:149], v[6:9]
	v_mfma_f32_16x16x32_bf16 v[2:5], v[184:187], v[150:153], v[2:5]
	v_mfma_f32_16x16x32_bf16 v[30:33], v[184:187], v[154:157], v[30:33]
	s_waitcnt lgkmcnt(1)
	v_mfma_f32_16x16x32_bf16 v[10:13], v[188:191], v[142:145], v[10:13]
	v_mfma_f32_16x16x32_bf16 v[26:29], v[188:191], v[146:149], v[26:29]
	v_mfma_f32_16x16x32_bf16 v[38:41], v[188:191], v[150:153], v[38:41]
	v_mfma_f32_16x16x32_bf16 v[66:69], v[188:191], v[154:157], v[66:69]
	s_waitcnt lgkmcnt(0)
	v_mfma_f32_16x16x32_bf16 v[82:85], v[192:195], v[142:145], v[82:85]
	v_mfma_f32_16x16x32_bf16 v[74:77], v[192:195], v[146:149], v[74:77]
	v_mfma_f32_16x16x32_bf16 v[62:65], v[192:195], v[150:153], v[62:65]
	v_mfma_f32_16x16x32_bf16 v[158:161], v[192:195], v[154:157], v[158:161]
	v_xor_b32_e32 v183, 0x10000, v183
	v_xor_b32_e32 v226, 0x10000, v226
	v_xor_b32_e32 v227, 0x10000, v227
	v_xor_b32_e32 v254, 0x10000, v254
	s_add_u32 s88, s88, 0x80
	s_addc_u32 s89, s89, 0
	s_add_u32 s90, s90, 0x80
	s_addc_u32 s91, s91, 0
	s_add_u32 s95, s95, 1
	s_cmp_lg_u32 s95, 14
	s_cbranch_scc1 .Lk_outproj
	s_waitcnt vmcnt(0)
	s_barrier
	s_add_u32 m0, s94, 0x10000
	s_nop 0
	global_load_lds_dwordx4 v255, s[88:89]
	s_add_u32 m0, m0, 0x2000
	s_add_u32 s92, s88, 0x20000
	s_addc_u32 s93, s89, 0
	global_load_lds_dwordx4 v255, s[92:93]
	s_add_u32 m0, m0, 0x2000
	s_add_u32 s92, s88, 0x40000
	s_addc_u32 s93, s89, 0
	global_load_lds_dwordx4 v255, s[92:93]
	s_add_u32 m0, m0, 0x2000
	s_add_u32 s92, s88, 0x60000
	s_addc_u32 s93, s89, 0
	global_load_lds_dwordx4 v255, s[92:93]
	s_add_u32 m0, m0, 0x2000
	s_nop 0
	global_load_lds_dwordx4 v255, s[90:91]
	s_add_u32 m0, m0, 0x2000
	s_add_u32 s92, s90, 0x20000
	s_addc_u32 s93, s91, 0
	global_load_lds_dwordx4 v255, s[92:93]
	s_add_u32 m0, m0, 0x2000
	s_add_u32 s92, s90, 0x40000
	s_addc_u32 s93, s91, 0
	global_load_lds_dwordx4 v255, s[92:93]
	s_add_u32 m0, m0, 0x2000
	s_add_u32 s92, s90, 0x60000
	s_addc_u32 s93, s91, 0
	global_load_lds_dwordx4 v255, s[92:93]
	v_add_u32_e32 v150, v181, v180
	ds_read_b128 v[122:125], v150 offset:32768
	v_add_u32_e32 v146, v179, v180
	ds_read_b128 v[126:129], v146
	ds_read_b128 v[130:133], v146 offset:2048
	ds_read_b128 v[138:141], v150 offset:34816
	ds_read_b128 v[142:145], v146 offset:4096
	ds_read_b128 v[146:149], v146 offset:6144
	s_waitcnt lgkmcnt(4)
	v_mfma_f32_16x16x32_bf16 v[134:137], v[122:125], v[126:129], v[134:137]
	v_add_u32_e32 v154, v181, v178
	v_or_b32_e32 v225, 0x18000, v181
	v_add_u32_e32 v192, v225, v180
	s_waitcnt lgkmcnt(3)
	v_mfma_f32_16x16x32_bf16 v[118:121], v[122:125], v[130:133], v[118:121]
	v_add_u32_e32 v225, v225, v178
	s_waitcnt lgkmcnt(1)
	v_mfma_f32_16x16x32_bf16 v[114:117], v[122:125], v[142:145], v[114:117]
	s_waitcnt lgkmcnt(0)
	v_mfma_f32_16x16x32_bf16 v[110:113], v[122:125], v[146:149], v[110:113]
	v_mfma_f32_16x16x32_bf16 v[106:109], v[138:141], v[126:129], v[106:109]
	v_mfma_f32_16x16x32_bf16 v[102:105], v[138:141], v[130:133], v[102:105]
	v_mfma_f32_16x16x32_bf16 v[98:101], v[138:141], v[142:145], v[98:101]
	v_mfma_f32_16x16x32_bf16 v[94:97], v[138:141], v[146:149], v[94:97]
	ds_read_b128 v[122:125], v150 offset:36864
	ds_read_b128 v[138:141], v150 offset:38912
	s_waitcnt lgkmcnt(1)
	v_mfma_f32_16x16x32_bf16 v[90:93], v[122:125], v[126:129], v[90:93]
	v_mfma_f32_16x16x32_bf16 v[86:89], v[122:125], v[130:133], v[86:89]
	v_mfma_f32_16x16x32_bf16 v[78:81], v[122:125], v[142:145], v[78:81]
	v_mfma_f32_16x16x32_bf16 v[70:73], v[122:125], v[146:149], v[70:73]
	s_waitcnt lgkmcnt(0)
	v_mfma_f32_16x16x32_bf16 v[58:61], v[138:141], v[126:129], v[58:61]
	v_mfma_f32_16x16x32_bf16 v[54:57], v[138:141], v[130:133], v[54:57]
	v_mfma_f32_16x16x32_bf16 v[50:53], v[138:141], v[142:145], v[50:53]
	v_mfma_f32_16x16x32_bf16 v[46:49], v[138:141], v[146:149], v[46:49]
	ds_read_b128 v[122:125], v150 offset:40960
	ds_read_b128 v[138:141], v150 offset:43008
	s_waitcnt lgkmcnt(1)
	v_mfma_f32_16x16x32_bf16 v[42:45], v[122:125], v[126:129], v[42:45]
	v_mfma_f32_16x16x32_bf16 v[34:37], v[122:125], v[130:133], v[34:37]
	v_mfma_f32_16x16x32_bf16 v[22:25], v[122:125], v[142:145], v[22:25]
	v_mfma_f32_16x16x32_bf16 v[18:21], v[122:125], v[146:149], v[18:21]
	s_waitcnt lgkmcnt(0)
	v_mfma_f32_16x16x32_bf16 v[14:17], v[138:141], v[126:129], v[14:17]
	v_mfma_f32_16x16x32_bf16 v[6:9], v[138:141], v[130:133], v[6:9]
	v_mfma_f32_16x16x32_bf16 v[2:5], v[138:141], v[142:145], v[2:5]
	v_mfma_f32_16x16x32_bf16 v[30:33], v[138:141], v[146:149], v[30:33]
	ds_read_b128 v[122:125], v150 offset:45056
	ds_read_b128 v[138:141], v150 offset:47104
	v_add_u32_e32 v150, v179, v178
	v_add_u32_e32 v179, 0x10000, v179
	s_waitcnt lgkmcnt(1)
	v_mfma_f32_16x16x32_bf16 v[10:13], v[122:125], v[126:129], v[10:13]
	v_mfma_f32_16x16x32_bf16 v[26:29], v[122:125], v[130:133], v[26:29]
	v_mfma_f32_16x16x32_bf16 v[38:41], v[122:125], v[142:145], v[38:41]
	v_mfma_f32_16x16x32_bf16 v[66:69], v[122:125], v[146:149], v[66:69]
	ds_read_b128 v[122:125], v154 offset:32768
	s_waitcnt lgkmcnt(1)
; DI f32x4 mfma16(bf16x8 a, bf16x8 b, f32x4 c) { return __builtin_amdgcn_mfma_f32_16x16x32_bf16(a, b, c, 0, 0, 0); }
; template <int MI, int NI>
; DI void gemm_kloop(const u16* Au, int lda, const u16* Bu, int ldb, int K, f32x4 (&acc)[NI][MI], unsigned char* smem) {
;     ...
;     {
;       const unsigned char* sa = smem + (kt & 1) * 65536;
;       const unsigned char* sb = sa + 32768;
; #pragma unroll
;       for (int ks = 0; ks < 2; ++ks) {
;         const int fo = ks ? fro1 : fro0;
;         bf16x8 af[MI];
; #pragma unroll
;         for (int i = 0; i < MI; ++i) af[i] = *(const bf16x8*)(sa + (wm * 16 * MI + i * 16) * 128 + fo);
; #pragma unroll
;         for (int nh = 0; nh < NI; nh += 4) {
;           bf16x8 wf[4];
; #pragma unroll
;           for (int i = 0; i < 4; ++i) wf[i] = *(const bf16x8*)(sb + (wn * 16 * NI + (nh + i) * 16) * 128 + fo);
; #pragma unroll
;           for (int ni = 0; ni < 4; ++ni)
; #pragma unroll
;             for (int mi = 0; mi < MI; ++mi) acc[nh + ni][mi] = mfma16(wf[ni], af[mi], acc[nh + ni][mi]);
;         }
;       }
;     }
;   }
;   __syncthreads();
	v_mfma_f32_16x16x32_bf16 v[82:85], v[138:141], v[126:129], v[82:85]
	v_mfma_f32_16x16x32_bf16 v[74:77], v[138:141], v[130:133], v[74:77]
	v_mfma_f32_16x16x32_bf16 v[62:65], v[138:141], v[142:145], v[62:65]
	v_mfma_f32_16x16x32_bf16 v[126:129], v[138:141], v[146:149], v[158:161]
	ds_read_b128 v[130:133], v150
	ds_read_b128 v[138:141], v150 offset:2048
	ds_read_b128 v[142:145], v154 offset:34816
	ds_read_b128 v[146:149], v150 offset:4096
	ds_read_b128 v[150:153], v150 offset:6144
	s_waitcnt lgkmcnt(4)
	v_mfma_f32_16x16x32_bf16 v[134:137], v[122:125], v[130:133], v[134:137]
	s_waitcnt lgkmcnt(3)
	v_mfma_f32_16x16x32_bf16 v[118:121], v[122:125], v[138:141], v[118:121]
	s_waitcnt lgkmcnt(1)
	v_mfma_f32_16x16x32_bf16 v[114:117], v[122:125], v[146:149], v[114:117]
	s_waitcnt lgkmcnt(0)
	v_mfma_f32_16x16x32_bf16 v[110:113], v[122:125], v[150:153], v[110:113]
	v_mfma_f32_16x16x32_bf16 v[106:109], v[142:145], v[130:133], v[106:109]
	v_mfma_f32_16x16x32_bf16 v[102:105], v[142:145], v[138:141], v[102:105]
	v_mfma_f32_16x16x32_bf16 v[98:101], v[142:145], v[146:149], v[98:101]
	v_mfma_f32_16x16x32_bf16 v[94:97], v[142:145], v[150:153], v[94:97]
	ds_read_b128 v[122:125], v154 offset:36864
	ds_read_b128 v[142:145], v154 offset:38912
	s_waitcnt lgkmcnt(1)
	v_mfma_f32_16x16x32_bf16 v[90:93], v[122:125], v[130:133], v[90:93]
	v_mfma_f32_16x16x32_bf16 v[86:89], v[122:125], v[138:141], v[86:89]
	v_mfma_f32_16x16x32_bf16 v[78:81], v[122:125], v[146:149], v[78:81]
	v_mfma_f32_16x16x32_bf16 v[70:73], v[122:125], v[150:153], v[70:73]
	s_waitcnt lgkmcnt(0)
	v_mfma_f32_16x16x32_bf16 v[58:61], v[142:145], v[130:133], v[58:61]
	v_mfma_f32_16x16x32_bf16 v[54:57], v[142:145], v[138:141], v[54:57]
	v_mfma_f32_16x16x32_bf16 v[50:53], v[142:145], v[146:149], v[50:53]
	v_mfma_f32_16x16x32_bf16 v[46:49], v[142:145], v[150:153], v[46:49]
	ds_read_b128 v[122:125], v154 offset:40960
	ds_read_b128 v[142:145], v154 offset:43008
	s_waitcnt lgkmcnt(1)
	v_mfma_f32_16x16x32_bf16 v[42:45], v[122:125], v[130:133], v[42:45]
	v_mfma_f32_16x16x32_bf16 v[34:37], v[122:125], v[138:141], v[34:37]
	v_mfma_f32_16x16x32_bf16 v[22:25], v[122:125], v[146:149], v[22:25]
	v_mfma_f32_16x16x32_bf16 v[18:21], v[122:125], v[150:153], v[18:21]
	s_waitcnt lgkmcnt(0)
	v_mfma_f32_16x16x32_bf16 v[14:17], v[142:145], v[130:133], v[14:17]
	v_mfma_f32_16x16x32_bf16 v[6:9], v[142:145], v[138:141], v[6:9]
	v_mfma_f32_16x16x32_bf16 v[2:5], v[142:145], v[146:149], v[2:5]
	v_mfma_f32_16x16x32_bf16 v[30:33], v[142:145], v[150:153], v[30:33]
	ds_read_b128 v[122:125], v154 offset:45056
	ds_read_b128 v[142:145], v154 offset:47104
	s_waitcnt vmcnt(0) lgkmcnt(0)
	s_barrier
	v_mfma_f32_16x16x32_bf16 v[10:13], v[122:125], v[130:133], v[10:13]
	v_mfma_f32_16x16x32_bf16 v[26:29], v[122:125], v[138:141], v[26:29]
	v_mfma_f32_16x16x32_bf16 v[38:41], v[122:125], v[146:149], v[38:41]
	v_mfma_f32_16x16x32_bf16 v[66:69], v[122:125], v[150:153], v[66:69]
	ds_read_b128 v[122:125], v192
	v_mfma_f32_16x16x32_bf16 v[126:129], v[142:145], v[150:153], v[126:129]
	v_add_u32_e32 v150, v179, v180
	v_mfma_f32_16x16x32_bf16 v[82:85], v[142:145], v[130:133], v[82:85]
	v_mfma_f32_16x16x32_bf16 v[74:77], v[142:145], v[138:141], v[74:77]
	v_mfma_f32_16x16x32_bf16 v[62:65], v[142:145], v[146:149], v[62:65]
	ds_read_b128 v[130:133], v150
	ds_read_b128 v[138:141], v150 offset:2048
	ds_read_b128 v[142:145], v192 offset:2048
	ds_read_b128 v[146:149], v150 offset:4096
	ds_read_b128 v[150:153], v150 offset:6144
	s_waitcnt lgkmcnt(4)
	v_mfma_f32_16x16x32_bf16 v[134:137], v[122:125], v[130:133], v[134:137]
	s_waitcnt lgkmcnt(3)
	v_mfma_f32_16x16x32_bf16 v[118:121], v[122:125], v[138:141], v[118:121]
	s_waitcnt lgkmcnt(1)
	v_mfma_f32_16x16x32_bf16 v[114:117], v[122:125], v[146:149], v[114:117]
	s_waitcnt lgkmcnt(0)
	v_mfma_f32_16x16x32_bf16 v[110:113], v[122:125], v[150:153], v[110:113]
	v_mfma_f32_16x16x32_bf16 v[106:109], v[142:145], v[130:133], v[106:109]
	v_mfma_f32_16x16x32_bf16 v[102:105], v[142:145], v[138:141], v[102:105]
	v_mfma_f32_16x16x32_bf16 v[98:101], v[142:145], v[146:149], v[98:101]
	v_mfma_f32_16x16x32_bf16 v[142:145], v[142:145], v[150:153], v[94:97]
	s_nop 2
	ds_read_b128 v[94:97], v192 offset:4096
	ds_read_b128 v[122:125], v192 offset:6144
	s_waitcnt lgkmcnt(0)
	v_mfma_f32_16x16x32_bf16 v[158:161], v[122:125], v[130:133], v[58:61]
	v_mfma_f32_16x16x32_bf16 v[162:165], v[122:125], v[138:141], v[54:57]
	s_nop 2
	ds_read_b128 v[54:57], v192 offset:8192
	ds_read_b128 v[58:61], v192 offset:10240
	s_waitcnt lgkmcnt(1)
	v_mfma_f32_16x16x32_bf16 v[180:183], v[54:57], v[150:153], v[18:21]
	s_waitcnt lgkmcnt(0)
	v_mfma_f32_16x16x32_bf16 v[184:187], v[58:61], v[130:133], v[14:17]
	s_nop 2
	ds_read_b128 v[14:17], v192 offset:12288
	ds_read_b128 v[18:21], v192 offset:14336
	s_waitcnt lgkmcnt(1)
	v_mfma_f32_16x16x32_bf16 v[192:195], v[14:17], v[130:133], v[10:13]
	s_nop 2
	ds_read_b128 v[10:13], v225
	v_mfma_f32_16x16x32_bf16 v[154:157], v[94:97], v[130:133], v[90:93]
	v_mfma_f32_16x16x32_bf16 v[86:89], v[94:97], v[138:141], v[86:89]
	v_mfma_f32_16x16x32_bf16 v[78:81], v[94:97], v[146:149], v[78:81]
	v_mfma_f32_16x16x32_bf16 v[70:73], v[94:97], v[150:153], v[70:73]
	v_mfma_f32_16x16x32_bf16 v[50:53], v[122:125], v[146:149], v[50:53]
	v_mfma_f32_16x16x32_bf16 v[46:49], v[122:125], v[150:153], v[46:49]
	v_mfma_f32_16x16x32_bf16 v[42:45], v[54:57], v[130:133], v[42:45]
	v_mfma_f32_16x16x32_bf16 v[34:37], v[54:57], v[138:141], v[34:37]
	v_mfma_f32_16x16x32_bf16 v[168:171], v[54:57], v[146:149], v[22:25]
	v_mfma_f32_16x16x32_bf16 v[6:9], v[58:61], v[138:141], v[6:9]
	v_mfma_f32_16x16x32_bf16 v[2:5], v[58:61], v[146:149], v[2:5]
	v_mfma_f32_16x16x32_bf16 v[188:191], v[58:61], v[150:153], v[30:33]
	v_mfma_f32_16x16x32_bf16 v[226:229], v[14:17], v[138:141], v[26:29]
	v_mfma_f32_16x16x32_bf16 v[38:41], v[14:17], v[146:149], v[38:41]
	v_mfma_f32_16x16x32_bf16 v[66:69], v[14:17], v[150:153], v[66:69]
	s_waitcnt lgkmcnt(1)
; template <int MI, int NI>
; DI void resid_epilogue(const Params& p, int from_x, const f32x4 (&acc)[NI][MI], int row0, int n0, float* rowss_next, bool last, int lm, int lg) {
; #pragma unroll
;   for (int mi = 0; mi < MI; ++mi) {
;     const int m = row0 + mi * 16 + lm;
;     const float* hr = hrow_r(p, from_x == 1 ? 0 : 1, m);
;     float* hw = hrow_w(p, m);
;     u16* hbr = p.hb + (size_t)m * DM;
;     float ss = 0.f;
; #pragma unroll
;     for (int ni = 0; ni < NI; ++ni) {
;       const int n = n0 + ni * 16 + lg * 4;
;       float4 h;
;       if (from_x >= 2) {
;         const u32x2 pk = *(const u32x2*)(hbr + n);
;         h = make_float4(__uint_as_float(pk[0] << 16), __uint_as_float(pk[0] & 0xffff0000u), __uint_as_float(pk[1] << 16), __uint_as_float(pk[1] & 0xffff0000u));
;       } else h = *(const float4*)(hr + n);
;       h.x += acc[ni][mi][0]; h.y += acc[ni][mi][1]; h.z += acc[ni][mi][2]; h.w += acc[ni][mi][3];
; DI void phase_resid(const Params& p, int from_x, const u16* A, int K, const u16* W, float* rowss_next, bool last,
;                     unsigned char* smem) {
;     ...
;     gemm_kloop<4, 8>(A + (size_t)(mt * 256) * K, K, W + (size_t)(nt * 256) * K, K, K, acc, smem);
;     resid_epilogue<4, 8>(p, from_x, acc, mt * 256 + wm * 64, nt * 256 + wn * 128, rowss_next, last, lm, lg);
	v_mfma_f32_16x16x32_bf16 v[130:133], v[18:21], v[130:133], v[82:85]
	v_mfma_f32_16x16x32_bf16 v[138:141], v[18:21], v[138:141], v[74:77]
	v_mfma_f32_16x16x32_bf16 v[146:149], v[18:21], v[146:149], v[62:65]
	v_mfma_f32_16x16x32_bf16 v[150:153], v[18:21], v[150:153], v[126:129]
	v_add_u32_e32 v18, v179, v178
	ds_read_b128 v[230:233], v18
	ds_read_b128 v[234:237], v18 offset:2048
	ds_read_b128 v[14:17], v225 offset:2048
	ds_read_b128 v[238:241], v18 offset:4096
	ds_read_b128 v[248:251], v18 offset:6144
	s_waitcnt lgkmcnt(4)
	v_mfma_f32_16x16x32_bf16 v[126:129], v[10:13], v[230:233], v[134:137]
	s_nop 2
	v_add_u32_e32 v136, s34, v176
	s_waitcnt lgkmcnt(3)
	v_mfma_f32_16x16x32_bf16 v[94:97], v[10:13], v[234:237], v[118:121]
	s_waitcnt lgkmcnt(1)
	v_mfma_f32_16x16x32_bf16 v[62:65], v[10:13], v[238:241], v[114:117]
	s_waitcnt lgkmcnt(0)
	v_mfma_f32_16x16x32_bf16 v[30:33], v[10:13], v[248:251], v[110:113]
	v_mfma_f32_16x16x32_bf16 v[122:125], v[14:17], v[230:233], v[106:109]
	v_mfma_f32_16x16x32_bf16 v[90:93], v[14:17], v[234:237], v[102:105]
	v_mfma_f32_16x16x32_bf16 v[58:61], v[14:17], v[238:241], v[98:101]
	v_mfma_f32_16x16x32_bf16 v[26:29], v[14:17], v[248:251], v[142:145]
	ds_read_b128 v[10:13], v225 offset:4096
	ds_read_b128 v[14:17], v225 offset:6144
	s_waitcnt lgkmcnt(1)
	v_mfma_f32_16x16x32_bf16 v[118:121], v[10:13], v[230:233], v[154:157]
	v_mfma_f32_16x16x32_bf16 v[86:89], v[10:13], v[234:237], v[86:89]
	v_mfma_f32_16x16x32_bf16 v[54:57], v[10:13], v[238:241], v[78:81]
	v_mfma_f32_16x16x32_bf16 v[22:25], v[10:13], v[248:251], v[70:73]
	ds_read_b128 v[10:13], v225 offset:8192
	s_nop 1
	ds_read_b128 v[70:73], v225 offset:10240
	s_waitcnt lgkmcnt(1)
	v_mfma_f32_16x16x32_bf16 v[110:113], v[10:13], v[230:233], v[42:45]
	s_waitcnt lgkmcnt(0)
	v_mfma_f32_16x16x32_bf16 v[42:45], v[70:73], v[238:241], v[2:5]
	s_nop 2
	ds_read_b128 v[2:5], v225 offset:12288
	ds_read_b128 v[142:145], v225 offset:14336
	s_waitcnt lgkmcnt(0)
	s_barrier
	v_mfma_f32_16x16x32_bf16 v[114:117], v[14:17], v[230:233], v[158:161]
	v_mfma_f32_16x16x32_bf16 v[82:85], v[14:17], v[234:237], v[162:165]
	v_mfma_f32_16x16x32_bf16 v[50:53], v[14:17], v[238:241], v[50:53]
	v_mfma_f32_16x16x32_bf16 v[18:21], v[14:17], v[248:251], v[46:49]
	v_mfma_f32_16x16x32_bf16 v[78:81], v[10:13], v[234:237], v[34:37]
	v_mfma_f32_16x16x32_bf16 v[46:49], v[10:13], v[238:241], v[168:171]
	v_mfma_f32_16x16x32_bf16 v[14:17], v[10:13], v[248:251], v[180:183]
	v_mfma_f32_16x16x32_bf16 v[106:109], v[70:73], v[230:233], v[184:187]
	v_mfma_f32_16x16x32_bf16 v[74:77], v[70:73], v[234:237], v[6:9]
	v_mfma_f32_16x16x32_bf16 v[10:13], v[70:73], v[248:251], v[188:191]
	v_mfma_f32_16x16x32_bf16 v[102:105], v[2:5], v[230:233], v[192:195]
	v_mfma_f32_16x16x32_bf16 v[70:73], v[2:5], v[234:237], v[226:229]
	v_mfma_f32_16x16x32_bf16 v[38:41], v[2:5], v[238:241], v[38:41]
	v_mfma_f32_16x16x32_bf16 v[6:9], v[2:5], v[248:251], v[66:69]
	v_mul_hi_i32 v2, v136, s81
	v_lshrrev_b32_e32 v3, 31, v2
	v_ashrrev_i32_e32 v2, 10, v2
	v_mfma_f32_16x16x32_bf16 v[98:101], v[142:145], v[230:233], v[130:133]
	v_mfma_f32_16x16x32_bf16 v[66:69], v[142:145], v[234:237], v[138:141]
	s_nop 1
	v_add_u32_e32 v132, v2, v3
	v_mad_i32_i24 v130, v132, s82, v136
	v_add_u32_e32 v133, -16, v130
	v_mfma_f32_16x16x32_bf16 v[34:37], v[142:145], v[238:241], v[146:149]
	v_cmp_lt_u32_e32 vcc, s83, v133
	v_mfma_f32_16x16x32_bf16 v[2:5], v[142:145], v[248:251], v[150:153]
	s_load_dwordx2 s[56:57], s[0:1], 0xc8
	s_load_dwordx2 s[58:59], s[0:1], 0xd8
	s_lshr_b32 s2, s49, 4
	s_lshl_b32 s2, s2, 2
	s_and_b32 s3, s49, 3
	s_or_b32 s2, s2, s3
	s_lshl_b32 s2, s2, 8
	s_lshr_b32 s3, s49, 2
	s_and_b32 s3, s3, 3
	s_lshl_b32 s3, s3, 8
	v_add_u32_e32 v130, s2, v176
	v_or_b32_e32 v131, s3, v177
	s_and_b64 vcc, exec, s[4:5]
	s_cbranch_vccnz .Lre_outproj_T
	s_load_dwordx2 s[60:61], s[0:1], 0x0
	s_waitcnt lgkmcnt(0)
	v_add_u32_e32 v168, 0, v130
	v_lshlrev_b32_e32 v168, 11, v168
	v_lshl_add_u32 v242, v131, 1, v168
	v_add_u32_e32 v168, 0, v130
	v_mul_hi_i32 v169, v168, s81
	v_lshrrev_b32_e32 v170, 31, v169
	v_ashrrev_i32_e32 v169, 10, v169
	v_add_u32_e32 v169, v169, v170
	v_mad_i32_i24 v170, v169, s82, v168
	v_add_u32_e32 v171, -16, v170
	v_cmp_lt_u32_e32 vcc, s83, v171
	v_lshl_add_u32 v171, v169, 12, v171
	v_add_u32_e32 v168, 0xfffff000, v170
	v_cmp_gt_i32_e64 s[2:3], 16, v170
	s_nop 1
	v_cndmask_b32_e64 v168, v168, v170, s[2:3]
	v_lshl_add_u32 v168, v169, 7, v168
	v_cndmask_b32_e32 v168, v171, v168, vcc
	v_mov_b32_e32 v169, s60
	v_mov_b32_e32 v170, s58
	v_cndmask_b32_e32 v248, v169, v170, vcc
	v_mov_b32_e32 v169, s61
	v_mov_b32_e32 v170, s59
	v_cndmask_b32_e32 v249, v169, v170, vcc
	v_lshlrev_b32_e32 v168, 12, v168
	v_lshl_add_u32 v168, v131, 2, v168
	v_add_co_u32_e32 v248, vcc, v248, v168
	s_nop 1
	v_addc_co_u32_e32 v249, vcc, 0, v249, vcc
	global_load_dwordx4 v[132:135], v[248:249], off offset:0
	global_load_dwordx4 v[136:139], v[248:249], off offset:64
	global_load_dwordx4 v[140:143], v[248:249], off offset:128
	global_load_dwordx4 v[144:147], v[248:249], off offset:192
	global_load_dwordx4 v[148:151], v[248:249], off offset:256
	global_load_dwordx4 v[152:155], v[248:249], off offset:320
	global_load_dwordx4 v[156:159], v[248:249], off offset:384
	global_load_dwordx4 v[160:163], v[248:249], off offset:448
	v_add_u32_e32 v168, 16, v130
	v_lshlrev_b32_e32 v168, 11, v168
	v_lshl_add_u32 v243, v131, 1, v168
	v_add_u32_e32 v168, 16, v130
	v_mul_hi_i32 v169, v168, s81
	v_lshrrev_b32_e32 v170, 31, v169
	v_ashrrev_i32_e32 v169, 10, v169
	v_add_u32_e32 v169, v169, v170
	v_mad_i32_i24 v170, v169, s82, v168
	v_add_u32_e32 v171, -16, v170
	v_cmp_lt_u32_e32 vcc, s83, v171
	v_lshl_add_u32 v171, v169, 12, v171
	v_add_u32_e32 v168, 0xfffff000, v170
	v_cmp_gt_i32_e64 s[2:3], 16, v170
	s_nop 1
	v_cndmask_b32_e64 v168, v168, v170, s[2:3]
	v_lshl_add_u32 v168, v169, 7, v168
	v_cndmask_b32_e32 v168, v171, v168, vcc
	v_mov_b32_e32 v169, s60
	v_mov_b32_e32 v170, s58
	v_cndmask_b32_e32 v250, v169, v170, vcc
	v_mov_b32_e32 v169, s61
	v_mov_b32_e32 v170, s59
	v_cndmask_b32_e32 v251, v169, v170, vcc
	v_lshlrev_b32_e32 v168, 12, v168
	v_lshl_add_u32 v168, v131, 2, v168
	v_add_co_u32_e32 v250, vcc, v250, v168
	s_nop 1
	v_addc_co_u32_e32 v251, vcc, 0, v251, vcc
	global_load_dwordx4 v[178:181], v[250:251], off offset:0
	global_load_dwordx4 v[182:185], v[250:251], off offset:64
	global_load_dwordx4 v[186:189], v[250:251], off offset:128
	global_load_dwordx4 v[190:193], v[250:251], off offset:192
	global_load_dwordx4 v[226:229], v[250:251], off offset:256
	global_load_dwordx4 v[230:233], v[250:251], off offset:320
	global_load_dwordx4 v[234:237], v[250:251], off offset:384
	global_load_dwordx4 v[238:241], v[250:251], off offset:448
	s_waitcnt vmcnt(15)
; template <int MI, int NI>
; DI void resid_epilogue(const Params& p, int from_x, const f32x4 (&acc)[NI][MI], int row0, int n0, float* rowss_next, bool last, int lm, int lg) {
;     ...
;     for (int ni = 0; ni < NI; ++ni) {
;       const int n = n0 + ni * 16 + lg * 4;
;       float4 h;
;       if (from_x >= 2) {
;         const u32x2 pk = *(const u32x2*)(hbr + n);
;         h = make_float4(__uint_as_float(pk[0] << 16), __uint_as_float(pk[0] & 0xffff0000u), __uint_as_float(pk[1] << 16), __uint_as_float(pk[1] & 0xffff0000u));
;       } else h = *(const float4*)(hr + n);
;       h.x += acc[ni][mi][0]; h.y += acc[ni][mi][1]; h.z += acc[ni][mi][2]; h.w += acc[ni][mi][3];
;       if (last) *(float4*)(hw + n) = h;
;       if (!last) {
;         u32x2 pk = {pack2bf(h.x, h.y), pack2bf(h.z, h.w)};
;         *(u32x2*)(hbr + n) = pk;
;         ss += h.x * h.x + h.y * h.y + h.z * h.z + h.w * h.w;
;       }
;     }
;     if (!last) {
;       ss += __shfl_xor(ss, 16);
;       ss += __shfl_xor(ss, 32);
;       if (lg == 0) atomicAdd(rowss_next + m, ss);
;     }
	v_pk_add_f32 v[194:195], v[126:127], v[132:133]
	v_pk_add_f32 v[254:255], v[128:129], v[134:135]
	v_cvt_pk_bf16_f32 v168, v194, v195
	v_cvt_pk_bf16_f32 v169, v254, v255
	global_store_dwordx2 v242, v[168:169], s[56:57] offset:0
	v_pk_mul_f32 v[194:195], v[194:195], v[194:195]
	v_pk_mul_f32 v[254:255], v[254:255], v[254:255]
	v_add_f32_e32 v170, v195, v194
	v_add_f32_e32 v170, v254, v170
	v_add_f32_e32 v170, v255, v170
	v_mov_b32_e32 v164, v170
	s_waitcnt vmcnt(15)
	v_pk_add_f32 v[194:195], v[122:123], v[136:137]
	v_pk_add_f32 v[254:255], v[124:125], v[138:139]
	v_cvt_pk_bf16_f32 v168, v194, v195
	v_cvt_pk_bf16_f32 v169, v254, v255
	global_store_dwordx2 v242, v[168:169], s[56:57] offset:32
	v_pk_mul_f32 v[194:195], v[194:195], v[194:195]
	v_pk_mul_f32 v[254:255], v[254:255], v[254:255]
	v_add_f32_e32 v170, v195, v194
	v_add_f32_e32 v170, v254, v170
	v_add_f32_e32 v170, v255, v170
	v_add_f32_e32 v164, v164, v170
	s_waitcnt vmcnt(15)
	v_pk_add_f32 v[194:195], v[118:119], v[140:141]
	v_pk_add_f32 v[254:255], v[120:121], v[142:143]
	v_cvt_pk_bf16_f32 v168, v194, v195
	v_cvt_pk_bf16_f32 v169, v254, v255
	global_store_dwordx2 v242, v[168:169], s[56:57] offset:64
	v_pk_mul_f32 v[194:195], v[194:195], v[194:195]
	v_pk_mul_f32 v[254:255], v[254:255], v[254:255]
	v_add_f32_e32 v170, v195, v194
	v_add_f32_e32 v170, v254, v170
	v_add_f32_e32 v170, v255, v170
	v_add_f32_e32 v164, v164, v170
	s_waitcnt vmcnt(15)
	v_pk_add_f32 v[194:195], v[114:115], v[144:145]
	v_pk_add_f32 v[254:255], v[116:117], v[146:147]
	v_cvt_pk_bf16_f32 v168, v194, v195
	v_cvt_pk_bf16_f32 v169, v254, v255
	global_store_dwordx2 v242, v[168:169], s[56:57] offset:96
	v_pk_mul_f32 v[194:195], v[194:195], v[194:195]
	v_pk_mul_f32 v[254:255], v[254:255], v[254:255]
	v_add_f32_e32 v170, v195, v194
	v_add_f32_e32 v170, v254, v170
	v_add_f32_e32 v170, v255, v170
	v_add_f32_e32 v164, v164, v170
	s_waitcnt vmcnt(15)
	v_pk_add_f32 v[194:195], v[110:111], v[148:149]
	v_pk_add_f32 v[254:255], v[112:113], v[150:151]
	v_cvt_pk_bf16_f32 v168, v194, v195
	v_cvt_pk_bf16_f32 v169, v254, v255
	global_store_dwordx2 v242, v[168:169], s[56:57] offset:128
	v_pk_mul_f32 v[194:195], v[194:195], v[194:195]
	v_pk_mul_f32 v[254:255], v[254:255], v[254:255]
	v_add_f32_e32 v170, v195, v194
	v_add_f32_e32 v170, v254, v170
	v_add_f32_e32 v170, v255, v170
	v_add_f32_e32 v164, v164, v170
	s_waitcnt vmcnt(15)
	v_pk_add_f32 v[194:195], v[106:107], v[152:153]
	v_pk_add_f32 v[254:255], v[108:109], v[154:155]
	v_cvt_pk_bf16_f32 v168, v194, v195
	v_cvt_pk_bf16_f32 v169, v254, v255
	global_store_dwordx2 v242, v[168:169], s[56:57] offset:160
	v_pk_mul_f32 v[194:195], v[194:195], v[194:195]
	v_pk_mul_f32 v[254:255], v[254:255], v[254:255]
	v_add_f32_e32 v170, v195, v194
	v_add_f32_e32 v170, v254, v170
	v_add_f32_e32 v170, v255, v170
	v_add_f32_e32 v164, v164, v170
	s_waitcnt vmcnt(15)
	v_pk_add_f32 v[194:195], v[102:103], v[156:157]
	v_pk_add_f32 v[254:255], v[104:105], v[158:159]
	v_cvt_pk_bf16_f32 v168, v194, v195
	v_cvt_pk_bf16_f32 v169, v254, v255
	global_store_dwordx2 v242, v[168:169], s[56:57] offset:192
	v_pk_mul_f32 v[194:195], v[194:195], v[194:195]
	v_pk_mul_f32 v[254:255], v[254:255], v[254:255]
	v_add_f32_e32 v170, v195, v194
	v_add_f32_e32 v170, v254, v170
	v_add_f32_e32 v170, v255, v170
	v_add_f32_e32 v164, v164, v170
	s_waitcnt vmcnt(15)
	v_pk_add_f32 v[194:195], v[98:99], v[160:161]
	v_pk_add_f32 v[254:255], v[100:101], v[162:163]
	v_cvt_pk_bf16_f32 v168, v194, v195
	v_cvt_pk_bf16_f32 v169, v254, v255
	global_store_dwordx2 v242, v[168:169], s[56:57] offset:224
	v_pk_mul_f32 v[194:195], v[194:195], v[194:195]
	v_pk_mul_f32 v[254:255], v[254:255], v[254:255]
	v_add_f32_e32 v170, v195, v194
	v_add_f32_e32 v170, v254, v170
	v_add_f32_e32 v170, v255, v170
	v_add_f32_e32 v164, v164, v170
	v_xor_b32_e32 v168, 16, v207
	v_lshlrev_b32_e32 v168, 2, v168
	ds_bpermute_b32 v169, v168, v164
	v_xor_b32_e32 v168, 32, v207
	v_lshlrev_b32_e32 v168, 2, v168
	s_waitcnt lgkmcnt(0)
	v_add_f32_e32 v164, v164, v169
	ds_bpermute_b32 v169, v168, v164
	v_add_u32_e32 v170, 0, v130
	v_lshlrev_b32_e32 v170, 2, v170
	v_and_b32_e32 v171, 63, v207
	v_cmp_gt_u32_e32 vcc, 16, v171
	s_waitcnt lgkmcnt(0)
	v_add_f32_e32 v164, v164, v169
	s_and_saveexec_b64 s[2:3], vcc
	global_atomic_add_f32 v170, v164, s[8:9]
	s_or_b64 exec, exec, s[2:3]
	v_add_u32_e32 v168, 32, v130
	v_lshlrev_b32_e32 v168, 11, v168
	v_lshl_add_u32 v242, v131, 1, v168
	v_add_u32_e32 v168, 32, v130
	v_mul_hi_i32 v169, v168, s81
	v_lshrrev_b32_e32 v170, 31, v169
	v_ashrrev_i32_e32 v169, 10, v169
	v_add_u32_e32 v169, v169, v170
	v_mad_i32_i24 v170, v169, s82, v168
	v_add_u32_e32 v171, -16, v170
	v_cmp_lt_u32_e32 vcc, s83, v171
	v_lshl_add_u32 v171, v169, 12, v171
	v_add_u32_e32 v168, 0xfffff000, v170
	v_cmp_gt_i32_e64 s[2:3], 16, v170
	s_nop 1
	v_cndmask_b32_e64 v168, v168, v170, s[2:3]
	v_lshl_add_u32 v168, v169, 7, v168
	v_cndmask_b32_e32 v168, v171, v168, vcc
	v_mov_b32_e32 v169, s60
	v_mov_b32_e32 v170, s58
	v_cndmask_b32_e32 v248, v169, v170, vcc
	v_mov_b32_e32 v169, s61
	v_mov_b32_e32 v170, s59
	v_cndmask_b32_e32 v249, v169, v170, vcc
	v_lshlrev_b32_e32 v168, 12, v168
	v_lshl_add_u32 v168, v131, 2, v168
	v_add_co_u32_e32 v248, vcc, v248, v168
	s_nop 1
	v_addc_co_u32_e32 v249, vcc, 0, v249, vcc
	global_load_dwordx4 v[132:135], v[248:249], off offset:0
	global_load_dwordx4 v[136:139], v[248:249], off offset:64
	global_load_dwordx4 v[140:143], v[248:249], off offset:128
	global_load_dwordx4 v[144:147], v[248:249], off offset:192
	global_load_dwordx4 v[148:151], v[248:249], off offset:256
	global_load_dwordx4 v[152:155], v[248:249], off offset:320
	global_load_dwordx4 v[156:159], v[248:249], off offset:384
	global_load_dwordx4 v[160:163], v[248:249], off offset:448
	s_waitcnt vmcnt(24)
; template <int MI, int NI>
; DI void resid_epilogue(const Params& p, int from_x, const f32x4 (&acc)[NI][MI], int row0, int n0, float* rowss_next, bool last, int lm, int lg) {
;     ...
;     for (int ni = 0; ni < NI; ++ni) {
;       const int n = n0 + ni * 16 + lg * 4;
;       float4 h;
;       if (from_x >= 2) {
;         const u32x2 pk = *(const u32x2*)(hbr + n);
;         h = make_float4(__uint_as_float(pk[0] << 16), __uint_as_float(pk[0] & 0xffff0000u), __uint_as_float(pk[1] << 16), __uint_as_float(pk[1] & 0xffff0000u));
;       } else h = *(const float4*)(hr + n);
;       h.x += acc[ni][mi][0]; h.y += acc[ni][mi][1]; h.z += acc[ni][mi][2]; h.w += acc[ni][mi][3];
;       if (last) *(float4*)(hw + n) = h;
;       if (!last) {
;         u32x2 pk = {pack2bf(h.x, h.y), pack2bf(h.z, h.w)};
;         *(u32x2*)(hbr + n) = pk;
;         ss += h.x * h.x + h.y * h.y + h.z * h.z + h.w * h.w;
;       }
;     }
;     if (!last) {
;       ss += __shfl_xor(ss, 16);
;       ss += __shfl_xor(ss, 32);
;       if (lg == 0) atomicAdd(rowss_next + m, ss);
;     }
	v_pk_add_f32 v[194:195], v[94:95], v[178:179]
	v_pk_add_f32 v[254:255], v[96:97], v[180:181]
	v_cvt_pk_bf16_f32 v168, v194, v195
	v_cvt_pk_bf16_f32 v169, v254, v255
	global_store_dwordx2 v243, v[168:169], s[56:57] offset:0
	v_pk_mul_f32 v[194:195], v[194:195], v[194:195]
	v_pk_mul_f32 v[254:255], v[254:255], v[254:255]
	v_add_f32_e32 v170, v195, v194
	v_add_f32_e32 v170, v254, v170
	v_add_f32_e32 v170, v255, v170
	v_mov_b32_e32 v164, v170
	s_waitcnt vmcnt(24)
	v_pk_add_f32 v[194:195], v[90:91], v[182:183]
	v_pk_add_f32 v[254:255], v[92:93], v[184:185]
	v_cvt_pk_bf16_f32 v168, v194, v195
	v_cvt_pk_bf16_f32 v169, v254, v255
	global_store_dwordx2 v243, v[168:169], s[56:57] offset:32
	v_pk_mul_f32 v[194:195], v[194:195], v[194:195]
	v_pk_mul_f32 v[254:255], v[254:255], v[254:255]
	v_add_f32_e32 v170, v195, v194
	v_add_f32_e32 v170, v254, v170
	v_add_f32_e32 v170, v255, v170
	v_add_f32_e32 v164, v164, v170
	s_waitcnt vmcnt(24)
	v_pk_add_f32 v[194:195], v[86:87], v[186:187]
	v_pk_add_f32 v[254:255], v[88:89], v[188:189]
	v_cvt_pk_bf16_f32 v168, v194, v195
	v_cvt_pk_bf16_f32 v169, v254, v255
	global_store_dwordx2 v243, v[168:169], s[56:57] offset:64
	v_pk_mul_f32 v[194:195], v[194:195], v[194:195]
	v_pk_mul_f32 v[254:255], v[254:255], v[254:255]
	v_add_f32_e32 v170, v195, v194
	v_add_f32_e32 v170, v254, v170
	v_add_f32_e32 v170, v255, v170
	v_add_f32_e32 v164, v164, v170
	s_waitcnt vmcnt(24)
	v_pk_add_f32 v[194:195], v[82:83], v[190:191]
	v_pk_add_f32 v[254:255], v[84:85], v[192:193]
	v_cvt_pk_bf16_f32 v168, v194, v195
	v_cvt_pk_bf16_f32 v169, v254, v255
	global_store_dwordx2 v243, v[168:169], s[56:57] offset:96
	v_pk_mul_f32 v[194:195], v[194:195], v[194:195]
	v_pk_mul_f32 v[254:255], v[254:255], v[254:255]
	v_add_f32_e32 v170, v195, v194
	v_add_f32_e32 v170, v254, v170
	v_add_f32_e32 v170, v255, v170
	v_add_f32_e32 v164, v164, v170
	s_waitcnt vmcnt(24)
	v_pk_add_f32 v[194:195], v[78:79], v[226:227]
	v_pk_add_f32 v[254:255], v[80:81], v[228:229]
	v_cvt_pk_bf16_f32 v168, v194, v195
	v_cvt_pk_bf16_f32 v169, v254, v255
	global_store_dwordx2 v243, v[168:169], s[56:57] offset:128
	v_pk_mul_f32 v[194:195], v[194:195], v[194:195]
	v_pk_mul_f32 v[254:255], v[254:255], v[254:255]
	v_add_f32_e32 v170, v195, v194
	v_add_f32_e32 v170, v254, v170
	v_add_f32_e32 v170, v255, v170
	v_add_f32_e32 v164, v164, v170
	s_waitcnt vmcnt(24)
	v_pk_add_f32 v[194:195], v[74:75], v[230:231]
	v_pk_add_f32 v[254:255], v[76:77], v[232:233]
	v_cvt_pk_bf16_f32 v168, v194, v195
	v_cvt_pk_bf16_f32 v169, v254, v255
	global_store_dwordx2 v243, v[168:169], s[56:57] offset:160
	v_pk_mul_f32 v[194:195], v[194:195], v[194:195]
	v_pk_mul_f32 v[254:255], v[254:255], v[254:255]
	v_add_f32_e32 v170, v195, v194
	v_add_f32_e32 v170, v254, v170
	v_add_f32_e32 v170, v255, v170
	v_add_f32_e32 v164, v164, v170
	s_waitcnt vmcnt(24)
	v_pk_add_f32 v[194:195], v[70:71], v[234:235]
	v_pk_add_f32 v[254:255], v[72:73], v[236:237]
	v_cvt_pk_bf16_f32 v168, v194, v195
	v_cvt_pk_bf16_f32 v169, v254, v255
	global_store_dwordx2 v243, v[168:169], s[56:57] offset:192
	v_pk_mul_f32 v[194:195], v[194:195], v[194:195]
	v_pk_mul_f32 v[254:255], v[254:255], v[254:255]
	v_add_f32_e32 v170, v195, v194
	v_add_f32_e32 v170, v254, v170
	v_add_f32_e32 v170, v255, v170
	v_add_f32_e32 v164, v164, v170
	s_waitcnt vmcnt(24)
	v_pk_add_f32 v[194:195], v[66:67], v[238:239]
	v_pk_add_f32 v[254:255], v[68:69], v[240:241]
	v_cvt_pk_bf16_f32 v168, v194, v195
	v_cvt_pk_bf16_f32 v169, v254, v255
	global_store_dwordx2 v243, v[168:169], s[56:57] offset:224
	v_pk_mul_f32 v[194:195], v[194:195], v[194:195]
	v_pk_mul_f32 v[254:255], v[254:255], v[254:255]
	v_add_f32_e32 v170, v195, v194
	v_add_f32_e32 v170, v254, v170
	v_add_f32_e32 v170, v255, v170
	v_add_f32_e32 v164, v164, v170
	v_xor_b32_e32 v168, 16, v207
	v_lshlrev_b32_e32 v168, 2, v168
	ds_bpermute_b32 v169, v168, v164
	v_xor_b32_e32 v168, 32, v207
	v_lshlrev_b32_e32 v168, 2, v168
	s_waitcnt lgkmcnt(0)
	v_add_f32_e32 v164, v164, v169
	ds_bpermute_b32 v169, v168, v164
	v_add_u32_e32 v170, 16, v130
	v_lshlrev_b32_e32 v170, 2, v170
	v_and_b32_e32 v171, 63, v207
	v_cmp_gt_u32_e32 vcc, 16, v171
	s_waitcnt lgkmcnt(0)
	v_add_f32_e32 v164, v164, v169
	s_and_saveexec_b64 s[2:3], vcc
	global_atomic_add_f32 v170, v164, s[8:9]
	s_or_b64 exec, exec, s[2:3]
	v_add_u32_e32 v168, 48, v130
	v_lshlrev_b32_e32 v168, 11, v168
	v_lshl_add_u32 v243, v131, 1, v168
	v_add_u32_e32 v168, 48, v130
	v_mul_hi_i32 v169, v168, s81
	v_lshrrev_b32_e32 v170, 31, v169
	v_ashrrev_i32_e32 v169, 10, v169
	v_add_u32_e32 v169, v169, v170
	v_mad_i32_i24 v170, v169, s82, v168
	v_add_u32_e32 v171, -16, v170
	v_cmp_lt_u32_e32 vcc, s83, v171
	v_lshl_add_u32 v171, v169, 12, v171
	v_add_u32_e32 v168, 0xfffff000, v170
	v_cmp_gt_i32_e64 s[2:3], 16, v170
	s_nop 1
	v_cndmask_b32_e64 v168, v168, v170, s[2:3]
	v_lshl_add_u32 v168, v169, 7, v168
	v_cndmask_b32_e32 v168, v171, v168, vcc
	v_mov_b32_e32 v169, s60
	v_mov_b32_e32 v170, s58
	v_cndmask_b32_e32 v250, v169, v170, vcc
	v_mov_b32_e32 v169, s61
	v_mov_b32_e32 v170, s59
	v_cndmask_b32_e32 v251, v169, v170, vcc
	v_lshlrev_b32_e32 v168, 12, v168
	v_lshl_add_u32 v168, v131, 2, v168
	v_add_co_u32_e32 v250, vcc, v250, v168
	s_nop 1
	v_addc_co_u32_e32 v251, vcc, 0, v251, vcc
	global_load_dwordx4 v[178:181], v[250:251], off offset:0
	global_load_dwordx4 v[182:185], v[250:251], off offset:64
	global_load_dwordx4 v[186:189], v[250:251], off offset:128
	global_load_dwordx4 v[190:193], v[250:251], off offset:192
	global_load_dwordx4 v[226:229], v[250:251], off offset:256
	global_load_dwordx4 v[230:233], v[250:251], off offset:320
	global_load_dwordx4 v[234:237], v[250:251], off offset:384
	global_load_dwordx4 v[238:241], v[250:251], off offset:448
	s_waitcnt vmcnt(24)
; template <int MI, int NI>
; DI void resid_epilogue(const Params& p, int from_x, const f32x4 (&acc)[NI][MI], int row0, int n0, float* rowss_next, bool last, int lm, int lg) {
;     ...
;     for (int ni = 0; ni < NI; ++ni) {
;       const int n = n0 + ni * 16 + lg * 4;
;       float4 h;
;       if (from_x >= 2) {
;         const u32x2 pk = *(const u32x2*)(hbr + n);
;         h = make_float4(__uint_as_float(pk[0] << 16), __uint_as_float(pk[0] & 0xffff0000u), __uint_as_float(pk[1] << 16), __uint_as_float(pk[1] & 0xffff0000u));
;       } else h = *(const float4*)(hr + n);
;       h.x += acc[ni][mi][0]; h.y += acc[ni][mi][1]; h.z += acc[ni][mi][2]; h.w += acc[ni][mi][3];
;       if (last) *(float4*)(hw + n) = h;
;       if (!last) {
;         u32x2 pk = {pack2bf(h.x, h.y), pack2bf(h.z, h.w)};
;         *(u32x2*)(hbr + n) = pk;
;         ss += h.x * h.x + h.y * h.y + h.z * h.z + h.w * h.w;
;       }
;     }
;     if (!last) {
;       ss += __shfl_xor(ss, 16);
;       ss += __shfl_xor(ss, 32);
;       if (lg == 0) atomicAdd(rowss_next + m, ss);
;     }
	v_pk_add_f32 v[194:195], v[62:63], v[132:133]
	v_pk_add_f32 v[254:255], v[64:65], v[134:135]
	v_cvt_pk_bf16_f32 v168, v194, v195
	v_cvt_pk_bf16_f32 v169, v254, v255
	global_store_dwordx2 v242, v[168:169], s[56:57] offset:0
	v_pk_mul_f32 v[194:195], v[194:195], v[194:195]
	v_pk_mul_f32 v[254:255], v[254:255], v[254:255]
	v_add_f32_e32 v170, v195, v194
	v_add_f32_e32 v170, v254, v170
	v_add_f32_e32 v170, v255, v170
	v_mov_b32_e32 v164, v170
	s_waitcnt vmcnt(24)
	v_pk_add_f32 v[194:195], v[58:59], v[136:137]
	v_pk_add_f32 v[254:255], v[60:61], v[138:139]
	v_cvt_pk_bf16_f32 v168, v194, v195
	v_cvt_pk_bf16_f32 v169, v254, v255
	global_store_dwordx2 v242, v[168:169], s[56:57] offset:32
	v_pk_mul_f32 v[194:195], v[194:195], v[194:195]
	v_pk_mul_f32 v[254:255], v[254:255], v[254:255]
	v_add_f32_e32 v170, v195, v194
	v_add_f32_e32 v170, v254, v170
	v_add_f32_e32 v170, v255, v170
	v_add_f32_e32 v164, v164, v170
	s_waitcnt vmcnt(24)
	v_pk_add_f32 v[194:195], v[54:55], v[140:141]
	v_pk_add_f32 v[254:255], v[56:57], v[142:143]
	v_cvt_pk_bf16_f32 v168, v194, v195
	v_cvt_pk_bf16_f32 v169, v254, v255
	global_store_dwordx2 v242, v[168:169], s[56:57] offset:64
	v_pk_mul_f32 v[194:195], v[194:195], v[194:195]
	v_pk_mul_f32 v[254:255], v[254:255], v[254:255]
	v_add_f32_e32 v170, v195, v194
	v_add_f32_e32 v170, v254, v170
	v_add_f32_e32 v170, v255, v170
	v_add_f32_e32 v164, v164, v170
	s_waitcnt vmcnt(24)
	v_pk_add_f32 v[194:195], v[50:51], v[144:145]
	v_pk_add_f32 v[254:255], v[52:53], v[146:147]
	v_cvt_pk_bf16_f32 v168, v194, v195
	v_cvt_pk_bf16_f32 v169, v254, v255
	global_store_dwordx2 v242, v[168:169], s[56:57] offset:96
	v_pk_mul_f32 v[194:195], v[194:195], v[194:195]
	v_pk_mul_f32 v[254:255], v[254:255], v[254:255]
	v_add_f32_e32 v170, v195, v194
	v_add_f32_e32 v170, v254, v170
	v_add_f32_e32 v170, v255, v170
	v_add_f32_e32 v164, v164, v170
	s_waitcnt vmcnt(24)
	v_pk_add_f32 v[194:195], v[46:47], v[148:149]
	v_pk_add_f32 v[254:255], v[48:49], v[150:151]
	v_cvt_pk_bf16_f32 v168, v194, v195
	v_cvt_pk_bf16_f32 v169, v254, v255
	global_store_dwordx2 v242, v[168:169], s[56:57] offset:128
	v_pk_mul_f32 v[194:195], v[194:195], v[194:195]
	v_pk_mul_f32 v[254:255], v[254:255], v[254:255]
	v_add_f32_e32 v170, v195, v194
	v_add_f32_e32 v170, v254, v170
	v_add_f32_e32 v170, v255, v170
	v_add_f32_e32 v164, v164, v170
	s_waitcnt vmcnt(24)
	v_pk_add_f32 v[194:195], v[42:43], v[152:153]
	v_pk_add_f32 v[254:255], v[44:45], v[154:155]
	v_cvt_pk_bf16_f32 v168, v194, v195
	v_cvt_pk_bf16_f32 v169, v254, v255
	global_store_dwordx2 v242, v[168:169], s[56:57] offset:160
	v_pk_mul_f32 v[194:195], v[194:195], v[194:195]
	v_pk_mul_f32 v[254:255], v[254:255], v[254:255]
	v_add_f32_e32 v170, v195, v194
	v_add_f32_e32 v170, v254, v170
	v_add_f32_e32 v170, v255, v170
	v_add_f32_e32 v164, v164, v170
	s_waitcnt vmcnt(24)
	v_pk_add_f32 v[194:195], v[38:39], v[156:157]
	v_pk_add_f32 v[254:255], v[40:41], v[158:159]
	v_cvt_pk_bf16_f32 v168, v194, v195
	v_cvt_pk_bf16_f32 v169, v254, v255
	global_store_dwordx2 v242, v[168:169], s[56:57] offset:192
	v_pk_mul_f32 v[194:195], v[194:195], v[194:195]
	v_pk_mul_f32 v[254:255], v[254:255], v[254:255]
	v_add_f32_e32 v170, v195, v194
	v_add_f32_e32 v170, v254, v170
	v_add_f32_e32 v170, v255, v170
	v_add_f32_e32 v164, v164, v170
	s_waitcnt vmcnt(24)
	v_pk_add_f32 v[194:195], v[34:35], v[160:161]
	v_pk_add_f32 v[254:255], v[36:37], v[162:163]
	v_cvt_pk_bf16_f32 v168, v194, v195
	v_cvt_pk_bf16_f32 v169, v254, v255
	global_store_dwordx2 v242, v[168:169], s[56:57] offset:224
	v_pk_mul_f32 v[194:195], v[194:195], v[194:195]
	v_pk_mul_f32 v[254:255], v[254:255], v[254:255]
	v_add_f32_e32 v170, v195, v194
	v_add_f32_e32 v170, v254, v170
	v_add_f32_e32 v170, v255, v170
	v_add_f32_e32 v164, v164, v170
	v_xor_b32_e32 v168, 16, v207
	v_lshlrev_b32_e32 v168, 2, v168
	ds_bpermute_b32 v169, v168, v164
	v_xor_b32_e32 v168, 32, v207
	v_lshlrev_b32_e32 v168, 2, v168
	s_waitcnt lgkmcnt(0)
	v_add_f32_e32 v164, v164, v169
	ds_bpermute_b32 v169, v168, v164
	v_add_u32_e32 v170, 32, v130
	v_lshlrev_b32_e32 v170, 2, v170
	v_and_b32_e32 v171, 63, v207
	v_cmp_gt_u32_e32 vcc, 16, v171
	s_waitcnt lgkmcnt(0)
	v_add_f32_e32 v164, v164, v169
	s_and_saveexec_b64 s[2:3], vcc
	global_atomic_add_f32 v170, v164, s[8:9]
	s_or_b64 exec, exec, s[2:3]
	s_waitcnt vmcnt(16)
	v_pk_add_f32 v[194:195], v[30:31], v[178:179]
	v_pk_add_f32 v[254:255], v[32:33], v[180:181]
	v_cvt_pk_bf16_f32 v168, v194, v195
	v_cvt_pk_bf16_f32 v169, v254, v255
	global_store_dwordx2 v243, v[168:169], s[56:57] offset:0
	v_pk_mul_f32 v[194:195], v[194:195], v[194:195]
	v_pk_mul_f32 v[254:255], v[254:255], v[254:255]
	v_add_f32_e32 v170, v195, v194
	v_add_f32_e32 v170, v254, v170
	v_add_f32_e32 v170, v255, v170
	v_mov_b32_e32 v164, v170
	s_waitcnt vmcnt(16)
	v_pk_add_f32 v[194:195], v[26:27], v[182:183]
	v_pk_add_f32 v[254:255], v[28:29], v[184:185]
	v_cvt_pk_bf16_f32 v168, v194, v195
	v_cvt_pk_bf16_f32 v169, v254, v255
	global_store_dwordx2 v243, v[168:169], s[56:57] offset:32
	v_pk_mul_f32 v[194:195], v[194:195], v[194:195]
	v_pk_mul_f32 v[254:255], v[254:255], v[254:255]
	v_add_f32_e32 v170, v195, v194
	v_add_f32_e32 v170, v254, v170
	v_add_f32_e32 v170, v255, v170
	v_add_f32_e32 v164, v164, v170
	s_waitcnt vmcnt(16)
	v_pk_add_f32 v[194:195], v[22:23], v[186:187]
	v_pk_add_f32 v[254:255], v[24:25], v[188:189]
	v_cvt_pk_bf16_f32 v168, v194, v195
	v_cvt_pk_bf16_f32 v169, v254, v255
	global_store_dwordx2 v243, v[168:169], s[56:57] offset:64
	v_pk_mul_f32 v[194:195], v[194:195], v[194:195]
	v_pk_mul_f32 v[254:255], v[254:255], v[254:255]
	v_add_f32_e32 v170, v195, v194
	v_add_f32_e32 v170, v254, v170
	v_add_f32_e32 v170, v255, v170
	v_add_f32_e32 v164, v164, v170
	s_waitcnt vmcnt(16)
; template <int MI, int NI>
; DI void resid_epilogue(const Params& p, int from_x, const f32x4 (&acc)[NI][MI], int row0, int n0, float* rowss_next, bool last, int lm, int lg) {
;     ...
;     for (int ni = 0; ni < NI; ++ni) {
;       const int n = n0 + ni * 16 + lg * 4;
;       float4 h;
;       if (from_x >= 2) {
;         const u32x2 pk = *(const u32x2*)(hbr + n);
;         h = make_float4(__uint_as_float(pk[0] << 16), __uint_as_float(pk[0] & 0xffff0000u), __uint_as_float(pk[1] << 16), __uint_as_float(pk[1] & 0xffff0000u));
;       } else h = *(const float4*)(hr + n);
;       h.x += acc[ni][mi][0]; h.y += acc[ni][mi][1]; h.z += acc[ni][mi][2]; h.w += acc[ni][mi][3];
;       if (last) *(float4*)(hw + n) = h;
;       if (!last) {
;         u32x2 pk = {pack2bf(h.x, h.y), pack2bf(h.z, h.w)};
;         *(u32x2*)(hbr + n) = pk;
;         ss += h.x * h.x + h.y * h.y + h.z * h.z + h.w * h.w;
;       }
;     }
;     if (!last) {
;       ss += __shfl_xor(ss, 16);
;       ss += __shfl_xor(ss, 32);
;       if (lg == 0) atomicAdd(rowss_next + m, ss);
;     }
	v_pk_add_f32 v[194:195], v[18:19], v[190:191]
	v_pk_add_f32 v[254:255], v[20:21], v[192:193]
	v_cvt_pk_bf16_f32 v168, v194, v195
	v_cvt_pk_bf16_f32 v169, v254, v255
	global_store_dwordx2 v243, v[168:169], s[56:57] offset:96
	v_pk_mul_f32 v[194:195], v[194:195], v[194:195]
	v_pk_mul_f32 v[254:255], v[254:255], v[254:255]
	v_add_f32_e32 v170, v195, v194
	v_add_f32_e32 v170, v254, v170
	v_add_f32_e32 v170, v255, v170
	v_add_f32_e32 v164, v164, v170
	s_waitcnt vmcnt(16)
	v_pk_add_f32 v[194:195], v[14:15], v[226:227]
	v_pk_add_f32 v[254:255], v[16:17], v[228:229]
	v_cvt_pk_bf16_f32 v168, v194, v195
	v_cvt_pk_bf16_f32 v169, v254, v255
	global_store_dwordx2 v243, v[168:169], s[56:57] offset:128
	v_pk_mul_f32 v[194:195], v[194:195], v[194:195]
	v_pk_mul_f32 v[254:255], v[254:255], v[254:255]
	v_add_f32_e32 v170, v195, v194
	v_add_f32_e32 v170, v254, v170
	v_add_f32_e32 v170, v255, v170
	v_add_f32_e32 v164, v164, v170
	s_waitcnt vmcnt(16)
	v_pk_add_f32 v[194:195], v[10:11], v[230:231]
	v_pk_add_f32 v[254:255], v[12:13], v[232:233]
	v_cvt_pk_bf16_f32 v168, v194, v195
	v_cvt_pk_bf16_f32 v169, v254, v255
	global_store_dwordx2 v243, v[168:169], s[56:57] offset:160
	v_pk_mul_f32 v[194:195], v[194:195], v[194:195]
	v_pk_mul_f32 v[254:255], v[254:255], v[254:255]
	v_add_f32_e32 v170, v195, v194
	v_add_f32_e32 v170, v254, v170
	v_add_f32_e32 v170, v255, v170
	v_add_f32_e32 v164, v164, v170
	s_waitcnt vmcnt(16)
	v_pk_add_f32 v[194:195], v[6:7], v[234:235]
	v_pk_add_f32 v[254:255], v[8:9], v[236:237]
	v_cvt_pk_bf16_f32 v168, v194, v195
	v_cvt_pk_bf16_f32 v169, v254, v255
	global_store_dwordx2 v243, v[168:169], s[56:57] offset:192
	v_pk_mul_f32 v[194:195], v[194:195], v[194:195]
	v_pk_mul_f32 v[254:255], v[254:255], v[254:255]
	v_add_f32_e32 v170, v195, v194
	v_add_f32_e32 v170, v254, v170
	v_add_f32_e32 v170, v255, v170
	v_add_f32_e32 v164, v164, v170
	s_waitcnt vmcnt(16)
	v_pk_add_f32 v[194:195], v[2:3], v[238:239]
	v_pk_add_f32 v[254:255], v[4:5], v[240:241]
	v_cvt_pk_bf16_f32 v168, v194, v195
	v_cvt_pk_bf16_f32 v169, v254, v255
	global_store_dwordx2 v243, v[168:169], s[56:57] offset:224
	v_pk_mul_f32 v[194:195], v[194:195], v[194:195]
	v_pk_mul_f32 v[254:255], v[254:255], v[254:255]
	v_add_f32_e32 v170, v195, v194
	v_add_f32_e32 v170, v254, v170
	v_add_f32_e32 v170, v255, v170
	v_add_f32_e32 v164, v164, v170
	v_xor_b32_e32 v168, 16, v207
	v_lshlrev_b32_e32 v168, 2, v168
	ds_bpermute_b32 v169, v168, v164
	v_xor_b32_e32 v168, 32, v207
	v_lshlrev_b32_e32 v168, 2, v168
	s_waitcnt lgkmcnt(0)
	v_add_f32_e32 v164, v164, v169
	ds_bpermute_b32 v169, v168, v164
	v_add_u32_e32 v170, 48, v130
	v_lshlrev_b32_e32 v170, 2, v170
	v_and_b32_e32 v171, 63, v207
	v_cmp_gt_u32_e32 vcc, 16, v171
	s_waitcnt lgkmcnt(0)
	v_add_f32_e32 v164, v164, v169
	s_and_saveexec_b64 s[2:3], vcc
	global_atomic_add_f32 v170, v164, s[8:9]
	s_or_b64 exec, exec, s[2:3]
	s_branch .Lresid_next_outproj
.Lre_outproj_T:
	s_waitcnt lgkmcnt(0)
	v_add_u32_e32 v168, 0, v130
	v_lshlrev_b32_e32 v168, 11, v168
	v_lshl_add_u32 v242, v131, 1, v168
	global_load_dwordx2 v[132:133], v242, s[56:57] offset:0
	global_load_dwordx2 v[134:135], v242, s[56:57] offset:32
	global_load_dwordx2 v[136:137], v242, s[56:57] offset:64
	global_load_dwordx2 v[138:139], v242, s[56:57] offset:96
	global_load_dwordx2 v[140:141], v242, s[56:57] offset:128
	global_load_dwordx2 v[142:143], v242, s[56:57] offset:160
	global_load_dwordx2 v[144:145], v242, s[56:57] offset:192
	global_load_dwordx2 v[146:147], v242, s[56:57] offset:224
	v_add_u32_e32 v168, 16, v130
	v_lshlrev_b32_e32 v168, 11, v168
	v_lshl_add_u32 v243, v131, 1, v168
	global_load_dwordx2 v[148:149], v243, s[56:57] offset:0
	global_load_dwordx2 v[150:151], v243, s[56:57] offset:32
	global_load_dwordx2 v[152:153], v243, s[56:57] offset:64
	global_load_dwordx2 v[154:155], v243, s[56:57] offset:96
	global_load_dwordx2 v[156:157], v243, s[56:57] offset:128
	global_load_dwordx2 v[158:159], v243, s[56:57] offset:160
	global_load_dwordx2 v[160:161], v243, s[56:57] offset:192
	global_load_dwordx2 v[162:163], v243, s[56:57] offset:224
	s_waitcnt vmcnt(15)
	v_lshlrev_b32_e32 v168, 16, v132
	v_and_b32_e32 v169, 0xffff0000, v132
	v_lshlrev_b32_e32 v170, 16, v133
	v_and_b32_e32 v171, 0xffff0000, v133
	v_pk_add_f32 v[192:193], v[126:127], v[168:169]
	v_pk_add_f32 v[194:195], v[128:129], v[170:171]
	v_cvt_pk_bf16_f32 v168, v192, v193
	v_cvt_pk_bf16_f32 v169, v194, v195
	global_store_dwordx2 v242, v[168:169], s[56:57] offset:0
	v_pk_mul_f32 v[192:193], v[192:193], v[192:193]
	v_pk_mul_f32 v[194:195], v[194:195], v[194:195]
	v_add_f32_e32 v170, v193, v192
	v_add_f32_e32 v170, v194, v170
	v_add_f32_e32 v170, v195, v170
	v_mov_b32_e32 v164, v170
	s_waitcnt vmcnt(15)
	v_lshlrev_b32_e32 v168, 16, v134
	v_and_b32_e32 v169, 0xffff0000, v134
	v_lshlrev_b32_e32 v170, 16, v135
	v_and_b32_e32 v171, 0xffff0000, v135
	v_pk_add_f32 v[192:193], v[122:123], v[168:169]
	v_pk_add_f32 v[194:195], v[124:125], v[170:171]
	v_cvt_pk_bf16_f32 v168, v192, v193
	v_cvt_pk_bf16_f32 v169, v194, v195
	global_store_dwordx2 v242, v[168:169], s[56:57] offset:32
	v_pk_mul_f32 v[192:193], v[192:193], v[192:193]
	v_pk_mul_f32 v[194:195], v[194:195], v[194:195]
	v_add_f32_e32 v170, v193, v192
	v_add_f32_e32 v170, v194, v170
	v_add_f32_e32 v170, v195, v170
	v_add_f32_e32 v164, v164, v170
	s_waitcnt vmcnt(15)
	v_lshlrev_b32_e32 v168, 16, v136
	v_and_b32_e32 v169, 0xffff0000, v136
	v_lshlrev_b32_e32 v170, 16, v137
	v_and_b32_e32 v171, 0xffff0000, v137
	v_pk_add_f32 v[192:193], v[118:119], v[168:169]
	v_pk_add_f32 v[194:195], v[120:121], v[170:171]
	v_cvt_pk_bf16_f32 v168, v192, v193
	v_cvt_pk_bf16_f32 v169, v194, v195
	global_store_dwordx2 v242, v[168:169], s[56:57] offset:64
	v_pk_mul_f32 v[192:193], v[192:193], v[192:193]
	v_pk_mul_f32 v[194:195], v[194:195], v[194:195]
	v_add_f32_e32 v170, v193, v192
	v_add_f32_e32 v170, v194, v170
	v_add_f32_e32 v170, v195, v170
	v_add_f32_e32 v164, v164, v170
	s_waitcnt vmcnt(15)
; template <int MI, int NI>
; DI void resid_epilogue(const Params& p, int from_x, const f32x4 (&acc)[NI][MI], int row0, int n0, float* rowss_next, bool last, int lm, int lg) {
; #pragma unroll
;   for (int mi = 0; mi < MI; ++mi) {
;     const int m = row0 + mi * 16 + lm;
;     const float* hr = hrow_r(p, from_x == 1 ? 0 : 1, m);
;     float* hw = hrow_w(p, m);
;     u16* hbr = p.hb + (size_t)m * DM;
;     float ss = 0.f;
; #pragma unroll
;     for (int ni = 0; ni < NI; ++ni) {
;       const int n = n0 + ni * 16 + lg * 4;
;       float4 h;
;       if (from_x >= 2) {
;         const u32x2 pk = *(const u32x2*)(hbr + n);
;         h = make_float4(__uint_as_float(pk[0] << 16), __uint_as_float(pk[0] & 0xffff0000u), __uint_as_float(pk[1] << 16), __uint_as_float(pk[1] & 0xffff0000u));
;       } else h = *(const float4*)(hr + n);
;       h.x += acc[ni][mi][0]; h.y += acc[ni][mi][1]; h.z += acc[ni][mi][2]; h.w += acc[ni][mi][3];
;       if (last) *(float4*)(hw + n) = h;
;       if (!last) {
;         u32x2 pk = {pack2bf(h.x, h.y), pack2bf(h.z, h.w)};
;         *(u32x2*)(hbr + n) = pk;
;         ss += h.x * h.x + h.y * h.y + h.z * h.z + h.w * h.w;
;       }
;     }
;     if (!last) {
;       ss += __shfl_xor(ss, 16);
;       ss += __shfl_xor(ss, 32);
;       if (lg == 0) atomicAdd(rowss_next + m, ss);
;     }
	v_lshlrev_b32_e32 v168, 16, v138
	v_and_b32_e32 v169, 0xffff0000, v138
	v_lshlrev_b32_e32 v170, 16, v139
	v_and_b32_e32 v171, 0xffff0000, v139
	v_pk_add_f32 v[192:193], v[114:115], v[168:169]
	v_pk_add_f32 v[194:195], v[116:117], v[170:171]
	v_cvt_pk_bf16_f32 v168, v192, v193
	v_cvt_pk_bf16_f32 v169, v194, v195
	global_store_dwordx2 v242, v[168:169], s[56:57] offset:96
	v_pk_mul_f32 v[192:193], v[192:193], v[192:193]
	v_pk_mul_f32 v[194:195], v[194:195], v[194:195]
	v_add_f32_e32 v170, v193, v192
	v_add_f32_e32 v170, v194, v170
	v_add_f32_e32 v170, v195, v170
	v_add_f32_e32 v164, v164, v170
	s_waitcnt vmcnt(15)
	v_lshlrev_b32_e32 v168, 16, v140
	v_and_b32_e32 v169, 0xffff0000, v140
	v_lshlrev_b32_e32 v170, 16, v141
	v_and_b32_e32 v171, 0xffff0000, v141
	v_pk_add_f32 v[192:193], v[110:111], v[168:169]
	v_pk_add_f32 v[194:195], v[112:113], v[170:171]
	v_cvt_pk_bf16_f32 v168, v192, v193
	v_cvt_pk_bf16_f32 v169, v194, v195
	global_store_dwordx2 v242, v[168:169], s[56:57] offset:128
	v_pk_mul_f32 v[192:193], v[192:193], v[192:193]
	v_pk_mul_f32 v[194:195], v[194:195], v[194:195]
	v_add_f32_e32 v170, v193, v192
	v_add_f32_e32 v170, v194, v170
	v_add_f32_e32 v170, v195, v170
	v_add_f32_e32 v164, v164, v170
	s_waitcnt vmcnt(15)
	v_lshlrev_b32_e32 v168, 16, v142
	v_and_b32_e32 v169, 0xffff0000, v142
	v_lshlrev_b32_e32 v170, 16, v143
	v_and_b32_e32 v171, 0xffff0000, v143
	v_pk_add_f32 v[192:193], v[106:107], v[168:169]
	v_pk_add_f32 v[194:195], v[108:109], v[170:171]
	v_cvt_pk_bf16_f32 v168, v192, v193
	v_cvt_pk_bf16_f32 v169, v194, v195
	global_store_dwordx2 v242, v[168:169], s[56:57] offset:160
	v_pk_mul_f32 v[192:193], v[192:193], v[192:193]
	v_pk_mul_f32 v[194:195], v[194:195], v[194:195]
	v_add_f32_e32 v170, v193, v192
	v_add_f32_e32 v170, v194, v170
	v_add_f32_e32 v170, v195, v170
	v_add_f32_e32 v164, v164, v170
	s_waitcnt vmcnt(15)
	v_lshlrev_b32_e32 v168, 16, v144
	v_and_b32_e32 v169, 0xffff0000, v144
	v_lshlrev_b32_e32 v170, 16, v145
	v_and_b32_e32 v171, 0xffff0000, v145
	v_pk_add_f32 v[192:193], v[102:103], v[168:169]
	v_pk_add_f32 v[194:195], v[104:105], v[170:171]
	v_cvt_pk_bf16_f32 v168, v192, v193
	v_cvt_pk_bf16_f32 v169, v194, v195
	global_store_dwordx2 v242, v[168:169], s[56:57] offset:192
	v_pk_mul_f32 v[192:193], v[192:193], v[192:193]
	v_pk_mul_f32 v[194:195], v[194:195], v[194:195]
	v_add_f32_e32 v170, v193, v192
	v_add_f32_e32 v170, v194, v170
	v_add_f32_e32 v170, v195, v170
	v_add_f32_e32 v164, v164, v170
	s_waitcnt vmcnt(15)
	v_lshlrev_b32_e32 v168, 16, v146
	v_and_b32_e32 v169, 0xffff0000, v146
	v_lshlrev_b32_e32 v170, 16, v147
	v_and_b32_e32 v171, 0xffff0000, v147
	v_pk_add_f32 v[192:193], v[98:99], v[168:169]
	v_pk_add_f32 v[194:195], v[100:101], v[170:171]
	v_cvt_pk_bf16_f32 v168, v192, v193
	v_cvt_pk_bf16_f32 v169, v194, v195
	global_store_dwordx2 v242, v[168:169], s[56:57] offset:224
	v_pk_mul_f32 v[192:193], v[192:193], v[192:193]
	v_pk_mul_f32 v[194:195], v[194:195], v[194:195]
	v_add_f32_e32 v170, v193, v192
	v_add_f32_e32 v170, v194, v170
	v_add_f32_e32 v170, v195, v170
	v_add_f32_e32 v164, v164, v170
	v_xor_b32_e32 v168, 16, v207
	v_lshlrev_b32_e32 v168, 2, v168
	ds_bpermute_b32 v169, v168, v164
	v_xor_b32_e32 v168, 32, v207
	v_lshlrev_b32_e32 v168, 2, v168
	s_waitcnt lgkmcnt(0)
	v_add_f32_e32 v164, v164, v169
	ds_bpermute_b32 v169, v168, v164
	v_add_u32_e32 v170, 0, v130
	v_lshlrev_b32_e32 v170, 2, v170
	v_and_b32_e32 v171, 63, v207
	v_cmp_gt_u32_e32 vcc, 16, v171
	s_waitcnt lgkmcnt(0)
	v_add_f32_e32 v164, v164, v169
	s_and_saveexec_b64 s[2:3], vcc
	global_atomic_add_f32 v170, v164, s[8:9]
	s_or_b64 exec, exec, s[2:3]
	v_add_u32_e32 v168, 32, v130
	v_lshlrev_b32_e32 v168, 11, v168
	v_lshl_add_u32 v242, v131, 1, v168
	global_load_dwordx2 v[132:133], v242, s[56:57] offset:0
	global_load_dwordx2 v[134:135], v242, s[56:57] offset:32
	global_load_dwordx2 v[136:137], v242, s[56:57] offset:64
	global_load_dwordx2 v[138:139], v242, s[56:57] offset:96
	global_load_dwordx2 v[140:141], v242, s[56:57] offset:128
	global_load_dwordx2 v[142:143], v242, s[56:57] offset:160
	global_load_dwordx2 v[144:145], v242, s[56:57] offset:192
	global_load_dwordx2 v[146:147], v242, s[56:57] offset:224
	s_waitcnt vmcnt(24)
	v_lshlrev_b32_e32 v168, 16, v148
	v_and_b32_e32 v169, 0xffff0000, v148
	v_lshlrev_b32_e32 v170, 16, v149
	v_and_b32_e32 v171, 0xffff0000, v149
	v_pk_add_f32 v[192:193], v[94:95], v[168:169]
	v_pk_add_f32 v[194:195], v[96:97], v[170:171]
	v_cvt_pk_bf16_f32 v168, v192, v193
	v_cvt_pk_bf16_f32 v169, v194, v195
	global_store_dwordx2 v243, v[168:169], s[56:57] offset:0
	v_pk_mul_f32 v[192:193], v[192:193], v[192:193]
	v_pk_mul_f32 v[194:195], v[194:195], v[194:195]
	v_add_f32_e32 v170, v193, v192
	v_add_f32_e32 v170, v194, v170
	v_add_f32_e32 v170, v195, v170
	v_mov_b32_e32 v164, v170
	s_waitcnt vmcnt(24)
	v_lshlrev_b32_e32 v168, 16, v150
	v_and_b32_e32 v169, 0xffff0000, v150
	v_lshlrev_b32_e32 v170, 16, v151
	v_and_b32_e32 v171, 0xffff0000, v151
	v_pk_add_f32 v[192:193], v[90:91], v[168:169]
	v_pk_add_f32 v[194:195], v[92:93], v[170:171]
	v_cvt_pk_bf16_f32 v168, v192, v193
	v_cvt_pk_bf16_f32 v169, v194, v195
	global_store_dwordx2 v243, v[168:169], s[56:57] offset:32
	v_pk_mul_f32 v[192:193], v[192:193], v[192:193]
	v_pk_mul_f32 v[194:195], v[194:195], v[194:195]
	v_add_f32_e32 v170, v193, v192
	v_add_f32_e32 v170, v194, v170
	v_add_f32_e32 v170, v195, v170
	v_add_f32_e32 v164, v164, v170
	s_waitcnt vmcnt(24)
; template <int MI, int NI>
; DI void resid_epilogue(const Params& p, int from_x, const f32x4 (&acc)[NI][MI], int row0, int n0, float* rowss_next, bool last, int lm, int lg) {
; #pragma unroll
;   for (int mi = 0; mi < MI; ++mi) {
;     const int m = row0 + mi * 16 + lm;
;     const float* hr = hrow_r(p, from_x == 1 ? 0 : 1, m);
;     float* hw = hrow_w(p, m);
;     u16* hbr = p.hb + (size_t)m * DM;
;     float ss = 0.f;
; #pragma unroll
;     for (int ni = 0; ni < NI; ++ni) {
;       const int n = n0 + ni * 16 + lg * 4;
;       float4 h;
;       if (from_x >= 2) {
;         const u32x2 pk = *(const u32x2*)(hbr + n);
;         h = make_float4(__uint_as_float(pk[0] << 16), __uint_as_float(pk[0] & 0xffff0000u), __uint_as_float(pk[1] << 16), __uint_as_float(pk[1] & 0xffff0000u));
;       } else h = *(const float4*)(hr + n);
;       h.x += acc[ni][mi][0]; h.y += acc[ni][mi][1]; h.z += acc[ni][mi][2]; h.w += acc[ni][mi][3];
;       if (last) *(float4*)(hw + n) = h;
;       if (!last) {
;         u32x2 pk = {pack2bf(h.x, h.y), pack2bf(h.z, h.w)};
;         *(u32x2*)(hbr + n) = pk;
;         ss += h.x * h.x + h.y * h.y + h.z * h.z + h.w * h.w;
;       }
;     }
;     if (!last) {
;       ss += __shfl_xor(ss, 16);
;       ss += __shfl_xor(ss, 32);
;       if (lg == 0) atomicAdd(rowss_next + m, ss);
;     }
	v_lshlrev_b32_e32 v168, 16, v152
	v_and_b32_e32 v169, 0xffff0000, v152
	v_lshlrev_b32_e32 v170, 16, v153
	v_and_b32_e32 v171, 0xffff0000, v153
	v_pk_add_f32 v[192:193], v[86:87], v[168:169]
	v_pk_add_f32 v[194:195], v[88:89], v[170:171]
	v_cvt_pk_bf16_f32 v168, v192, v193
	v_cvt_pk_bf16_f32 v169, v194, v195
	global_store_dwordx2 v243, v[168:169], s[56:57] offset:64
	v_pk_mul_f32 v[192:193], v[192:193], v[192:193]
	v_pk_mul_f32 v[194:195], v[194:195], v[194:195]
	v_add_f32_e32 v170, v193, v192
	v_add_f32_e32 v170, v194, v170
	v_add_f32_e32 v170, v195, v170
	v_add_f32_e32 v164, v164, v170
	s_waitcnt vmcnt(24)
	v_lshlrev_b32_e32 v168, 16, v154
	v_and_b32_e32 v169, 0xffff0000, v154
	v_lshlrev_b32_e32 v170, 16, v155
	v_and_b32_e32 v171, 0xffff0000, v155
	v_pk_add_f32 v[192:193], v[82:83], v[168:169]
	v_pk_add_f32 v[194:195], v[84:85], v[170:171]
	v_cvt_pk_bf16_f32 v168, v192, v193
	v_cvt_pk_bf16_f32 v169, v194, v195
	global_store_dwordx2 v243, v[168:169], s[56:57] offset:96
	v_pk_mul_f32 v[192:193], v[192:193], v[192:193]
	v_pk_mul_f32 v[194:195], v[194:195], v[194:195]
	v_add_f32_e32 v170, v193, v192
	v_add_f32_e32 v170, v194, v170
	v_add_f32_e32 v170, v195, v170
	v_add_f32_e32 v164, v164, v170
	s_waitcnt vmcnt(24)
	v_lshlrev_b32_e32 v168, 16, v156
	v_and_b32_e32 v169, 0xffff0000, v156
	v_lshlrev_b32_e32 v170, 16, v157
	v_and_b32_e32 v171, 0xffff0000, v157
	v_pk_add_f32 v[192:193], v[78:79], v[168:169]
	v_pk_add_f32 v[194:195], v[80:81], v[170:171]
	v_cvt_pk_bf16_f32 v168, v192, v193
	v_cvt_pk_bf16_f32 v169, v194, v195
	global_store_dwordx2 v243, v[168:169], s[56:57] offset:128
	v_pk_mul_f32 v[192:193], v[192:193], v[192:193]
	v_pk_mul_f32 v[194:195], v[194:195], v[194:195]
	v_add_f32_e32 v170, v193, v192
	v_add_f32_e32 v170, v194, v170
	v_add_f32_e32 v170, v195, v170
	v_add_f32_e32 v164, v164, v170
	s_waitcnt vmcnt(24)
	v_lshlrev_b32_e32 v168, 16, v158
	v_and_b32_e32 v169, 0xffff0000, v158
	v_lshlrev_b32_e32 v170, 16, v159
	v_and_b32_e32 v171, 0xffff0000, v159
	v_pk_add_f32 v[192:193], v[74:75], v[168:169]
	v_pk_add_f32 v[194:195], v[76:77], v[170:171]
	v_cvt_pk_bf16_f32 v168, v192, v193
	v_cvt_pk_bf16_f32 v169, v194, v195
	global_store_dwordx2 v243, v[168:169], s[56:57] offset:160
	v_pk_mul_f32 v[192:193], v[192:193], v[192:193]
	v_pk_mul_f32 v[194:195], v[194:195], v[194:195]
	v_add_f32_e32 v170, v193, v192
	v_add_f32_e32 v170, v194, v170
	v_add_f32_e32 v170, v195, v170
	v_add_f32_e32 v164, v164, v170
	s_waitcnt vmcnt(24)
	v_lshlrev_b32_e32 v168, 16, v160
	v_and_b32_e32 v169, 0xffff0000, v160
	v_lshlrev_b32_e32 v170, 16, v161
	v_and_b32_e32 v171, 0xffff0000, v161
	v_pk_add_f32 v[192:193], v[70:71], v[168:169]
	v_pk_add_f32 v[194:195], v[72:73], v[170:171]
	v_cvt_pk_bf16_f32 v168, v192, v193
	v_cvt_pk_bf16_f32 v169, v194, v195
	global_store_dwordx2 v243, v[168:169], s[56:57] offset:192
	v_pk_mul_f32 v[192:193], v[192:193], v[192:193]
	v_pk_mul_f32 v[194:195], v[194:195], v[194:195]
	v_add_f32_e32 v170, v193, v192
	v_add_f32_e32 v170, v194, v170
	v_add_f32_e32 v170, v195, v170
	v_add_f32_e32 v164, v164, v170
	s_waitcnt vmcnt(24)
	v_lshlrev_b32_e32 v168, 16, v162
	v_and_b32_e32 v169, 0xffff0000, v162
	v_lshlrev_b32_e32 v170, 16, v163
	v_and_b32_e32 v171, 0xffff0000, v163
	v_pk_add_f32 v[192:193], v[66:67], v[168:169]
	v_pk_add_f32 v[194:195], v[68:69], v[170:171]
	v_cvt_pk_bf16_f32 v168, v192, v193
	v_cvt_pk_bf16_f32 v169, v194, v195
	global_store_dwordx2 v243, v[168:169], s[56:57] offset:224
	v_pk_mul_f32 v[192:193], v[192:193], v[192:193]
	v_pk_mul_f32 v[194:195], v[194:195], v[194:195]
	v_add_f32_e32 v170, v193, v192
	v_add_f32_e32 v170, v194, v170
	v_add_f32_e32 v170, v195, v170
	v_add_f32_e32 v164, v164, v170
	v_xor_b32_e32 v168, 16, v207
	v_lshlrev_b32_e32 v168, 2, v168
	ds_bpermute_b32 v169, v168, v164
	v_xor_b32_e32 v168, 32, v207
	v_lshlrev_b32_e32 v168, 2, v168
	s_waitcnt lgkmcnt(0)
	v_add_f32_e32 v164, v164, v169
	ds_bpermute_b32 v169, v168, v164
	v_add_u32_e32 v170, 16, v130
	v_lshlrev_b32_e32 v170, 2, v170
	v_and_b32_e32 v171, 63, v207
	v_cmp_gt_u32_e32 vcc, 16, v171
	s_waitcnt lgkmcnt(0)
	v_add_f32_e32 v164, v164, v169
	s_and_saveexec_b64 s[2:3], vcc
	global_atomic_add_f32 v170, v164, s[8:9]
	s_or_b64 exec, exec, s[2:3]
	v_add_u32_e32 v168, 48, v130
	v_lshlrev_b32_e32 v168, 11, v168
	v_lshl_add_u32 v243, v131, 1, v168
	global_load_dwordx2 v[148:149], v243, s[56:57] offset:0
	global_load_dwordx2 v[150:151], v243, s[56:57] offset:32
	global_load_dwordx2 v[152:153], v243, s[56:57] offset:64
	global_load_dwordx2 v[154:155], v243, s[56:57] offset:96
	global_load_dwordx2 v[156:157], v243, s[56:57] offset:128
	global_load_dwordx2 v[158:159], v243, s[56:57] offset:160
	global_load_dwordx2 v[160:161], v243, s[56:57] offset:192
	global_load_dwordx2 v[162:163], v243, s[56:57] offset:224
	s_waitcnt vmcnt(24)
	v_lshlrev_b32_e32 v168, 16, v132
	v_and_b32_e32 v169, 0xffff0000, v132
	v_lshlrev_b32_e32 v170, 16, v133
	v_and_b32_e32 v171, 0xffff0000, v133
	v_pk_add_f32 v[192:193], v[62:63], v[168:169]
	v_pk_add_f32 v[194:195], v[64:65], v[170:171]
	v_cvt_pk_bf16_f32 v168, v192, v193
	v_cvt_pk_bf16_f32 v169, v194, v195
	global_store_dwordx2 v242, v[168:169], s[56:57] offset:0
	v_pk_mul_f32 v[192:193], v[192:193], v[192:193]
	v_pk_mul_f32 v[194:195], v[194:195], v[194:195]
	v_add_f32_e32 v170, v193, v192
	v_add_f32_e32 v170, v194, v170
	v_add_f32_e32 v170, v195, v170
	v_mov_b32_e32 v164, v170
	s_waitcnt vmcnt(24)
; template <int MI, int NI>
; DI void resid_epilogue(const Params& p, int from_x, const f32x4 (&acc)[NI][MI], int row0, int n0, float* rowss_next, bool last, int lm, int lg) {
; #pragma unroll
;   for (int mi = 0; mi < MI; ++mi) {
;     const int m = row0 + mi * 16 + lm;
;     const float* hr = hrow_r(p, from_x == 1 ? 0 : 1, m);
;     float* hw = hrow_w(p, m);
;     u16* hbr = p.hb + (size_t)m * DM;
;     float ss = 0.f;
; #pragma unroll
;     for (int ni = 0; ni < NI; ++ni) {
;       const int n = n0 + ni * 16 + lg * 4;
;       float4 h;
;       if (from_x >= 2) {
;         const u32x2 pk = *(const u32x2*)(hbr + n);
;         h = make_float4(__uint_as_float(pk[0] << 16), __uint_as_float(pk[0] & 0xffff0000u), __uint_as_float(pk[1] << 16), __uint_as_float(pk[1] & 0xffff0000u));
;       } else h = *(const float4*)(hr + n);
;       h.x += acc[ni][mi][0]; h.y += acc[ni][mi][1]; h.z += acc[ni][mi][2]; h.w += acc[ni][mi][3];
;       if (last) *(float4*)(hw + n) = h;
;       if (!last) {
;         u32x2 pk = {pack2bf(h.x, h.y), pack2bf(h.z, h.w)};
;         *(u32x2*)(hbr + n) = pk;
;         ss += h.x * h.x + h.y * h.y + h.z * h.z + h.w * h.w;
;       }
;     }
;     if (!last) {
;       ss += __shfl_xor(ss, 16);
;       ss += __shfl_xor(ss, 32);
;       if (lg == 0) atomicAdd(rowss_next + m, ss);
;     }
	v_lshlrev_b32_e32 v168, 16, v134
	v_and_b32_e32 v169, 0xffff0000, v134
	v_lshlrev_b32_e32 v170, 16, v135
	v_and_b32_e32 v171, 0xffff0000, v135
	v_pk_add_f32 v[192:193], v[58:59], v[168:169]
	v_pk_add_f32 v[194:195], v[60:61], v[170:171]
	v_cvt_pk_bf16_f32 v168, v192, v193
	v_cvt_pk_bf16_f32 v169, v194, v195
	global_store_dwordx2 v242, v[168:169], s[56:57] offset:32
	v_pk_mul_f32 v[192:193], v[192:193], v[192:193]
	v_pk_mul_f32 v[194:195], v[194:195], v[194:195]
	v_add_f32_e32 v170, v193, v192
	v_add_f32_e32 v170, v194, v170
	v_add_f32_e32 v170, v195, v170
	v_add_f32_e32 v164, v164, v170
	s_waitcnt vmcnt(24)
	v_lshlrev_b32_e32 v168, 16, v136
	v_and_b32_e32 v169, 0xffff0000, v136
	v_lshlrev_b32_e32 v170, 16, v137
	v_and_b32_e32 v171, 0xffff0000, v137
	v_pk_add_f32 v[192:193], v[54:55], v[168:169]
	v_pk_add_f32 v[194:195], v[56:57], v[170:171]
	v_cvt_pk_bf16_f32 v168, v192, v193
	v_cvt_pk_bf16_f32 v169, v194, v195
	global_store_dwordx2 v242, v[168:169], s[56:57] offset:64
	v_pk_mul_f32 v[192:193], v[192:193], v[192:193]
	v_pk_mul_f32 v[194:195], v[194:195], v[194:195]
	v_add_f32_e32 v170, v193, v192
	v_add_f32_e32 v170, v194, v170
	v_add_f32_e32 v170, v195, v170
	v_add_f32_e32 v164, v164, v170
	s_waitcnt vmcnt(24)
	v_lshlrev_b32_e32 v168, 16, v138
	v_and_b32_e32 v169, 0xffff0000, v138
	v_lshlrev_b32_e32 v170, 16, v139
	v_and_b32_e32 v171, 0xffff0000, v139
	v_pk_add_f32 v[192:193], v[50:51], v[168:169]
	v_pk_add_f32 v[194:195], v[52:53], v[170:171]
	v_cvt_pk_bf16_f32 v168, v192, v193
	v_cvt_pk_bf16_f32 v169, v194, v195
	global_store_dwordx2 v242, v[168:169], s[56:57] offset:96
	v_pk_mul_f32 v[192:193], v[192:193], v[192:193]
	v_pk_mul_f32 v[194:195], v[194:195], v[194:195]
	v_add_f32_e32 v170, v193, v192
	v_add_f32_e32 v170, v194, v170
	v_add_f32_e32 v170, v195, v170
	v_add_f32_e32 v164, v164, v170
	s_waitcnt vmcnt(24)
	v_lshlrev_b32_e32 v168, 16, v140
	v_and_b32_e32 v169, 0xffff0000, v140
	v_lshlrev_b32_e32 v170, 16, v141
	v_and_b32_e32 v171, 0xffff0000, v141
	v_pk_add_f32 v[192:193], v[46:47], v[168:169]
	v_pk_add_f32 v[194:195], v[48:49], v[170:171]
	v_cvt_pk_bf16_f32 v168, v192, v193
	v_cvt_pk_bf16_f32 v169, v194, v195
	global_store_dwordx2 v242, v[168:169], s[56:57] offset:128
	v_pk_mul_f32 v[192:193], v[192:193], v[192:193]
	v_pk_mul_f32 v[194:195], v[194:195], v[194:195]
	v_add_f32_e32 v170, v193, v192
	v_add_f32_e32 v170, v194, v170
	v_add_f32_e32 v170, v195, v170
	v_add_f32_e32 v164, v164, v170
	s_waitcnt vmcnt(24)
	v_lshlrev_b32_e32 v168, 16, v142
	v_and_b32_e32 v169, 0xffff0000, v142
	v_lshlrev_b32_e32 v170, 16, v143
	v_and_b32_e32 v171, 0xffff0000, v143
	v_pk_add_f32 v[192:193], v[42:43], v[168:169]
	v_pk_add_f32 v[194:195], v[44:45], v[170:171]
	v_cvt_pk_bf16_f32 v168, v192, v193
	v_cvt_pk_bf16_f32 v169, v194, v195
	global_store_dwordx2 v242, v[168:169], s[56:57] offset:160
	v_pk_mul_f32 v[192:193], v[192:193], v[192:193]
	v_pk_mul_f32 v[194:195], v[194:195], v[194:195]
	v_add_f32_e32 v170, v193, v192
	v_add_f32_e32 v170, v194, v170
	v_add_f32_e32 v170, v195, v170
	v_add_f32_e32 v164, v164, v170
	s_waitcnt vmcnt(24)
	v_lshlrev_b32_e32 v168, 16, v144
	v_and_b32_e32 v169, 0xffff0000, v144
	v_lshlrev_b32_e32 v170, 16, v145
	v_and_b32_e32 v171, 0xffff0000, v145
	v_pk_add_f32 v[192:193], v[38:39], v[168:169]
	v_pk_add_f32 v[194:195], v[40:41], v[170:171]
	v_cvt_pk_bf16_f32 v168, v192, v193
	v_cvt_pk_bf16_f32 v169, v194, v195
	global_store_dwordx2 v242, v[168:169], s[56:57] offset:192
	v_pk_mul_f32 v[192:193], v[192:193], v[192:193]
	v_pk_mul_f32 v[194:195], v[194:195], v[194:195]
	v_add_f32_e32 v170, v193, v192
	v_add_f32_e32 v170, v194, v170
	v_add_f32_e32 v170, v195, v170
	v_add_f32_e32 v164, v164, v170
	s_waitcnt vmcnt(24)
	v_lshlrev_b32_e32 v168, 16, v146
	v_and_b32_e32 v169, 0xffff0000, v146
	v_lshlrev_b32_e32 v170, 16, v147
	v_and_b32_e32 v171, 0xffff0000, v147
	v_pk_add_f32 v[192:193], v[34:35], v[168:169]
	v_pk_add_f32 v[194:195], v[36:37], v[170:171]
	v_cvt_pk_bf16_f32 v168, v192, v193
	v_cvt_pk_bf16_f32 v169, v194, v195
	global_store_dwordx2 v242, v[168:169], s[56:57] offset:224
	v_pk_mul_f32 v[192:193], v[192:193], v[192:193]
	v_pk_mul_f32 v[194:195], v[194:195], v[194:195]
	v_add_f32_e32 v170, v193, v192
	v_add_f32_e32 v170, v194, v170
	v_add_f32_e32 v170, v195, v170
	v_add_f32_e32 v164, v164, v170
	v_xor_b32_e32 v168, 16, v207
	v_lshlrev_b32_e32 v168, 2, v168
	ds_bpermute_b32 v169, v168, v164
	v_xor_b32_e32 v168, 32, v207
	v_lshlrev_b32_e32 v168, 2, v168
	s_waitcnt lgkmcnt(0)
	v_add_f32_e32 v164, v164, v169
	ds_bpermute_b32 v169, v168, v164
	v_add_u32_e32 v170, 32, v130
	v_lshlrev_b32_e32 v170, 2, v170
	v_and_b32_e32 v171, 63, v207
	v_cmp_gt_u32_e32 vcc, 16, v171
	s_waitcnt lgkmcnt(0)
	v_add_f32_e32 v164, v164, v169
	s_and_saveexec_b64 s[2:3], vcc
	global_atomic_add_f32 v170, v164, s[8:9]
	s_or_b64 exec, exec, s[2:3]
	s_waitcnt vmcnt(16)
	v_lshlrev_b32_e32 v168, 16, v148
	v_and_b32_e32 v169, 0xffff0000, v148
	v_lshlrev_b32_e32 v170, 16, v149
	v_and_b32_e32 v171, 0xffff0000, v149
	v_pk_add_f32 v[192:193], v[30:31], v[168:169]
	v_pk_add_f32 v[194:195], v[32:33], v[170:171]
	v_cvt_pk_bf16_f32 v168, v192, v193
	v_cvt_pk_bf16_f32 v169, v194, v195
	global_store_dwordx2 v243, v[168:169], s[56:57] offset:0
	v_pk_mul_f32 v[192:193], v[192:193], v[192:193]
	v_pk_mul_f32 v[194:195], v[194:195], v[194:195]
	v_add_f32_e32 v170, v193, v192
	v_add_f32_e32 v170, v194, v170
	v_add_f32_e32 v170, v195, v170
	v_mov_b32_e32 v164, v170
	s_waitcnt vmcnt(16)
; template <int MI, int NI>
; DI void resid_epilogue(const Params& p, int from_x, const f32x4 (&acc)[NI][MI], int row0, int n0, float* rowss_next, bool last, int lm, int lg) {
; #pragma unroll
;   for (int mi = 0; mi < MI; ++mi) {
;     const int m = row0 + mi * 16 + lm;
;     const float* hr = hrow_r(p, from_x == 1 ? 0 : 1, m);
;     float* hw = hrow_w(p, m);
;     u16* hbr = p.hb + (size_t)m * DM;
;     float ss = 0.f;
; #pragma unroll
;     for (int ni = 0; ni < NI; ++ni) {
;       const int n = n0 + ni * 16 + lg * 4;
;       float4 h;
;       if (from_x >= 2) {
;         const u32x2 pk = *(const u32x2*)(hbr + n);
;         h = make_float4(__uint_as_float(pk[0] << 16), __uint_as_float(pk[0] & 0xffff0000u), __uint_as_float(pk[1] << 16), __uint_as_float(pk[1] & 0xffff0000u));
;       } else h = *(const float4*)(hr + n);
;       h.x += acc[ni][mi][0]; h.y += acc[ni][mi][1]; h.z += acc[ni][mi][2]; h.w += acc[ni][mi][3];
;       if (last) *(float4*)(hw + n) = h;
;       if (!last) {
;         u32x2 pk = {pack2bf(h.x, h.y), pack2bf(h.z, h.w)};
;         *(u32x2*)(hbr + n) = pk;
;         ss += h.x * h.x + h.y * h.y + h.z * h.z + h.w * h.w;
;       }
;     }
;     if (!last) {
;       ss += __shfl_xor(ss, 16);
;       ss += __shfl_xor(ss, 32);
;       if (lg == 0) atomicAdd(rowss_next + m, ss);
;     }
	v_lshlrev_b32_e32 v168, 16, v150
	v_and_b32_e32 v169, 0xffff0000, v150
	v_lshlrev_b32_e32 v170, 16, v151
	v_and_b32_e32 v171, 0xffff0000, v151
	v_pk_add_f32 v[192:193], v[26:27], v[168:169]
	v_pk_add_f32 v[194:195], v[28:29], v[170:171]
	v_cvt_pk_bf16_f32 v168, v192, v193
	v_cvt_pk_bf16_f32 v169, v194, v195
	global_store_dwordx2 v243, v[168:169], s[56:57] offset:32
	v_pk_mul_f32 v[192:193], v[192:193], v[192:193]
	v_pk_mul_f32 v[194:195], v[194:195], v[194:195]
	v_add_f32_e32 v170, v193, v192
	v_add_f32_e32 v170, v194, v170
	v_add_f32_e32 v170, v195, v170
	v_add_f32_e32 v164, v164, v170
	s_waitcnt vmcnt(16)
	v_lshlrev_b32_e32 v168, 16, v152
	v_and_b32_e32 v169, 0xffff0000, v152
	v_lshlrev_b32_e32 v170, 16, v153
	v_and_b32_e32 v171, 0xffff0000, v153
	v_pk_add_f32 v[192:193], v[22:23], v[168:169]
	v_pk_add_f32 v[194:195], v[24:25], v[170:171]
	v_cvt_pk_bf16_f32 v168, v192, v193
	v_cvt_pk_bf16_f32 v169, v194, v195
	global_store_dwordx2 v243, v[168:169], s[56:57] offset:64
	v_pk_mul_f32 v[192:193], v[192:193], v[192:193]
	v_pk_mul_f32 v[194:195], v[194:195], v[194:195]
	v_add_f32_e32 v170, v193, v192
	v_add_f32_e32 v170, v194, v170
	v_add_f32_e32 v170, v195, v170
	v_add_f32_e32 v164, v164, v170
	s_waitcnt vmcnt(16)
	v_lshlrev_b32_e32 v168, 16, v154
	v_and_b32_e32 v169, 0xffff0000, v154
	v_lshlrev_b32_e32 v170, 16, v155
	v_and_b32_e32 v171, 0xffff0000, v155
	v_pk_add_f32 v[192:193], v[18:19], v[168:169]
	v_pk_add_f32 v[194:195], v[20:21], v[170:171]
	v_cvt_pk_bf16_f32 v168, v192, v193
	v_cvt_pk_bf16_f32 v169, v194, v195
	global_store_dwordx2 v243, v[168:169], s[56:57] offset:96
	v_pk_mul_f32 v[192:193], v[192:193], v[192:193]
	v_pk_mul_f32 v[194:195], v[194:195], v[194:195]
	v_add_f32_e32 v170, v193, v192
	v_add_f32_e32 v170, v194, v170
	v_add_f32_e32 v170, v195, v170
	v_add_f32_e32 v164, v164, v170
	s_waitcnt vmcnt(16)
	v_lshlrev_b32_e32 v168, 16, v156
	v_and_b32_e32 v169, 0xffff0000, v156
	v_lshlrev_b32_e32 v170, 16, v157
	v_and_b32_e32 v171, 0xffff0000, v157
	v_pk_add_f32 v[192:193], v[14:15], v[168:169]
	v_pk_add_f32 v[194:195], v[16:17], v[170:171]
	v_cvt_pk_bf16_f32 v168, v192, v193
	v_cvt_pk_bf16_f32 v169, v194, v195
	global_store_dwordx2 v243, v[168:169], s[56:57] offset:128
	v_pk_mul_f32 v[192:193], v[192:193], v[192:193]
	v_pk_mul_f32 v[194:195], v[194:195], v[194:195]
	v_add_f32_e32 v170, v193, v192
	v_add_f32_e32 v170, v194, v170
	v_add_f32_e32 v170, v195, v170
	v_add_f32_e32 v164, v164, v170
	s_waitcnt vmcnt(16)
	v_lshlrev_b32_e32 v168, 16, v158
	v_and_b32_e32 v169, 0xffff0000, v158
	v_lshlrev_b32_e32 v170, 16, v159
	v_and_b32_e32 v171, 0xffff0000, v159
	v_pk_add_f32 v[192:193], v[10:11], v[168:169]
	v_pk_add_f32 v[194:195], v[12:13], v[170:171]
	v_cvt_pk_bf16_f32 v168, v192, v193
	v_cvt_pk_bf16_f32 v169, v194, v195
	global_store_dwordx2 v243, v[168:169], s[56:57] offset:160
	v_pk_mul_f32 v[192:193], v[192:193], v[192:193]
	v_pk_mul_f32 v[194:195], v[194:195], v[194:195]
	v_add_f32_e32 v170, v193, v192
	v_add_f32_e32 v170, v194, v170
	v_add_f32_e32 v170, v195, v170
	v_add_f32_e32 v164, v164, v170
	s_waitcnt vmcnt(16)
	v_lshlrev_b32_e32 v168, 16, v160
	v_and_b32_e32 v169, 0xffff0000, v160
	v_lshlrev_b32_e32 v170, 16, v161
	v_and_b32_e32 v171, 0xffff0000, v161
	v_pk_add_f32 v[192:193], v[6:7], v[168:169]
	v_pk_add_f32 v[194:195], v[8:9], v[170:171]
	v_cvt_pk_bf16_f32 v168, v192, v193
	v_cvt_pk_bf16_f32 v169, v194, v195
	global_store_dwordx2 v243, v[168:169], s[56:57] offset:192
	v_pk_mul_f32 v[192:193], v[192:193], v[192:193]
	v_pk_mul_f32 v[194:195], v[194:195], v[194:195]
	v_add_f32_e32 v170, v193, v192
	v_add_f32_e32 v170, v194, v170
	v_add_f32_e32 v170, v195, v170
	v_add_f32_e32 v164, v164, v170
	s_waitcnt vmcnt(16)
	v_lshlrev_b32_e32 v168, 16, v162
	v_and_b32_e32 v169, 0xffff0000, v162
	v_lshlrev_b32_e32 v170, 16, v163
	v_and_b32_e32 v171, 0xffff0000, v163
	v_pk_add_f32 v[192:193], v[2:3], v[168:169]
	v_pk_add_f32 v[194:195], v[4:5], v[170:171]
	v_cvt_pk_bf16_f32 v168, v192, v193
	v_cvt_pk_bf16_f32 v169, v194, v195
	global_store_dwordx2 v243, v[168:169], s[56:57] offset:224
	v_pk_mul_f32 v[192:193], v[192:193], v[192:193]
	v_pk_mul_f32 v[194:195], v[194:195], v[194:195]
	v_add_f32_e32 v170, v193, v192
	v_add_f32_e32 v170, v194, v170
	v_add_f32_e32 v170, v195, v170
	v_add_f32_e32 v164, v164, v170
	v_xor_b32_e32 v168, 16, v207
	v_lshlrev_b32_e32 v168, 2, v168
	ds_bpermute_b32 v169, v168, v164
	v_xor_b32_e32 v168, 32, v207
	v_lshlrev_b32_e32 v168, 2, v168
	s_waitcnt lgkmcnt(0)
	v_add_f32_e32 v164, v164, v169
	ds_bpermute_b32 v169, v168, v164
	v_add_u32_e32 v170, 48, v130
	v_lshlrev_b32_e32 v170, 2, v170
	v_and_b32_e32 v171, 63, v207
	v_cmp_gt_u32_e32 vcc, 16, v171
	s_waitcnt lgkmcnt(0)
	v_add_f32_e32 v164, v164, v169
	s_and_saveexec_b64 s[2:3], vcc
	global_atomic_add_f32 v170, v164, s[8:9]
	s_or_b64 exec, exec, s[2:3]
	s_branch .Lresid_next_outproj

; template <int MI, int NI>
; DI void gemm_kloop(const u16* Au, int lda, const u16* Bu, int ldb, int K, f32x4 (&acc)[NI][MI], unsigned char* smem) {
;     ...
;   GLOAD(0);
;   SWRITE(0);
;   if (nk > 1) GLOAD(64);
; template <int MI>
; DI void merge_tile(const Params& p, int layer, int rowbase, int nt, unsigned char* smem) {
;     ...
;     gemm_kloop<MI, 4>(Y + (size_t)rowbase * Kb, Kb, Wb + (size_t)(nt * 128) * Kb, Kb, Kb, acc, smem);
;     u32 brp[4][MI][2];
; #pragma unroll
;     for (int ni = 0; ni < 4; ++ni)
; #pragma unroll
;       for (int mi = 0; mi < MI; ++mi) {
;         brp[ni][mi][0] = pack2bf(acc[ni][mi][0], acc[ni][mi][1]);
;         brp[ni][mi][1] = pack2bf(acc[ni][mi][2], acc[ni][mi][3]);
;       }
;     zero_acc<MI, 4>(acc);
;     gemm_kloop<MI, 4>(p.hb + (size_t)rowbase * DM, DM, WL + OFF_WG + (size_t)(br * 1024 + nt * 128) * DM, DM, DM, acc, smem);
.LBB0_285:
	v_add_u32_e32 v95, s69, v98
	v_add_u32_e32 v90, v95, v97
	s_barrier
	s_waitcnt vmcnt(4)
	ds_read_b128 v[2:5], v90 offset:32768
	v_add_u32_e32 v91, s69, v96
	v_add_u32_e32 v92, v91, v97
	ds_read_b128 v[6:9], v92
	s_waitcnt vmcnt(2)
	ds_read_b128 v[10:13], v92 offset:2048
	s_waitcnt vmcnt(0)
	ds_read_b128 v[14:17], v90 offset:34816
	s_waitcnt lgkmcnt(0)
	v_mfma_f32_16x16x32_bf16 v[70:73], v[14:17], v[6:9], v[70:73]
	v_add_u32_e32 v100, v91, v94
	v_add_u32_e32 v94, v95, v94
	v_mov_b32_e32 v155, v166
	v_mfma_f32_16x16x32_bf16 v[18:21], v[2:5], v[6:9], v[86:89]
	s_lshl_b32 s10, s66, 10
	s_add_i32 s28, s10, s44
	s_ashr_i32 s55, s54, 31
	v_mfma_f32_16x16x32_bf16 v[22:25], v[2:5], v[10:13], v[82:85]
	s_nop 2
	ds_read_b128 v[82:85], v92 offset:4096
	ds_read_b128 v[86:89], v92 offset:6144
	s_ashr_i32 s29, s28, 31
	s_lshl_b64 s[2:3], s[54:55], 11
	s_waitcnt lgkmcnt(1)
	v_mfma_f32_16x16x32_bf16 v[78:81], v[2:5], v[82:85], v[78:81]
	s_lshl_b64 s[28:29], s[28:29], 11
	s_add_u32 s28, s60, s28
	s_addc_u32 s29, s61, s29
	s_waitcnt lgkmcnt(0)
	v_mfma_f32_16x16x32_bf16 v[74:77], v[2:5], v[86:89], v[74:77]
	ds_read_b128 v[2:5], v90 offset:36864
	s_add_u32 s2, s23, s2
	s_addc_u32 s3, s21, s3
	v_mfma_f32_16x16x32_bf16 v[66:69], v[14:17], v[10:13], v[66:69]
	v_mfma_f32_16x16x32_bf16 v[62:65], v[14:17], v[82:85], v[62:65]
	v_mfma_f32_16x16x32_bf16 v[14:17], v[14:17], v[86:89], v[58:61]
	s_nop 2
	ds_read_b128 v[58:61], v90 offset:38912
	s_waitcnt lgkmcnt(1)
	v_mfma_f32_16x16x32_bf16 v[90:93], v[2:5], v[6:9], v[54:57]
	ds_read_b128 v[96:99], v100
	ds_read_b128 v[110:113], v100 offset:2048
	ds_read_b128 v[122:125], v100 offset:4096
	ds_read_b128 v[126:129], v100 offset:6144
	ds_read_b128 v[54:57], v94 offset:32768
	ds_read_b128 v[100:103], v94 offset:34816
	ds_read_b128 v[114:117], v94 offset:36864
	ds_read_b128 v[192:195], v94 offset:38912
	v_mfma_f32_16x16x32_bf16 v[50:53], v[2:5], v[10:13], v[50:53]
	s_waitcnt lgkmcnt(0)
	s_barrier
	s_mov_b64 s[24:25], s[46:47]
	s_mov_b64 s[26:27], s[28:29]
	v_lshlrev_b32_e32 v255, 4, v166
	v_xor_b32_e32 v255, v255, v166
	v_and_b32_e32 v255, 0x70, v255
	v_lshrrev_b32_e32 v254, 3, v166
	v_lshl_or_b32 v255, v254, 11, v255
	v_lshrrev_b32_e32 v254, 6, v166
	s_nop 0
	v_readfirstlane_b32 s19, v254
	s_nop 3
	s_lshl_b32 s19, s19, 10
	s_mov_b32 m0, s19
	s_nop 0
	global_load_lds_dwordx4 v255, s[24:25]
	s_add_u32 m0, m0, 0x2000
	s_add_u32 s38, s24, 0x20000
	s_addc_u32 s39, s25, 0
	global_load_lds_dwordx4 v255, s[38:39]
	s_add_u32 m0, m0, 0x2000
	s_add_u32 s38, s24, 0x40000
	s_addc_u32 s39, s25, 0
	global_load_lds_dwordx4 v255, s[38:39]
	s_add_u32 m0, m0, 0x2000
	s_add_u32 s38, s24, 0x60000
	s_addc_u32 s39, s25, 0
	global_load_lds_dwordx4 v255, s[38:39]
	s_add_u32 m0, m0, 0x2000
	s_nop 0
	global_load_lds_dwordx4 v255, s[26:27]
	s_add_u32 m0, m0, 0x2000
	s_add_u32 s38, s26, 0x20000
	s_addc_u32 s39, s27, 0
	global_load_lds_dwordx4 v255, s[38:39]
	s_add_u32 s24, s24, 0x80
	s_addc_u32 s25, s25, 0
	s_add_u32 s26, s26, 0x80
	s_addc_u32 s27, s27, 0
	v_mfma_f32_16x16x32_bf16 v[104:107], v[2:5], v[82:85], v[46:49]
	s_nop 0
	v_ashrrev_i32_e32 v130, 3, v155
	v_mfma_f32_16x16x32_bf16 v[38:41], v[2:5], v[86:89], v[38:41]
	v_lshlrev_b32_e32 v2, 3, v155
	v_and_b32_e32 v2, 56, v2
	v_and_b32_e32 v157, 15, v155
	v_mfma_f32_16x16x32_bf16 v[6:9], v[58:61], v[6:9], v[34:37]
	v_bfe_u32 v225, v155, 1, 3
	v_mfma_f32_16x16x32_bf16 v[34:37], v[58:61], v[10:13], v[30:33]
	v_lshl_or_b32 v10, v130, 10, v2
	v_ashrrev_i32_e32 v11, 31, v10
	v_lshlrev_b64 v[94:95], 1, v[10:11]
	v_lshl_add_u64 v[108:109], s[46:47], 0, v[94:95]
	v_mfma_f32_16x16x32_bf16 v[10:13], v[54:57], v[110:113], v[22:25]
	v_lshl_add_u64 v[118:119], s[28:29], 0, v[94:95]
	s_mov_b32 s28, 0
	s_nop 0
	v_add_co_u32_e32 v22, vcc, s33, v108
	v_mfma_f32_16x16x32_bf16 v[26:29], v[58:61], v[82:85], v[26:29]
	s_nop 0
	v_addc_co_u32_e32 v23, vcc, 0, v109, vcc
	v_add_co_u32_e32 v30, vcc, s36, v108
	v_mfma_f32_16x16x32_bf16 v[42:45], v[58:61], v[86:89], v[42:45]
	s_nop 0
	v_addc_co_u32_e32 v31, vcc, 0, v109, vcc
	s_nop 0
	v_mfma_f32_16x16x32_bf16 v[2:5], v[54:57], v[96:99], v[18:21]
	s_nop 0
	s_nop 0
	s_nop 0
	v_mfma_f32_16x16x32_bf16 v[18:21], v[54:57], v[122:125], v[78:81]
	v_mfma_f32_16x16x32_bf16 v[30:33], v[54:57], v[126:129], v[74:77]
	v_add_co_u32_e32 v54, vcc, s37, v108
	s_nop 1
	v_addc_co_u32_e32 v55, vcc, 0, v109, vcc
	v_add_co_u32_e32 v120, vcc, s33, v118
	v_mfma_f32_16x16x32_bf16 v[46:49], v[100:103], v[96:99], v[70:73]
	s_nop 0
	v_addc_co_u32_e32 v121, vcc, 0, v119, vcc
	s_nop 0
	s_nop 0
	v_mfma_f32_16x16x32_bf16 v[78:81], v[100:103], v[126:129], v[14:17]
	s_nop 2
	v_lshlrev_b32_e32 v17, 7, v130
	s_nop 0
	v_mfma_f32_16x16x32_bf16 v[54:57], v[100:103], v[110:113], v[66:69]
	v_lshlrev_b32_e32 v16, 4, v155
	v_xor_b32_e32 v16, v16, v155
	v_and_or_b32 v237, v16, s12, v17
	v_mfma_f32_16x16x32_bf16 v[66:69], v[100:103], v[122:125], v[62:65]
	v_lshrrev_b32_e32 v14, 4, v155
	v_bfe_u32 v15, v155, 4, 2
	s_nop 0
	v_mfma_f32_16x16x32_bf16 v[86:89], v[114:117], v[96:99], v[90:93]
	v_mfma_f32_16x16x32_bf16 v[90:93], v[114:117], v[110:113], v[50:53]
	s_nop 0
	s_nop 0
	v_mfma_f32_16x16x32_bf16 v[102:105], v[114:117], v[122:125], v[104:107]
	v_mfma_f32_16x16x32_bf16 v[106:109], v[114:117], v[126:129], v[38:41]
	v_mfma_f32_16x16x32_bf16 v[114:117], v[192:195], v[96:99], v[6:9]
	s_nop 2
	v_lshl_add_u64 v[6:7], s[48:49], 0, v[94:95]
	v_lshl_add_u64 v[8:9], s[50:51], 0, v[94:95]
	s_nop 0
	s_nop 0
	v_lshl_add_u64 v[6:7], s[52:53], 0, v[94:95]
	s_nop 0
	v_lshlrev_b32_e32 v7, 6, v155
	v_mfma_f32_16x16x32_bf16 v[118:121], v[192:195], v[110:113], v[34:37]
	v_and_b32_e32 v234, 0xffffe000, v7
	v_lshlrev_b32_e32 v7, 7, v155
; DI f32x4 mfma16(bf16x8 a, bf16x8 b, f32x4 c) { return __builtin_amdgcn_mfma_f32_16x16x32_bf16(a, b, c, 0, 0, 0); }
; template <int MI, int NI>
; DI void gemm_kloop(const u16* Au, int lda, const u16* Bu, int ldb, int K, f32x4 (&acc)[NI][MI], unsigned char* smem) {
;     ...
;   for (int kt = 0; kt < nk; ++kt) {
;     __syncthreads();
;     if (kt + 1 < nk) {
;       SWRITE((kt + 1) & 1);
;       if (kt + 2 < nk) GLOAD((kt + 2) << 6);
;     }
;     {
;       const unsigned char* sa = smem + (kt & 1) * 65536;
;       const unsigned char* sb = sa + 32768;
; #pragma unroll
;       for (int ks = 0; ks < 2; ++ks) {
;         const int fo = ks ? fro1 : fro0;
;         bf16x8 af[MI];
; #pragma unroll
;         for (int i = 0; i < MI; ++i) af[i] = *(const bf16x8*)(sa + (wm * 16 * MI + i * 16) * 128 + fo);
; #pragma unroll
;         for (int nh = 0; nh < NI; nh += 4) {
;           bf16x8 wf[4];
; #pragma unroll
;           for (int i = 0; i < 4; ++i) wf[i] = *(const bf16x8*)(sb + (wn * 16 * NI + (nh + i) * 16) * 128 + fo);
; #pragma unroll
;           for (int ni = 0; ni < 4; ++ni)
; #pragma unroll
;             for (int mi = 0; mi < MI; ++mi) acc[nh + ni][mi] = mfma16(wf[ni], af[mi], acc[nh + ni][mi]);
;         }
; template <int MI, int NI>
; DI void zero_acc(f32x4 (&acc)[NI][MI]) {
;     ...
;     for (int j = 0; j < MI; ++j) acc[i][j] = f32x4{0.f, 0.f, 0.f, 0.f};
	v_lshlrev_b32_e32 v6, 7, v157
	v_mfma_f32_16x16x32_bf16 v[122:125], v[192:195], v[122:125], v[26:29]
	v_and_b32_e32 v235, 0x2000, v7
	v_bitop3_b32 v7, v14, v225, 3 bitop3:0x6c
	v_lshl_or_b32 v233, v7, 4, v6
	v_mfma_f32_16x16x32_bf16 v[126:129], v[192:195], v[126:129], v[42:45]
	v_bitop3_b32 v7, v15, v225, 4 bitop3:0x36
	v_mov_b32_e32 v110, 0
	v_lshl_or_b32 v232, v7, 4, v6
	v_lshl_add_u64 v[192:193], s[2:3], 0, v[94:95]
	v_lshl_add_u64 v[194:195], s[56:57], 0, v[94:95]
	s_mov_b64 s[2:3], 0
	v_mov_b32_e32 v111, v110
	v_mov_b32_e32 v112, v110
	v_mov_b32_e32 v113, v110
	v_mov_b32_e32 v34, v110
	v_mov_b32_e32 v35, v110
	v_mov_b32_e32 v36, v110
	v_mov_b32_e32 v37, v110
	v_mov_b32_e32 v62, v110
	v_mov_b32_e32 v63, v110
	v_mov_b32_e32 v64, v110
	v_mov_b32_e32 v65, v110
	v_mov_b32_e32 v70, v110
	v_mov_b32_e32 v71, v110
	v_mov_b32_e32 v72, v110
	v_mov_b32_e32 v73, v110
	v_mov_b32_e32 v22, v110
	v_mov_b32_e32 v23, v110
	v_mov_b32_e32 v24, v110
	v_mov_b32_e32 v25, v110
	v_mov_b32_e32 v6, v110
	v_mov_b32_e32 v7, v110
	v_mov_b32_e32 v8, v110
	v_mov_b32_e32 v9, v110
	v_mov_b32_e32 v14, v110
	v_mov_b32_e32 v15, v110
	v_mov_b32_e32 v16, v110
	v_mov_b32_e32 v17, v110
	v_mov_b32_e32 v26, v110
	v_mov_b32_e32 v27, v110
	v_mov_b32_e32 v28, v110
	v_mov_b32_e32 v29, v110
	v_mov_b32_e32 v38, v110
	v_mov_b32_e32 v39, v110
	v_mov_b32_e32 v40, v110
	v_mov_b32_e32 v41, v110
	v_mov_b32_e32 v42, v110
	v_mov_b32_e32 v43, v110
	v_mov_b32_e32 v44, v110
	v_mov_b32_e32 v45, v110
	v_mov_b32_e32 v50, v110
	v_mov_b32_e32 v51, v110
	v_mov_b32_e32 v52, v110
	v_mov_b32_e32 v53, v110
	v_mov_b32_e32 v58, v110
	v_mov_b32_e32 v59, v110
	v_mov_b32_e32 v60, v110
	v_mov_b32_e32 v61, v110
	v_mov_b32_e32 v74, v110
	v_mov_b32_e32 v75, v110
	v_mov_b32_e32 v76, v110
	v_mov_b32_e32 v77, v110
	v_mov_b32_e32 v82, v110
	v_mov_b32_e32 v83, v110
	v_mov_b32_e32 v84, v110
	v_mov_b32_e32 v85, v110
	v_mov_b32_e32 v94, v110
	v_mov_b32_e32 v95, v110
	v_mov_b32_e32 v96, v110
	v_mov_b32_e32 v97, v110
	v_mov_b32_e32 v98, v110
	v_mov_b32_e32 v99, v110
	v_mov_b32_e32 v100, v110
	v_mov_b32_e32 v101, v110
	v_and_b32_e32 v231, 15, v166
	v_bfe_u32 v242, v166, 4, 2
	v_lshrrev_b32_e32 v243, 1, v231
	v_xor_b32_e32 v155, v242, v243
	v_or_b32_e32 v242, 4, v242
	v_xor_b32_e32 v157, v242, v243
	v_lshlrev_b32_e32 v231, 7, v231
	v_lshl_or_b32 v155, v155, 4, v231
	v_lshl_or_b32 v157, v157, 4, v231
	v_lshrrev_b32_e32 v231, 7, v166
	v_bfe_u32 v242, v166, 6, 1
	v_mul_u32_u24_e32 v242, 0x2000, v242
	v_add_u32_e32 v225, v242, v155
	v_add_u32_e32 v230, v242, v157
	v_mul_u32_u24_e32 v231, 0x2000, v231
	v_add_u32_e32 v155, v231, v155
	v_add_u32_e32 v157, v231, v157
	s_mov_b32 s32, 0
.Lk_mgate:
	s_waitcnt vmcnt(0) lgkmcnt(0)
	s_barrier
	ds_read_b128 v[130:133], v225 offset:32768
	ds_read_b128 v[150:153], v155
	ds_read_b128 v[134:137], v225 offset:34816
	ds_read_b128 v[138:141], v225 offset:36864
	ds_read_b128 v[142:145], v225 offset:38912
	ds_read_b128 v[226:229], v155 offset:2048
	ds_read_b128 v[238:241], v155 offset:4096
	s_and_b32 s38, s32, 1
	s_xor_b32 s38, s38, 1
	s_lshl_b32 s38, s38, 16
	s_waitcnt lgkmcnt(5)
	v_mfma_f32_16x16x32_bf16 v[98:101], v[130:133], v[150:153], v[98:101]
	ds_read_b128 v[248:251], v155 offset:6144
	s_waitcnt lgkmcnt(5)
	v_mfma_f32_16x16x32_bf16 v[58:61], v[134:137], v[150:153], v[58:61]
	s_waitcnt lgkmcnt(4)
	v_mfma_f32_16x16x32_bf16 v[26:29], v[138:141], v[150:153], v[26:29]
	s_add_u32 m0, s38, s19
	s_nop 0
	global_load_lds_dwordx4 v255, s[24:25]
	s_waitcnt lgkmcnt(3)
	v_mfma_f32_16x16x32_bf16 v[70:73], v[142:145], v[150:153], v[70:73]
	s_waitcnt lgkmcnt(2)
	v_mfma_f32_16x16x32_bf16 v[94:97], v[130:133], v[226:229], v[94:97]
	ds_read_b128 v[150:153], v157
	v_mfma_f32_16x16x32_bf16 v[50:53], v[134:137], v[226:229], v[50:53]
	v_mfma_f32_16x16x32_bf16 v[14:17], v[138:141], v[226:229], v[14:17]
	s_add_u32 m0, m0, 0x2000
	s_add_u32 s38, s24, 0x20000
	s_addc_u32 s39, s25, 0
	global_load_lds_dwordx4 v255, s[38:39]
	v_mfma_f32_16x16x32_bf16 v[62:65], v[142:145], v[226:229], v[62:65]
	s_waitcnt lgkmcnt(2)
	v_mfma_f32_16x16x32_bf16 v[82:85], v[130:133], v[238:241], v[82:85]
	ds_read_b128 v[226:229], v157 offset:2048
	v_mfma_f32_16x16x32_bf16 v[42:45], v[134:137], v[238:241], v[42:45]
	ds_read_b128 v[146:149], v230 offset:32768
	v_mfma_f32_16x16x32_bf16 v[6:9], v[138:141], v[238:241], v[6:9]
	s_add_u32 m0, m0, 0x2000
	s_add_u32 s38, s24, 0x40000
	s_addc_u32 s39, s25, 0
	global_load_lds_dwordx4 v255, s[38:39]
	v_mfma_f32_16x16x32_bf16 v[34:37], v[142:145], v[238:241], v[34:37]
	s_waitcnt lgkmcnt(3)
	v_mfma_f32_16x16x32_bf16 v[74:77], v[130:133], v[248:251], v[74:77]
	ds_read_b128 v[238:241], v157 offset:4096
	v_mfma_f32_16x16x32_bf16 v[38:41], v[134:137], v[248:251], v[38:41]
	ds_read_b128 v[134:137], v230 offset:34816
	v_mfma_f32_16x16x32_bf16 v[22:25], v[138:141], v[248:251], v[22:25]
	ds_read_b128 v[138:141], v230 offset:36864
	s_add_u32 m0, m0, 0x2000
	s_add_u32 s38, s24, 0x60000
	s_addc_u32 s39, s25, 0
	global_load_lds_dwordx4 v255, s[38:39]
	v_mfma_f32_16x16x32_bf16 v[110:113], v[142:145], v[248:251], v[110:113]
	ds_read_b128 v[142:145], v230 offset:38912
	s_waitcnt lgkmcnt(4)
	v_mfma_f32_16x16x32_bf16 v[98:101], v[146:149], v[150:153], v[98:101]
	ds_read_b128 v[248:251], v157 offset:6144
	s_waitcnt lgkmcnt(3)
	v_mfma_f32_16x16x32_bf16 v[58:61], v[134:137], v[150:153], v[58:61]
	s_waitcnt lgkmcnt(2)
	v_mfma_f32_16x16x32_bf16 v[26:29], v[138:141], v[150:153], v[26:29]
	s_add_u32 m0, m0, 0x2000
	s_nop 0
	global_load_lds_dwordx4 v255, s[26:27]
	s_waitcnt lgkmcnt(1)
	v_mfma_f32_16x16x32_bf16 v[70:73], v[142:145], v[150:153], v[70:73]
	v_mfma_f32_16x16x32_bf16 v[94:97], v[146:149], v[226:229], v[94:97]
	v_mfma_f32_16x16x32_bf16 v[50:53], v[134:137], v[226:229], v[50:53]
	v_mfma_f32_16x16x32_bf16 v[14:17], v[138:141], v[226:229], v[14:17]
	s_add_u32 m0, m0, 0x2000
	s_add_u32 s38, s26, 0x20000
	s_addc_u32 s39, s27, 0
	global_load_lds_dwordx4 v255, s[38:39]
	v_mfma_f32_16x16x32_bf16 v[62:65], v[142:145], v[226:229], v[62:65]
	v_mfma_f32_16x16x32_bf16 v[82:85], v[146:149], v[238:241], v[82:85]
	v_mfma_f32_16x16x32_bf16 v[42:45], v[134:137], v[238:241], v[42:45]
	v_mfma_f32_16x16x32_bf16 v[6:9], v[138:141], v[238:241], v[6:9]
	v_mfma_f32_16x16x32_bf16 v[34:37], v[142:145], v[238:241], v[34:37]
	s_waitcnt lgkmcnt(0)
	v_mfma_f32_16x16x32_bf16 v[74:77], v[146:149], v[248:251], v[74:77]
	v_mfma_f32_16x16x32_bf16 v[38:41], v[134:137], v[248:251], v[38:41]
	v_mfma_f32_16x16x32_bf16 v[22:25], v[138:141], v[248:251], v[22:25]
	v_mfma_f32_16x16x32_bf16 v[110:113], v[142:145], v[248:251], v[110:113]
	v_xor_b32_e32 v155, 0x10000, v155
	v_xor_b32_e32 v157, 0x10000, v157
	v_xor_b32_e32 v225, 0x10000, v225
	v_xor_b32_e32 v230, 0x10000, v230
	s_add_u32 s24, s24, 0x80
	s_addc_u32 s25, s25, 0
	s_add_u32 s26, s26, 0x80
	s_addc_u32 s27, s27, 0
	s_add_u32 s32, s32, 1
	s_cmp_lg_u32 s32, 14
	s_cbranch_scc1 .Lk_mgate
; DI f32x4 mfma16(bf16x8 a, bf16x8 b, f32x4 c) { return __builtin_amdgcn_mfma_f32_16x16x32_bf16(a, b, c, 0, 0, 0); }
; template <int MI, int NI>
; DI void gemm_kloop(const u16* Au, int lda, const u16* Bu, int ldb, int K, f32x4 (&acc)[NI][MI], unsigned char* smem) {
;     ...
;   for (int kt = 0; kt < nk; ++kt) {
;     __syncthreads();
;     if (kt + 1 < nk) {
;       SWRITE((kt + 1) & 1);
;       if (kt + 2 < nk) GLOAD((kt + 2) << 6);
;     }
;     {
;       const unsigned char* sa = smem + (kt & 1) * 65536;
;       const unsigned char* sb = sa + 32768;
; #pragma unroll
;       for (int ks = 0; ks < 2; ++ks) {
;         const int fo = ks ? fro1 : fro0;
;         bf16x8 af[MI];
; #pragma unroll
;         for (int i = 0; i < MI; ++i) af[i] = *(const bf16x8*)(sa + (wm * 16 * MI + i * 16) * 128 + fo);
; #pragma unroll
;         for (int nh = 0; nh < NI; nh += 4) {
;           bf16x8 wf[4];
; #pragma unroll
;           for (int i = 0; i < 4; ++i) wf[i] = *(const bf16x8*)(sb + (wn * 16 * NI + (nh + i) * 16) * 128 + fo);
; #pragma unroll
;           for (int ni = 0; ni < 4; ++ni)
; #pragma unroll
;             for (int mi = 0; mi < MI; ++mi) acc[nh + ni][mi] = mfma16(wf[ni], af[mi], acc[nh + ni][mi]);
;         }
;       }
;     }
;   }
; template <int MI>
; DI void merge_tile(const Params& p, int layer, int rowbase, int nt, unsigned char* smem) {
;     ...
;         brp[ni][mi][0] = pack2bf(acc[ni][mi][0], acc[ni][mi][1]);
;         brp[ni][mi][1] = pack2bf(acc[ni][mi][2], acc[ni][mi][3]);
	v_cvt_pk_bf16_f32 v242, v2, v3
	s_waitcnt vmcnt(0)
	s_barrier
	s_add_u32 m0, s19, 0x10000
	s_nop 0
	global_load_lds_dwordx4 v255, s[24:25]
	s_add_u32 m0, m0, 0x2000
	s_add_u32 s38, s24, 0x20000
	s_addc_u32 s39, s25, 0
	global_load_lds_dwordx4 v255, s[38:39]
	s_add_u32 m0, m0, 0x2000
	s_add_u32 s38, s24, 0x40000
	s_addc_u32 s39, s25, 0
	global_load_lds_dwordx4 v255, s[38:39]
	s_add_u32 m0, m0, 0x2000
	s_add_u32 s38, s24, 0x60000
	s_addc_u32 s39, s25, 0
	global_load_lds_dwordx4 v255, s[38:39]
	s_add_u32 m0, m0, 0x2000
	s_nop 0
	global_load_lds_dwordx4 v255, s[26:27]
	s_add_u32 m0, m0, 0x2000
	s_add_u32 s38, s26, 0x20000
	s_addc_u32 s39, s27, 0
	global_load_lds_dwordx4 v255, s[38:39]
	s_mov_b32 s24, 0x58000
	s_mov_b32 s25, 0xefa18f08
	s_mov_b32 s26, 0x3f317217
	s_mov_b32 s27, 0x7f800000
	s_mov_b32 s38, 0x3e38aa3b
	s_brev_b32 s39, 1
	v_cvt_pk_bf16_f32 v193, v30, v31
	v_add_u32_e32 v30, v234, v233
	v_cvt_pk_bf16_f32 v241, v4, v5
	v_cvt_pk_bf16_f32 v231, v10, v11
	v_cvt_pk_bf16_f32 v230, v12, v13
	v_cvt_pk_bf16_f32 v226, v18, v19
	v_cvt_pk_bf16_f32 v225, v20, v21
	v_cvt_pk_bf16_f32 v192, v32, v33
	v_cvt_pk_bf16_f32 v236, v88, v89
	v_cvt_pk_bf16_f32 v89, v102, v103
	ds_read_b128 v[2:5], v30
	ds_read_b128 v[10:13], v30 offset:2048
	ds_read_b128 v[18:21], v30 offset:4096
	ds_read_b128 v[30:33], v30 offset:6144
	v_add_u32_e32 v103, v235, v233
	v_cvt_pk_bf16_f32 v240, v46, v47
	v_cvt_pk_bf16_f32 v239, v48, v49
	v_cvt_pk_bf16_f32 v229, v54, v55
	v_cvt_pk_bf16_f32 v228, v56, v57
	v_cvt_pk_bf16_f32 v195, v66, v67
	v_cvt_pk_bf16_f32 v194, v68, v69
	v_cvt_pk_bf16_f32 v155, v80, v81
	v_cvt_pk_bf16_f32 v88, v104, v105
	v_cvt_pk_bf16_f32 v81, v106, v107
	ds_read_b128 v[46:49], v103 offset:32768
	ds_read_b128 v[54:57], v103 offset:34816
	ds_read_b128 v[66:69], v103 offset:36864
	ds_read_b128 v[104:107], v103 offset:38912
	s_waitcnt lgkmcnt(1)
	v_mfma_f32_16x16x32_bf16 v[26:29], v[66:69], v[2:5], v[26:29]
	v_add_u32_e32 v103, v235, v232
	v_cvt_pk_bf16_f32 v80, v108, v109
	v_cvt_pk_bf16_f32 v238, v86, v87
	v_mfma_f32_16x16x32_bf16 v[14:17], v[66:69], v[10:13], v[14:17]
	v_cvt_pk_bf16_f32 v86, v124, v125
	v_or_b32_e32 v124, 0x18000, v235
	v_cvt_pk_bf16_f32 v227, v90, v91
	v_mfma_f32_16x16x32_bf16 v[6:9], v[66:69], v[18:21], v[6:9]
	v_cvt_pk_bf16_f32 v92, v92, v93
	v_cvt_pk_bf16_f32 v102, v114, v115
	v_cvt_pk_bf16_f32 v93, v116, v117
	v_mfma_f32_16x16x32_bf16 v[22:25], v[66:69], v[30:33], v[22:25]
	v_add_u32_e32 v66, v234, v232
	v_cvt_pk_bf16_f32 v91, v118, v119
	v_cvt_pk_bf16_f32 v90, v120, v121
	v_mfma_f32_16x16x32_bf16 v[98:101], v[46:49], v[2:5], v[98:101]
	v_cvt_pk_bf16_f32 v87, v122, v123
	v_cvt_pk_bf16_f32 v157, v78, v79
	v_cvt_pk_bf16_f32 v79, v126, v127
	v_mfma_f32_16x16x32_bf16 v[94:97], v[46:49], v[10:13], v[94:97]
	v_cvt_pk_bf16_f32 v78, v128, v129
	s_lshl_b64 s[2:3], s[10:11], 2
	s_add_u32 s2, s9, s2
	v_mfma_f32_16x16x32_bf16 v[82:85], v[46:49], v[18:21], v[82:85]
	s_addc_u32 s3, s59, s3
	s_add_i32 s66, s66, 1
	s_addk_i32 s54, 0x400
	v_mfma_f32_16x16x32_bf16 v[46:49], v[46:49], v[30:33], v[74:77]
	s_cmp_eq_u32 s66, 3
	v_mfma_f32_16x16x32_bf16 v[58:61], v[54:57], v[2:5], v[58:61]
	v_mfma_f32_16x16x32_bf16 v[50:53], v[54:57], v[10:13], v[50:53]
	v_mfma_f32_16x16x32_bf16 v[42:45], v[54:57], v[18:21], v[42:45]
	v_mfma_f32_16x16x32_bf16 v[38:41], v[54:57], v[30:33], v[38:41]
	s_waitcnt lgkmcnt(0)
	v_mfma_f32_16x16x32_bf16 v[2:5], v[104:107], v[2:5], v[70:73]
	v_mfma_f32_16x16x32_bf16 v[10:13], v[104:107], v[10:13], v[62:65]
	v_mfma_f32_16x16x32_bf16 v[18:21], v[104:107], v[18:21], v[34:37]
	s_nop 2
	ds_read_b128 v[34:37], v66
	ds_read_b128 v[54:57], v66 offset:2048
	ds_read_b128 v[62:65], v66 offset:4096
	ds_read_b128 v[66:69], v66 offset:6144
	v_mfma_f32_16x16x32_bf16 v[30:33], v[104:107], v[30:33], v[110:113]
	ds_read_b128 v[70:73], v103 offset:32768
	ds_read_b128 v[74:77], v103 offset:34816
	ds_read_b128 v[104:107], v103 offset:36864
	ds_read_b128 v[108:111], v103 offset:38912
	v_add_u32_e32 v103, 0x10000, v234
	s_waitcnt lgkmcnt(0)
	v_mfma_f32_16x16x32_bf16 v[46:49], v[70:73], v[66:69], v[46:49]
	s_waitcnt vmcnt(0)
	s_barrier
	v_mfma_f32_16x16x32_bf16 v[38:41], v[74:77], v[66:69], v[38:41]
	v_mfma_f32_16x16x32_bf16 v[22:25], v[104:107], v[66:69], v[22:25]
	v_mfma_f32_16x16x32_bf16 v[2:5], v[108:111], v[34:37], v[2:5]
	v_mfma_f32_16x16x32_bf16 v[10:13], v[108:111], v[54:57], v[10:13]
	v_mfma_f32_16x16x32_bf16 v[18:21], v[108:111], v[62:65], v[18:21]
	v_mfma_f32_16x16x32_bf16 v[30:33], v[108:111], v[66:69], v[30:33]
	v_add_u32_e32 v66, v103, v233
	v_add_u32_e32 v108, v124, v233
	v_mfma_f32_16x16x32_bf16 v[98:101], v[70:73], v[34:37], v[98:101]
	v_mfma_f32_16x16x32_bf16 v[94:97], v[70:73], v[54:57], v[94:97]
	v_mfma_f32_16x16x32_bf16 v[82:85], v[70:73], v[62:65], v[82:85]
	v_mfma_f32_16x16x32_bf16 v[58:61], v[74:77], v[34:37], v[58:61]
	v_mfma_f32_16x16x32_bf16 v[50:53], v[74:77], v[54:57], v[50:53]
	v_mfma_f32_16x16x32_bf16 v[42:45], v[74:77], v[62:65], v[42:45]
	v_mfma_f32_16x16x32_bf16 v[26:29], v[104:107], v[34:37], v[26:29]
	v_mfma_f32_16x16x32_bf16 v[14:17], v[104:107], v[54:57], v[14:17]
	v_mfma_f32_16x16x32_bf16 v[6:9], v[104:107], v[62:65], v[6:9]
	ds_read_b128 v[34:37], v66
	ds_read_b128 v[54:57], v66 offset:2048
	ds_read_b128 v[62:65], v66 offset:4096
	ds_read_b128 v[66:69], v66 offset:6144
	ds_read_b128 v[70:73], v108
	ds_read_b128 v[74:77], v108 offset:2048
	ds_read_b128 v[104:107], v108 offset:4096
	ds_read_b128 v[108:111], v108 offset:6144
	s_waitcnt lgkmcnt(3)
	v_mfma_f32_16x16x32_bf16 v[98:101], v[70:73], v[34:37], v[98:101]
	s_waitcnt lgkmcnt(2)
	v_mfma_f32_16x16x32_bf16 v[58:61], v[74:77], v[34:37], v[58:61]
	s_waitcnt lgkmcnt(1)
; DI f32x4 mfma16(bf16x8 a, bf16x8 b, f32x4 c) { return __builtin_amdgcn_mfma_f32_16x16x32_bf16(a, b, c, 0, 0, 0); }
; template <int MI, int NI>
; DI void gemm_kloop(const u16* Au, int lda, const u16* Bu, int ldb, int K, f32x4 (&acc)[NI][MI], unsigned char* smem) {
;     ...
;           for (int ni = 0; ni < 4; ++ni)
; #pragma unroll
;             for (int mi = 0; mi < MI; ++mi) acc[nh + ni][mi] = mfma16(wf[ni], af[mi], acc[nh + ni][mi]);
; template <int MI>
; DI void merge_tile(const Params& p, int layer, int rowbase, int nt, unsigned char* smem) {
;     ...
; #pragma unroll
;     for (int mi = 0; mi < MI; ++mi) {
;       const float rs = rsqrtf(rowss[m0 + mi * 16] * (1.f / DM) + EPS);
; #pragma unroll
;       for (int ni = 0; ni < 4; ++ni) {
;         const float4 b4 = *(const float4*)(bg + br * DM + n0 + ni * 16);
;         const float bb[4] = {b4.x, b4.y, b4.z, b4.w};
;         float mv[4];
; #pragma unroll
;         for (int r = 0; r < 4; ++r) {
;           const float gv = acc[ni][mi][r] * rs + bb[r];
;           const float sg = 1.f / (1.f + __expf(-gv));
;           const u32 w = brp[ni][mi][r >> 1], mw = mp[ni][mi][r >> 1];
;           const float bv = __uint_as_float((r & 1) ? (w & 0xffff0000u) : (w << 16));
;           const float mo = __uint_as_float((r & 1) ? (mw & 0xffff0000u) : (mw << 16));
;           mv[r] = mo + sg * bv;
;         }
;         mp[ni][mi][0] = pack2bf(mv[0], mv[1]);
;         mp[ni][mi][1] = pack2bf(mv[2], mv[3]);
;       }
	v_mfma_f32_16x16x32_bf16 v[26:29], v[104:107], v[34:37], v[26:29]
	s_waitcnt lgkmcnt(0)
	v_mfma_f32_16x16x32_bf16 v[2:5], v[108:111], v[34:37], v[2:5]
	v_mfma_f32_16x16x32_bf16 v[34:37], v[108:111], v[54:57], v[10:13]
	s_nop 2
	v_add_u32_e32 v10, v103, v232
	v_mfma_f32_16x16x32_bf16 v[94:97], v[70:73], v[54:57], v[94:97]
	v_mfma_f32_16x16x32_bf16 v[82:85], v[70:73], v[62:65], v[82:85]
	v_mfma_f32_16x16x32_bf16 v[70:73], v[70:73], v[66:69], v[46:49]
	v_mfma_f32_16x16x32_bf16 v[50:53], v[74:77], v[54:57], v[50:53]
	v_mfma_f32_16x16x32_bf16 v[42:45], v[74:77], v[62:65], v[42:45]
	v_mfma_f32_16x16x32_bf16 v[38:41], v[74:77], v[66:69], v[38:41]
	v_mfma_f32_16x16x32_bf16 v[74:77], v[104:107], v[54:57], v[14:17]
	v_mfma_f32_16x16x32_bf16 v[6:9], v[104:107], v[62:65], v[6:9]
	v_mfma_f32_16x16x32_bf16 v[104:107], v[104:107], v[66:69], v[22:25]
	v_mfma_f32_16x16x32_bf16 v[112:115], v[108:111], v[62:65], v[18:21]
	v_mfma_f32_16x16x32_bf16 v[30:33], v[108:111], v[66:69], v[30:33]
	ds_read_b128 v[66:69], v10
	ds_read_b128 v[108:111], v10 offset:2048
	ds_read_b128 v[116:119], v10 offset:4096
	ds_read_b128 v[120:123], v10 offset:6144
	v_add_u32_e32 v18, v124, v232
	ds_read_b128 v[10:13], v18
	ds_read_b128 v[14:17], v18 offset:2048
	ds_read_b128 v[124:127], v18 offset:4096
	ds_read_b128 v[128:131], v18 offset:6144
	s_waitcnt lgkmcnt(3)
	v_mfma_f32_16x16x32_bf16 v[98:101], v[10:13], v[66:69], v[98:101]
	s_waitcnt lgkmcnt(0)
	s_barrier
	v_mfma_f32_16x16x32_bf16 v[62:65], v[10:13], v[108:111], v[94:97]
	v_mfma_f32_16x16x32_bf16 v[46:49], v[10:13], v[116:119], v[82:85]
	v_mfma_f32_16x16x32_bf16 v[22:25], v[10:13], v[120:123], v[70:73]
	v_mfma_f32_16x16x32_bf16 v[10:13], v[124:127], v[66:69], v[26:29]
	s_nop 2
	v_mov_b32_e32 v26, v156
	v_mov_b32_e32 v28, v154
	v_mfma_f32_16x16x32_bf16 v[18:21], v[14:17], v[66:69], v[58:61]
	v_ashrrev_i32_e32 v27, 31, v26
	v_lshl_add_u64 v[70:71], v[26:27], 2, s[40:41]
	global_load_dword v26, v[70:71], off
	v_ashrrev_i32_e32 v29, 31, v28
	v_lshl_add_u64 v[72:73], v[28:29], 2, s[2:3]
	v_mfma_f32_16x16x32_bf16 v[66:69], v[128:131], v[66:69], v[2:5]
	v_lshlrev_b32_e32 v28, 16, v242
	v_and_b32_e32 v29, 0xffff0000, v242
	s_waitcnt vmcnt(0)
	v_fmamk_f32 v26, v26, 0x3a800000, v199
	v_mfma_f32_16x16x32_bf16 v[2:5], v[128:131], v[120:123], v[30:33]
	v_cmp_gt_f32_e32 vcc, s14, v26
	v_mul_f32_e32 v27, 0x4b800000, v26
	s_nop 0
	global_load_dwordx4 v[30:33], v[72:73], off
	v_cndmask_b32_e32 v26, v26, v27, vcc
	v_rsq_f32_e32 v26, v26
	v_mfma_f32_16x16x32_bf16 v[54:57], v[124:127], v[108:111], v[74:77]
	v_mul_f32_e32 v27, 0x45800000, v26
	v_cndmask_b32_e32 v82, v26, v27, vcc
	s_nop 0
	v_lshlrev_b32_e32 v74, 16, v176
	v_and_b32_e32 v75, 0xffff0000, v176
	v_mfma_f32_16x16x32_bf16 v[58:61], v[14:17], v[108:111], v[50:53]
	s_waitcnt vmcnt(0)
	v_fma_f32 v26, v98, v82, v30
	v_fma_f32 v27, v99, v82, v31
	v_mul_f32_e32 v26, 0xbfb8aa3b, v26
	v_mul_f32_e32 v27, 0xbfb8aa3b, v27
	v_exp_f32_e32 v26, v26
	v_exp_f32_e32 v27, v27
	v_mfma_f32_16x16x32_bf16 v[50:53], v[128:131], v[108:111], v[34:37]
	v_add_f32_e64 v26, v26, 1.0
	v_add_f32_e64 v27, v27, 1.0
	v_div_scale_f32 v76, s[2:3], v27, v27, 1.0
	v_rcp_f32_e32 v77, v76
	v_mfma_f32_16x16x32_bf16 v[42:45], v[14:17], v[116:119], v[42:45]
	v_fma_f32 v83, -v76, v77, 1.0
	v_fmac_f32_e32 v77, v83, v77
	v_div_scale_f32 v83, vcc, 1.0, v27, 1.0
	v_mul_f32_e32 v84, v83, v77
	v_fma_f32 v85, -v76, v84, v83
	v_fmac_f32_e32 v84, v85, v77
	v_fma_f32 v76, -v76, v84, v83
	v_div_fmas_f32 v76, v76, v77, v84
	v_div_fixup_f32 v27, v76, v27, 1.0
	v_div_scale_f32 v76, s[2:3], v26, v26, 1.0
	v_rcp_f32_e32 v77, v76
	v_mfma_f32_16x16x32_bf16 v[14:17], v[14:17], v[120:123], v[38:41]
	v_fma_f32 v83, -v76, v77, 1.0
	v_fmac_f32_e32 v77, v83, v77
	v_div_scale_f32 v83, vcc, 1.0, v26, 1.0
	v_mul_f32_e32 v84, v83, v77
	v_fma_f32 v85, -v76, v84, v83
	v_fmac_f32_e32 v84, v85, v77
	v_fma_f32 v76, -v76, v84, v83
	v_div_fmas_f32 v76, v76, v77, v84
	v_div_fixup_f32 v26, v76, v26, 1.0
	v_pk_fma_f32 v[26:27], v[26:27], v[28:29], v[74:75]
	v_fma_f32 v28, v100, v82, v32
	v_fma_f32 v29, v101, v82, v33
	v_mul_f32_e32 v28, 0xbfb8aa3b, v28
	v_mul_f32_e32 v29, 0xbfb8aa3b, v29
	v_exp_f32_e32 v28, v28
	v_exp_f32_e32 v29, v29
	v_lshlrev_b32_e32 v74, 16, v241
	v_lshlrev_b32_e32 v76, 16, v177
	v_and_b32_e32 v75, 0xffff0000, v241
	v_pk_add_f32 v[28:29], v[28:29], 1.0 op_sel_hi:[1,0]
	v_and_b32_e32 v77, 0xffff0000, v177
	v_div_scale_f32 v83, s[2:3], v29, v29, 1.0
	v_rcp_f32_e32 v84, v83
	v_cvt_pk_bf16_f32 v176, v26, v27
	v_mfma_f32_16x16x32_bf16 v[38:41], v[124:127], v[116:119], v[6:9]
	v_fma_f32 v85, -v83, v84, 1.0
	v_fmac_f32_e32 v84, v85, v84
	v_div_scale_f32 v85, vcc, 1.0, v29, 1.0
	v_mul_f32_e32 v94, v85, v84
	v_fma_f32 v95, -v83, v94, v85
	v_fmac_f32_e32 v94, v95, v84
	v_fma_f32 v83, -v83, v94, v85
	v_div_fmas_f32 v83, v83, v84, v94
	v_div_fixup_f32 v29, v83, v29, 1.0
	v_div_scale_f32 v83, s[2:3], v28, v28, 1.0
	v_rcp_f32_e32 v84, v83
	v_mfma_f32_16x16x32_bf16 v[34:37], v[128:131], v[116:119], v[112:115]
	v_fma_f32 v85, -v83, v84, 1.0
	v_fmac_f32_e32 v84, v85, v84
	v_div_scale_f32 v85, vcc, 1.0, v28, 1.0
	v_mul_f32_e32 v94, v85, v84
	v_fma_f32 v95, -v83, v94, v85
	v_fmac_f32_e32 v94, v95, v84
	v_fma_f32 v83, -v83, v94, v85
	v_div_fmas_f32 v83, v83, v84, v94
	v_div_fixup_f32 v28, v83, v28, 1.0
	v_pk_fma_f32 v[28:29], v[28:29], v[74:75], v[76:77]
	v_lshlrev_b32_e32 v74, 16, v240
	v_cvt_pk_bf16_f32 v177, v28, v29
	global_load_dwordx4 v[26:29], v[72:73], off offset:64
	v_lshlrev_b32_e32 v76, 16, v180
	v_and_b32_e32 v75, 0xffff0000, v240
	v_and_b32_e32 v77, 0xffff0000, v180
	v_mfma_f32_16x16x32_bf16 v[6:9], v[124:127], v[120:123], v[104:107]
	s_waitcnt vmcnt(0)
; template <int MI>
; DI void merge_tile(const Params& p, int layer, int rowbase, int nt, unsigned char* smem) {
;     ...
;       const float rs = rsqrtf(rowss[m0 + mi * 16] * (1.f / DM) + EPS);
; #pragma unroll
;       for (int ni = 0; ni < 4; ++ni) {
;         const float4 b4 = *(const float4*)(bg + br * DM + n0 + ni * 16);
;         const float bb[4] = {b4.x, b4.y, b4.z, b4.w};
;         float mv[4];
; #pragma unroll
;         for (int r = 0; r < 4; ++r) {
;           const float gv = acc[ni][mi][r] * rs + bb[r];
;           const float sg = 1.f / (1.f + __expf(-gv));
;           const u32 w = brp[ni][mi][r >> 1], mw = mp[ni][mi][r >> 1];
;           const float bv = __uint_as_float((r & 1) ? (w & 0xffff0000u) : (w << 16));
;           const float mo = __uint_as_float((r & 1) ? (mw & 0xffff0000u) : (mw << 16));
;           mv[r] = mo + sg * bv;
;         }
;         mp[ni][mi][0] = pack2bf(mv[0], mv[1]);
;         mp[ni][mi][1] = pack2bf(mv[2], mv[3]);
;       }
	v_fma_f32 v18, v18, v82, v26
	v_fma_f32 v19, v19, v82, v27
	v_mul_f32_e32 v18, 0xbfb8aa3b, v18
	v_mul_f32_e32 v19, 0xbfb8aa3b, v19
	v_exp_f32_e32 v18, v18
	v_exp_f32_e32 v19, v19
	v_fma_f32 v20, v20, v82, v28
	v_fma_f32 v21, v21, v82, v29
	v_mul_f32_e32 v20, 0xbfb8aa3b, v20
	v_pk_add_f32 v[18:19], v[18:19], 1.0 op_sel_hi:[1,0]
	v_mul_f32_e32 v21, 0xbfb8aa3b, v21
	v_div_scale_f32 v83, s[2:3], v19, v19, 1.0
	v_rcp_f32_e32 v84, v83
	v_exp_f32_e32 v20, v20
	v_exp_f32_e32 v21, v21
	v_fma_f32 v85, -v83, v84, 1.0
	v_fmac_f32_e32 v84, v85, v84
	v_div_scale_f32 v85, vcc, 1.0, v19, 1.0
	v_mul_f32_e32 v94, v85, v84
	v_fma_f32 v95, -v83, v94, v85
	v_fmac_f32_e32 v94, v95, v84
	v_fma_f32 v83, -v83, v94, v85
	v_div_fmas_f32 v83, v83, v84, v94
	v_div_fixup_f32 v19, v83, v19, 1.0
	v_div_scale_f32 v83, s[2:3], v18, v18, 1.0
	v_rcp_f32_e32 v84, v83
	v_pk_add_f32 v[20:21], v[20:21], 1.0 op_sel_hi:[1,0]
	v_fma_f32 v85, -v83, v84, 1.0
	v_fmac_f32_e32 v84, v85, v84
	v_div_scale_f32 v85, vcc, 1.0, v18, 1.0
	v_mul_f32_e32 v94, v85, v84
	v_fma_f32 v95, -v83, v94, v85
	v_fmac_f32_e32 v94, v95, v84
	v_fma_f32 v83, -v83, v94, v85
	v_div_fmas_f32 v83, v83, v84, v94
	v_div_fixup_f32 v18, v83, v18, 1.0
	v_div_scale_f32 v83, s[2:3], v21, v21, 1.0
	v_rcp_f32_e32 v84, v83
	v_pk_fma_f32 v[18:19], v[18:19], v[74:75], v[76:77]
	v_lshlrev_b32_e32 v74, 16, v239
	v_lshlrev_b32_e32 v76, 16, v181
	v_fma_f32 v85, -v83, v84, 1.0
	v_fmac_f32_e32 v84, v85, v84
	v_div_scale_f32 v85, vcc, 1.0, v21, 1.0
	v_mul_f32_e32 v94, v85, v84
	v_fma_f32 v95, -v83, v94, v85
	v_fmac_f32_e32 v94, v95, v84
	v_fma_f32 v83, -v83, v94, v85
	v_div_fmas_f32 v83, v83, v84, v94
	v_div_fixup_f32 v21, v83, v21, 1.0
	v_div_scale_f32 v83, s[2:3], v20, v20, 1.0
	v_rcp_f32_e32 v84, v83
	v_and_b32_e32 v75, 0xffff0000, v239
	v_and_b32_e32 v77, 0xffff0000, v181
	v_cvt_pk_bf16_f32 v180, v18, v19
	v_fma_f32 v85, -v83, v84, 1.0
	v_fmac_f32_e32 v84, v85, v84
	v_div_scale_f32 v85, vcc, 1.0, v20, 1.0
	v_mul_f32_e32 v94, v85, v84
	v_fma_f32 v95, -v83, v94, v85
	v_fmac_f32_e32 v94, v95, v84
	v_fma_f32 v83, -v83, v94, v85
	v_div_fmas_f32 v83, v83, v84, v94
	v_div_fixup_f32 v20, v83, v20, 1.0
	v_pk_fma_f32 v[20:21], v[20:21], v[74:75], v[76:77]
	v_lshlrev_b32_e32 v74, 16, v238
	v_cvt_pk_bf16_f32 v181, v20, v21
	global_load_dwordx4 v[18:21], v[72:73], off offset:128
	v_lshlrev_b32_e32 v76, 16, v184
	v_and_b32_e32 v75, 0xffff0000, v238
	v_and_b32_e32 v77, 0xffff0000, v184
	s_waitcnt vmcnt(0)
	v_fma_f32 v10, v10, v82, v18
	v_fma_f32 v11, v11, v82, v19
	v_mul_f32_e32 v10, 0xbfb8aa3b, v10
	v_mul_f32_e32 v11, 0xbfb8aa3b, v11
	v_exp_f32_e32 v10, v10
	v_exp_f32_e32 v11, v11
	v_fma_f32 v12, v12, v82, v20
	v_fma_f32 v13, v13, v82, v21
	v_mul_f32_e32 v12, 0xbfb8aa3b, v12
	v_pk_add_f32 v[10:11], v[10:11], 1.0 op_sel_hi:[1,0]
	v_mul_f32_e32 v13, 0xbfb8aa3b, v13
	v_div_scale_f32 v83, s[2:3], v11, v11, 1.0
	v_rcp_f32_e32 v84, v83
	v_exp_f32_e32 v12, v12
	v_exp_f32_e32 v13, v13
	v_fma_f32 v85, -v83, v84, 1.0
	v_fmac_f32_e32 v84, v85, v84
	v_div_scale_f32 v85, vcc, 1.0, v11, 1.0
	v_mul_f32_e32 v94, v85, v84
	v_fma_f32 v95, -v83, v94, v85
	v_fmac_f32_e32 v94, v95, v84
	v_fma_f32 v83, -v83, v94, v85
	v_div_fmas_f32 v83, v83, v84, v94
	v_div_fixup_f32 v11, v83, v11, 1.0
	v_div_scale_f32 v83, s[2:3], v10, v10, 1.0
	v_rcp_f32_e32 v84, v83
	v_pk_add_f32 v[12:13], v[12:13], 1.0 op_sel_hi:[1,0]
	v_fma_f32 v85, -v83, v84, 1.0
	v_fmac_f32_e32 v84, v85, v84
	v_div_scale_f32 v85, vcc, 1.0, v10, 1.0
	v_mul_f32_e32 v94, v85, v84
	v_fma_f32 v95, -v83, v94, v85
	v_fmac_f32_e32 v94, v95, v84
	v_fma_f32 v83, -v83, v94, v85
	v_div_fmas_f32 v83, v83, v84, v94
	v_div_fixup_f32 v10, v83, v10, 1.0
	v_div_scale_f32 v83, s[2:3], v13, v13, 1.0
	v_rcp_f32_e32 v84, v83
	v_pk_fma_f32 v[10:11], v[10:11], v[74:75], v[76:77]
	v_lshlrev_b32_e32 v74, 16, v236
	v_lshlrev_b32_e32 v76, 16, v185
	v_fma_f32 v85, -v83, v84, 1.0
	v_fmac_f32_e32 v84, v85, v84
	v_div_scale_f32 v85, vcc, 1.0, v13, 1.0
	v_mul_f32_e32 v94, v85, v84
	v_fma_f32 v95, -v83, v94, v85
	v_fmac_f32_e32 v94, v95, v84
	v_fma_f32 v83, -v83, v94, v85
	v_div_fmas_f32 v83, v83, v84, v94
	v_div_fixup_f32 v13, v83, v13, 1.0
	v_div_scale_f32 v83, s[2:3], v12, v12, 1.0
	v_rcp_f32_e32 v84, v83
	v_and_b32_e32 v75, 0xffff0000, v236
	v_and_b32_e32 v77, 0xffff0000, v185
	v_cvt_pk_bf16_f32 v184, v10, v11
	v_fma_f32 v85, -v83, v84, 1.0
	v_fmac_f32_e32 v84, v85, v84
	v_div_scale_f32 v85, vcc, 1.0, v12, 1.0
	v_mul_f32_e32 v94, v85, v84
	v_fma_f32 v95, -v83, v94, v85
	v_fmac_f32_e32 v94, v95, v84
	v_fma_f32 v83, -v83, v94, v85
	v_div_fmas_f32 v83, v83, v84, v94
	v_div_fixup_f32 v12, v83, v12, 1.0
	v_pk_fma_f32 v[12:13], v[12:13], v[74:75], v[76:77]
	v_lshlrev_b32_e32 v74, 16, v190
	v_cvt_pk_bf16_f32 v185, v12, v13
	global_load_dwordx4 v[10:13], v[72:73], off offset:192
	v_lshlrev_b32_e32 v72, 16, v102
	v_and_b32_e32 v73, 0xffff0000, v102
	v_and_b32_e32 v75, 0xffff0000, v190
	s_waitcnt vmcnt(0)
; template <int MI>
; DI void merge_tile(const Params& p, int layer, int rowbase, int nt, unsigned char* smem) {
;     ...
;       const float rs = rsqrtf(rowss[m0 + mi * 16] * (1.f / DM) + EPS);
; #pragma unroll
;       for (int ni = 0; ni < 4; ++ni) {
;         const float4 b4 = *(const float4*)(bg + br * DM + n0 + ni * 16);
;         const float bb[4] = {b4.x, b4.y, b4.z, b4.w};
;         float mv[4];
; #pragma unroll
;         for (int r = 0; r < 4; ++r) {
;           const float gv = acc[ni][mi][r] * rs + bb[r];
;           const float sg = 1.f / (1.f + __expf(-gv));
;           const u32 w = brp[ni][mi][r >> 1], mw = mp[ni][mi][r >> 1];
;           const float bv = __uint_as_float((r & 1) ? (w & 0xffff0000u) : (w << 16));
;           const float mo = __uint_as_float((r & 1) ? (mw & 0xffff0000u) : (mw << 16));
;           mv[r] = mo + sg * bv;
;         }
;         mp[ni][mi][0] = pack2bf(mv[0], mv[1]);
;         mp[ni][mi][1] = pack2bf(mv[2], mv[3]);
;       }
	v_fma_f32 v66, v66, v82, v10
	v_fma_f32 v67, v67, v82, v11
	v_mul_f32_e32 v66, 0xbfb8aa3b, v66
	v_mul_f32_e32 v67, 0xbfb8aa3b, v67
	v_exp_f32_e32 v66, v66
	v_exp_f32_e32 v67, v67
	v_fma_f32 v68, v68, v82, v12
	v_fma_f32 v69, v69, v82, v13
	v_mul_f32_e32 v68, 0xbfb8aa3b, v68
	v_pk_add_f32 v[66:67], v[66:67], 1.0 op_sel_hi:[1,0]
	v_mul_f32_e32 v69, 0xbfb8aa3b, v69
	v_div_scale_f32 v76, s[2:3], v67, v67, 1.0
	v_rcp_f32_e32 v77, v76
	v_exp_f32_e32 v68, v68
	v_exp_f32_e32 v69, v69
	v_fma_f32 v83, -v76, v77, 1.0
	v_fmac_f32_e32 v77, v83, v77
	v_div_scale_f32 v83, vcc, 1.0, v67, 1.0
	v_mul_f32_e32 v84, v83, v77
	v_fma_f32 v85, -v76, v84, v83
	v_fmac_f32_e32 v84, v85, v77
	v_fma_f32 v76, -v76, v84, v83
	v_div_fmas_f32 v76, v76, v77, v84
	v_div_fixup_f32 v67, v76, v67, 1.0
	v_div_scale_f32 v76, s[2:3], v66, v66, 1.0
	v_rcp_f32_e32 v77, v76
	v_pk_add_f32 v[68:69], v[68:69], 1.0 op_sel_hi:[1,0]
	v_fma_f32 v83, -v76, v77, 1.0
	v_fmac_f32_e32 v77, v83, v77
	v_div_scale_f32 v83, vcc, 1.0, v66, 1.0
	v_mul_f32_e32 v84, v83, v77
	v_fma_f32 v85, -v76, v84, v83
	v_fmac_f32_e32 v84, v85, v77
	v_fma_f32 v76, -v76, v84, v83
	v_div_fmas_f32 v76, v76, v77, v84
	v_div_fixup_f32 v66, v76, v66, 1.0
	v_pk_fma_f32 v[66:67], v[66:67], v[72:73], v[74:75]
	v_div_scale_f32 v76, s[2:3], v69, v69, 1.0
	v_cvt_pk_bf16_f32 v190, v66, v67
	global_load_dword v66, v[70:71], off offset:64
	v_rcp_f32_e32 v77, v76
	v_lshlrev_b32_e32 v72, 16, v93
	v_lshlrev_b32_e32 v74, 16, v191
	v_and_b32_e32 v73, 0xffff0000, v93
	v_fma_f32 v82, -v76, v77, 1.0
	v_fmac_f32_e32 v77, v82, v77
	v_div_scale_f32 v82, vcc, 1.0, v69, 1.0
	v_mul_f32_e32 v83, v82, v77
	v_fma_f32 v84, -v76, v83, v82
	v_fmac_f32_e32 v83, v84, v77
	v_fma_f32 v76, -v76, v83, v82
	v_div_fmas_f32 v76, v76, v77, v83
	v_div_fixup_f32 v69, v76, v69, 1.0
	v_div_scale_f32 v76, s[2:3], v68, v68, 1.0
	v_rcp_f32_e32 v77, v76
	v_and_b32_e32 v75, 0xffff0000, v191
	v_fma_f32 v82, -v76, v77, 1.0
	v_fmac_f32_e32 v77, v82, v77
	v_div_scale_f32 v82, vcc, 1.0, v68, 1.0
	v_mul_f32_e32 v83, v82, v77
	v_fma_f32 v84, -v76, v83, v82
	v_fmac_f32_e32 v83, v84, v77
	v_fma_f32 v76, -v76, v83, v82
	v_div_fmas_f32 v76, v76, v77, v83
	v_div_fixup_f32 v68, v76, v68, 1.0
	v_pk_fma_f32 v[68:69], v[68:69], v[72:73], v[74:75]
	s_waitcnt vmcnt(0)
	v_fmamk_f32 v66, v66, 0x3a800000, v199
	v_cmp_gt_f32_e32 vcc, s14, v66
	v_mul_f32_e32 v67, 0x4b800000, v66
	v_cvt_pk_bf16_f32 v191, v68, v69
	v_cndmask_b32_e32 v66, v66, v67, vcc
	v_rsq_f32_e32 v66, v66
	v_lshlrev_b32_e32 v68, 16, v168
	v_and_b32_e32 v69, 0xffff0000, v168
	v_mul_f32_e32 v67, 0x45800000, v66
	v_cndmask_b32_e32 v72, v66, v67, vcc
	v_fma_f32 v62, v62, v72, v30
	v_fma_f32 v63, v63, v72, v31
	v_mul_f32_e32 v62, 0xbfb8aa3b, v62
	v_mul_f32_e32 v63, 0xbfb8aa3b, v63
	v_exp_f32_e32 v62, v62
	v_exp_f32_e32 v63, v63
	v_fma_f32 v64, v64, v72, v32
	v_fma_f32 v65, v65, v72, v33
	v_mul_f32_e32 v64, 0xbfb8aa3b, v64
	v_pk_add_f32 v[62:63], v[62:63], 1.0 op_sel_hi:[1,0]
	v_mul_f32_e32 v65, 0xbfb8aa3b, v65
	v_div_scale_f32 v73, s[2:3], v63, v63, 1.0
	v_rcp_f32_e32 v74, v73
	v_exp_f32_e32 v64, v64
	v_exp_f32_e32 v65, v65
	v_fma_f32 v58, v58, v72, v26
	v_fma_f32 v75, -v73, v74, 1.0
	v_fmac_f32_e32 v74, v75, v74
	v_div_scale_f32 v75, vcc, 1.0, v63, 1.0
	v_mul_f32_e32 v76, v75, v74
	v_fma_f32 v77, -v73, v76, v75
	v_fmac_f32_e32 v76, v77, v74
	v_fma_f32 v73, -v73, v76, v75
	v_div_fmas_f32 v73, v73, v74, v76
	v_div_fixup_f32 v63, v73, v63, 1.0
	v_div_scale_f32 v73, s[2:3], v62, v62, 1.0
	v_rcp_f32_e32 v74, v73
	v_pk_add_f32 v[64:65], v[64:65], 1.0 op_sel_hi:[1,0]
	v_fma_f32 v59, v59, v72, v27
	v_mul_f32_e32 v58, 0xbfb8aa3b, v58
	v_fma_f32 v75, -v73, v74, 1.0
	v_fmac_f32_e32 v74, v75, v74
	v_div_scale_f32 v75, vcc, 1.0, v62, 1.0
	v_mul_f32_e32 v76, v75, v74
	v_fma_f32 v77, -v73, v76, v75
	v_fmac_f32_e32 v76, v77, v74
	v_fma_f32 v73, -v73, v76, v75
	v_div_fmas_f32 v73, v73, v74, v76
	v_div_fixup_f32 v62, v73, v62, 1.0
	v_div_scale_f32 v73, s[2:3], v65, v65, 1.0
	v_rcp_f32_e32 v74, v73
	v_mul_f32_e32 v59, 0xbfb8aa3b, v59
	v_exp_f32_e32 v58, v58
	v_exp_f32_e32 v59, v59
	v_fma_f32 v75, -v73, v74, 1.0
	v_fmac_f32_e32 v74, v75, v74
	v_div_scale_f32 v75, vcc, 1.0, v65, 1.0
	v_mul_f32_e32 v76, v75, v74
	v_fma_f32 v77, -v73, v76, v75
	v_fmac_f32_e32 v76, v77, v74
	v_fma_f32 v73, -v73, v76, v75
	v_div_fmas_f32 v73, v73, v74, v76
	v_div_fixup_f32 v65, v73, v65, 1.0
	v_div_scale_f32 v73, s[2:3], v64, v64, 1.0
	v_rcp_f32_e32 v74, v73
	v_lshlrev_b32_e32 v66, 16, v231
	v_and_b32_e32 v67, 0xffff0000, v231
	v_pk_fma_f32 v[62:63], v[62:63], v[66:67], v[68:69]
	v_fma_f32 v75, -v73, v74, 1.0
	v_fmac_f32_e32 v74, v75, v74
	v_div_scale_f32 v75, vcc, 1.0, v64, 1.0
	v_mul_f32_e32 v76, v75, v74
	v_fma_f32 v77, -v73, v76, v75
	v_fmac_f32_e32 v76, v77, v74
	v_fma_f32 v73, -v73, v76, v75
	v_div_fmas_f32 v73, v73, v74, v76
	v_lshlrev_b32_e32 v66, 16, v230
	v_lshlrev_b32_e32 v68, 16, v169
	v_and_b32_e32 v67, 0xffff0000, v230
	v_and_b32_e32 v69, 0xffff0000, v169
	v_div_fixup_f32 v64, v73, v64, 1.0
	v_pk_add_f32 v[58:59], v[58:59], 1.0 op_sel_hi:[1,0]
	v_pk_fma_f32 v[64:65], v[64:65], v[66:67], v[68:69]
	v_div_scale_f32 v66, s[2:3], v59, v59, 1.0
	v_rcp_f32_e32 v67, v66
	v_fma_f32 v60, v60, v72, v28
	v_fma_f32 v61, v61, v72, v29
	v_mul_f32_e32 v60, 0xbfb8aa3b, v60
	v_fma_f32 v68, -v66, v67, 1.0
	v_fmac_f32_e32 v67, v68, v67
	v_div_scale_f32 v68, vcc, 1.0, v59, 1.0
	v_mul_f32_e32 v69, v68, v67
	v_fma_f32 v73, -v66, v69, v68
	v_fmac_f32_e32 v69, v73, v67
	v_fma_f32 v66, -v66, v69, v68
	v_div_fmas_f32 v66, v66, v67, v69
	v_div_fixup_f32 v59, v66, v59, 1.0
	v_div_scale_f32 v66, s[2:3], v58, v58, 1.0
	v_rcp_f32_e32 v67, v66
	v_mul_f32_e32 v61, 0xbfb8aa3b, v61
; template <int MI>
; DI void merge_tile(const Params& p, int layer, int rowbase, int nt, unsigned char* smem) {
;     ...
;       const float rs = rsqrtf(rowss[m0 + mi * 16] * (1.f / DM) + EPS);
; #pragma unroll
;       for (int ni = 0; ni < 4; ++ni) {
;         const float4 b4 = *(const float4*)(bg + br * DM + n0 + ni * 16);
;         const float bb[4] = {b4.x, b4.y, b4.z, b4.w};
;         float mv[4];
; #pragma unroll
;         for (int r = 0; r < 4; ++r) {
;           const float gv = acc[ni][mi][r] * rs + bb[r];
;           const float sg = 1.f / (1.f + __expf(-gv));
;           const u32 w = brp[ni][mi][r >> 1], mw = mp[ni][mi][r >> 1];
;           const float bv = __uint_as_float((r & 1) ? (w & 0xffff0000u) : (w << 16));
;           const float mo = __uint_as_float((r & 1) ? (mw & 0xffff0000u) : (mw << 16));
;           mv[r] = mo + sg * bv;
;         }
;         mp[ni][mi][0] = pack2bf(mv[0], mv[1]);
;         mp[ni][mi][1] = pack2bf(mv[2], mv[3]);
;       }
	v_exp_f32_e32 v60, v60
	v_exp_f32_e32 v61, v61
	v_fma_f32 v68, -v66, v67, 1.0
	v_fmac_f32_e32 v67, v68, v67
	v_div_scale_f32 v68, vcc, 1.0, v58, 1.0
	v_mul_f32_e32 v69, v68, v67
	v_fma_f32 v73, -v66, v69, v68
	v_fmac_f32_e32 v69, v73, v67
	v_fma_f32 v66, -v66, v69, v68
	v_div_fmas_f32 v66, v66, v67, v69
	v_pk_add_f32 v[60:61], v[60:61], 1.0 op_sel_hi:[1,0]
	v_div_fixup_f32 v58, v66, v58, 1.0
	v_div_scale_f32 v66, s[2:3], v61, v61, 1.0
	v_rcp_f32_e32 v67, v66
	v_fma_f32 v54, v54, v72, v18
	v_fma_f32 v55, v55, v72, v19
	v_mul_f32_e32 v54, 0xbfb8aa3b, v54
	v_fma_f32 v68, -v66, v67, 1.0
	v_fmac_f32_e32 v67, v68, v67
	v_div_scale_f32 v68, vcc, 1.0, v61, 1.0
	v_mul_f32_e32 v69, v68, v67
	v_fma_f32 v73, -v66, v69, v68
	v_fmac_f32_e32 v69, v73, v67
	v_fma_f32 v66, -v66, v69, v68
	v_div_fmas_f32 v66, v66, v67, v69
	v_div_fixup_f32 v61, v66, v61, 1.0
	v_div_scale_f32 v66, s[2:3], v60, v60, 1.0
	v_rcp_f32_e32 v67, v66
	v_mul_f32_e32 v55, 0xbfb8aa3b, v55
	v_exp_f32_e32 v54, v54
	v_exp_f32_e32 v55, v55
	v_fma_f32 v68, -v66, v67, 1.0
	v_fmac_f32_e32 v67, v68, v67
	v_div_scale_f32 v68, vcc, 1.0, v60, 1.0
	v_mul_f32_e32 v69, v68, v67
	v_fma_f32 v73, -v66, v69, v68
	v_fmac_f32_e32 v69, v73, v67
	v_fma_f32 v66, -v66, v69, v68
	v_cvt_pk_bf16_f32 v168, v62, v63
	v_cvt_pk_bf16_f32 v169, v64, v65
	v_lshlrev_b32_e32 v62, 16, v229
	v_lshlrev_b32_e32 v64, 16, v170
	v_and_b32_e32 v63, 0xffff0000, v229
	v_and_b32_e32 v65, 0xffff0000, v170
	v_div_fmas_f32 v66, v66, v67, v69
	v_pk_fma_f32 v[58:59], v[58:59], v[62:63], v[64:65]
	v_lshlrev_b32_e32 v62, 16, v228
	v_lshlrev_b32_e32 v64, 16, v171
	v_and_b32_e32 v63, 0xffff0000, v228
	v_and_b32_e32 v65, 0xffff0000, v171
	v_div_fixup_f32 v60, v66, v60, 1.0
	v_pk_add_f32 v[54:55], v[54:55], 1.0 op_sel_hi:[1,0]
	v_pk_fma_f32 v[60:61], v[60:61], v[62:63], v[64:65]
	v_div_scale_f32 v62, s[2:3], v55, v55, 1.0
	v_rcp_f32_e32 v63, v62
	v_fma_f32 v56, v56, v72, v20
	v_fma_f32 v57, v57, v72, v21
	v_mul_f32_e32 v56, 0xbfb8aa3b, v56
	v_fma_f32 v64, -v62, v63, 1.0
	v_fmac_f32_e32 v63, v64, v63
	v_div_scale_f32 v64, vcc, 1.0, v55, 1.0
	v_mul_f32_e32 v65, v64, v63
	v_fma_f32 v66, -v62, v65, v64
	v_fmac_f32_e32 v65, v66, v63
	v_fma_f32 v62, -v62, v65, v64
	v_div_fmas_f32 v62, v62, v63, v65
	v_div_fixup_f32 v55, v62, v55, 1.0
	v_div_scale_f32 v62, s[2:3], v54, v54, 1.0
	v_rcp_f32_e32 v63, v62
	v_mul_f32_e32 v57, 0xbfb8aa3b, v57
	v_exp_f32_e32 v56, v56
	v_exp_f32_e32 v57, v57
	v_fma_f32 v64, -v62, v63, 1.0
	v_fmac_f32_e32 v63, v64, v63
	v_div_scale_f32 v64, vcc, 1.0, v54, 1.0
	v_mul_f32_e32 v65, v64, v63
	v_fma_f32 v66, -v62, v65, v64
	v_fmac_f32_e32 v65, v66, v63
	v_fma_f32 v62, -v62, v65, v64
	v_div_fmas_f32 v62, v62, v63, v65
	v_pk_add_f32 v[56:57], v[56:57], 1.0 op_sel_hi:[1,0]
	v_div_fixup_f32 v54, v62, v54, 1.0
	v_div_scale_f32 v62, s[2:3], v57, v57, 1.0
	v_rcp_f32_e32 v63, v62
	v_fma_f32 v50, v50, v72, v10
	v_fma_f32 v51, v51, v72, v11
	v_mul_f32_e32 v50, 0xbfb8aa3b, v50
	v_fma_f32 v64, -v62, v63, 1.0
	v_fmac_f32_e32 v63, v64, v63
	v_div_scale_f32 v64, vcc, 1.0, v57, 1.0
	v_mul_f32_e32 v65, v64, v63
	v_fma_f32 v66, -v62, v65, v64
	v_fmac_f32_e32 v65, v66, v63
	v_fma_f32 v62, -v62, v65, v64
	v_div_fmas_f32 v62, v62, v63, v65
	v_div_fixup_f32 v57, v62, v57, 1.0
	v_div_scale_f32 v62, s[2:3], v56, v56, 1.0
	v_rcp_f32_e32 v63, v62
	v_mul_f32_e32 v51, 0xbfb8aa3b, v51
	v_exp_f32_e32 v50, v50
	v_exp_f32_e32 v51, v51
	v_fma_f32 v64, -v62, v63, 1.0
	v_fmac_f32_e32 v63, v64, v63
	v_div_scale_f32 v64, vcc, 1.0, v56, 1.0
	v_mul_f32_e32 v65, v64, v63
	v_fma_f32 v66, -v62, v65, v64
	v_fmac_f32_e32 v65, v66, v63
	v_fma_f32 v62, -v62, v65, v64
	v_cvt_pk_bf16_f32 v170, v58, v59
	v_cvt_pk_bf16_f32 v171, v60, v61
	v_lshlrev_b32_e32 v58, 16, v227
	v_lshlrev_b32_e32 v60, 16, v172
	v_and_b32_e32 v59, 0xffff0000, v227
	v_and_b32_e32 v61, 0xffff0000, v172
	v_div_fmas_f32 v62, v62, v63, v65
	v_pk_fma_f32 v[54:55], v[54:55], v[58:59], v[60:61]
	v_lshlrev_b32_e32 v58, 16, v92
	v_lshlrev_b32_e32 v60, 16, v173
	v_and_b32_e32 v59, 0xffff0000, v92
	v_and_b32_e32 v61, 0xffff0000, v173
	v_div_fixup_f32 v56, v62, v56, 1.0
	v_pk_add_f32 v[50:51], v[50:51], 1.0 op_sel_hi:[1,0]
	v_pk_fma_f32 v[56:57], v[56:57], v[58:59], v[60:61]
	v_div_scale_f32 v58, s[2:3], v51, v51, 1.0
	v_rcp_f32_e32 v59, v58
	v_cvt_pk_bf16_f32 v172, v54, v55
	v_cvt_pk_bf16_f32 v173, v56, v57
	v_lshlrev_b32_e32 v54, 16, v91
	v_fma_f32 v60, -v58, v59, 1.0
	v_fmac_f32_e32 v59, v60, v59
	v_div_scale_f32 v60, vcc, 1.0, v51, 1.0
	v_mul_f32_e32 v61, v60, v59
	v_fma_f32 v62, -v58, v61, v60
	v_fmac_f32_e32 v61, v62, v59
	v_fma_f32 v58, -v58, v61, v60
	v_div_fmas_f32 v58, v58, v59, v61
	v_div_fixup_f32 v51, v58, v51, 1.0
	v_div_scale_f32 v58, s[2:3], v50, v50, 1.0
	v_rcp_f32_e32 v59, v58
	v_lshlrev_b32_e32 v56, 16, v174
	v_and_b32_e32 v55, 0xffff0000, v91
	v_and_b32_e32 v57, 0xffff0000, v174
	v_fma_f32 v60, -v58, v59, 1.0
	v_fmac_f32_e32 v59, v60, v59
	v_div_scale_f32 v60, vcc, 1.0, v50, 1.0
	v_mul_f32_e32 v61, v60, v59
	v_fma_f32 v62, -v58, v61, v60
	v_fmac_f32_e32 v61, v62, v59
	v_fma_f32 v58, -v58, v61, v60
	v_div_fmas_f32 v58, v58, v59, v61
	v_div_fixup_f32 v50, v58, v50, 1.0
	v_pk_fma_f32 v[50:51], v[50:51], v[54:55], v[56:57]
	v_fma_f32 v52, v52, v72, v12
	v_cvt_pk_bf16_f32 v174, v50, v51
	global_load_dword v50, v[70:71], off offset:128
	v_fma_f32 v53, v53, v72, v13
	v_mul_f32_e32 v52, 0xbfb8aa3b, v52
	v_mul_f32_e32 v53, 0xbfb8aa3b, v53
	v_exp_f32_e32 v52, v52
	v_exp_f32_e32 v53, v53
	v_lshlrev_b32_e32 v54, 16, v90
	v_lshlrev_b32_e32 v56, 16, v175
	v_and_b32_e32 v55, 0xffff0000, v90
	v_pk_add_f32 v[52:53], v[52:53], 1.0 op_sel_hi:[1,0]
	v_and_b32_e32 v57, 0xffff0000, v175
	v_div_scale_f32 v58, s[2:3], v53, v53, 1.0
	v_rcp_f32_e32 v59, v58
	s_waitcnt vmcnt(0)
; template <int MI>
; DI void merge_tile(const Params& p, int layer, int rowbase, int nt, unsigned char* smem) {
;     ...
;       const float rs = rsqrtf(rowss[m0 + mi * 16] * (1.f / DM) + EPS);
; #pragma unroll
;       for (int ni = 0; ni < 4; ++ni) {
;         const float4 b4 = *(const float4*)(bg + br * DM + n0 + ni * 16);
;         const float bb[4] = {b4.x, b4.y, b4.z, b4.w};
;         float mv[4];
; #pragma unroll
;         for (int r = 0; r < 4; ++r) {
;           const float gv = acc[ni][mi][r] * rs + bb[r];
;           const float sg = 1.f / (1.f + __expf(-gv));
;           const u32 w = brp[ni][mi][r >> 1], mw = mp[ni][mi][r >> 1];
;           const float bv = __uint_as_float((r & 1) ? (w & 0xffff0000u) : (w << 16));
;           const float mo = __uint_as_float((r & 1) ? (mw & 0xffff0000u) : (mw << 16));
;           mv[r] = mo + sg * bv;
;         }
;         mp[ni][mi][0] = pack2bf(mv[0], mv[1]);
;         mp[ni][mi][1] = pack2bf(mv[2], mv[3]);
;       }
	v_fmamk_f32 v50, v50, 0x3a800000, v199
	v_fma_f32 v60, -v58, v59, 1.0
	v_fmac_f32_e32 v59, v60, v59
	v_div_scale_f32 v60, vcc, 1.0, v53, 1.0
	v_mul_f32_e32 v61, v60, v59
	v_fma_f32 v62, -v58, v61, v60
	v_fmac_f32_e32 v61, v62, v59
	v_fma_f32 v58, -v58, v61, v60
	v_div_fmas_f32 v58, v58, v59, v61
	v_div_fixup_f32 v53, v58, v53, 1.0
	v_div_scale_f32 v58, s[2:3], v52, v52, 1.0
	v_rcp_f32_e32 v59, v58
	v_mul_f32_e32 v51, 0x4b800000, v50
	v_fma_f32 v60, -v58, v59, 1.0
	v_fmac_f32_e32 v59, v60, v59
	v_div_scale_f32 v60, vcc, 1.0, v52, 1.0
	v_mul_f32_e32 v61, v60, v59
	v_fma_f32 v62, -v58, v61, v60
	v_fmac_f32_e32 v61, v62, v59
	v_fma_f32 v58, -v58, v61, v60
	v_div_fmas_f32 v58, v58, v59, v61
	v_cmp_gt_f32_e32 vcc, s14, v50
	v_div_fixup_f32 v52, v58, v52, 1.0
	v_pk_fma_f32 v[52:53], v[52:53], v[54:55], v[56:57]
	v_cndmask_b32_e32 v50, v50, v51, vcc
	v_rsq_f32_e32 v50, v50
	v_cvt_pk_bf16_f32 v175, v52, v53
	v_lshlrev_b32_e32 v52, 16, v158
	v_and_b32_e32 v53, 0xffff0000, v158
	v_mul_f32_e32 v51, 0x45800000, v50
	v_cndmask_b32_e32 v54, v50, v51, vcc
	v_fma_f32 v46, v46, v54, v30
	v_fma_f32 v47, v47, v54, v31
	v_mul_f32_e32 v46, 0xbfb8aa3b, v46
	v_mul_f32_e32 v47, 0xbfb8aa3b, v47
	v_exp_f32_e32 v46, v46
	v_exp_f32_e32 v47, v47
	v_fma_f32 v48, v48, v54, v32
	v_fma_f32 v49, v49, v54, v33
	v_mul_f32_e32 v48, 0xbfb8aa3b, v48
	v_pk_add_f32 v[46:47], v[46:47], 1.0 op_sel_hi:[1,0]
	v_mul_f32_e32 v49, 0xbfb8aa3b, v49
	v_div_scale_f32 v55, s[2:3], v47, v47, 1.0
	v_rcp_f32_e32 v56, v55
	v_exp_f32_e32 v48, v48
	v_exp_f32_e32 v49, v49
	v_fma_f32 v42, v42, v54, v26
	v_fma_f32 v57, -v55, v56, 1.0
	v_fmac_f32_e32 v56, v57, v56
	v_div_scale_f32 v57, vcc, 1.0, v47, 1.0
	v_mul_f32_e32 v58, v57, v56
	v_fma_f32 v59, -v55, v58, v57
	v_fmac_f32_e32 v58, v59, v56
	v_fma_f32 v55, -v55, v58, v57
	v_div_fmas_f32 v55, v55, v56, v58
	v_div_fixup_f32 v47, v55, v47, 1.0
	v_div_scale_f32 v55, s[2:3], v46, v46, 1.0
	v_rcp_f32_e32 v56, v55
	v_pk_add_f32 v[48:49], v[48:49], 1.0 op_sel_hi:[1,0]
	v_fma_f32 v43, v43, v54, v27
	v_mul_f32_e32 v42, 0xbfb8aa3b, v42
	v_fma_f32 v57, -v55, v56, 1.0
	v_fmac_f32_e32 v56, v57, v56
	v_div_scale_f32 v57, vcc, 1.0, v46, 1.0
	v_mul_f32_e32 v58, v57, v56
	v_fma_f32 v59, -v55, v58, v57
	v_fmac_f32_e32 v58, v59, v56
	v_fma_f32 v55, -v55, v58, v57
	v_div_fmas_f32 v55, v55, v56, v58
	v_div_fixup_f32 v46, v55, v46, 1.0
	v_div_scale_f32 v55, s[2:3], v49, v49, 1.0
	v_rcp_f32_e32 v56, v55
	v_mul_f32_e32 v43, 0xbfb8aa3b, v43
	v_exp_f32_e32 v42, v42
	v_exp_f32_e32 v43, v43
	v_fma_f32 v57, -v55, v56, 1.0
	v_fmac_f32_e32 v56, v57, v56
	v_div_scale_f32 v57, vcc, 1.0, v49, 1.0
	v_mul_f32_e32 v58, v57, v56
	v_fma_f32 v59, -v55, v58, v57
	v_fmac_f32_e32 v58, v59, v56
	v_fma_f32 v55, -v55, v58, v57
	v_div_fmas_f32 v55, v55, v56, v58
	v_div_fixup_f32 v49, v55, v49, 1.0
	v_div_scale_f32 v55, s[2:3], v48, v48, 1.0
	v_rcp_f32_e32 v56, v55
	v_lshlrev_b32_e32 v50, 16, v226
	v_and_b32_e32 v51, 0xffff0000, v226
	v_pk_fma_f32 v[46:47], v[46:47], v[50:51], v[52:53]
	v_fma_f32 v57, -v55, v56, 1.0
	v_fmac_f32_e32 v56, v57, v56
	v_div_scale_f32 v57, vcc, 1.0, v48, 1.0
	v_mul_f32_e32 v58, v57, v56
	v_fma_f32 v59, -v55, v58, v57
	v_fmac_f32_e32 v58, v59, v56
	v_fma_f32 v55, -v55, v58, v57
	v_div_fmas_f32 v55, v55, v56, v58
	v_lshlrev_b32_e32 v50, 16, v225
	v_lshlrev_b32_e32 v52, 16, v159
	v_and_b32_e32 v51, 0xffff0000, v225
	v_and_b32_e32 v53, 0xffff0000, v159
	v_div_fixup_f32 v48, v55, v48, 1.0
	v_pk_add_f32 v[42:43], v[42:43], 1.0 op_sel_hi:[1,0]
	v_pk_fma_f32 v[48:49], v[48:49], v[50:51], v[52:53]
	v_div_scale_f32 v50, s[2:3], v43, v43, 1.0
	v_rcp_f32_e32 v51, v50
	v_fma_f32 v44, v44, v54, v28
	v_fma_f32 v45, v45, v54, v29
	v_mul_f32_e32 v44, 0xbfb8aa3b, v44
	v_fma_f32 v52, -v50, v51, 1.0
	v_fmac_f32_e32 v51, v52, v51
	v_div_scale_f32 v52, vcc, 1.0, v43, 1.0
	v_mul_f32_e32 v53, v52, v51
	v_fma_f32 v55, -v50, v53, v52
	v_fmac_f32_e32 v53, v55, v51
	v_fma_f32 v50, -v50, v53, v52
	v_div_fmas_f32 v50, v50, v51, v53
	v_div_fixup_f32 v43, v50, v43, 1.0
	v_div_scale_f32 v50, s[2:3], v42, v42, 1.0
	v_rcp_f32_e32 v51, v50
	v_mul_f32_e32 v45, 0xbfb8aa3b, v45
	v_exp_f32_e32 v44, v44
	v_exp_f32_e32 v45, v45
	v_fma_f32 v52, -v50, v51, 1.0
	v_fmac_f32_e32 v51, v52, v51
	v_div_scale_f32 v52, vcc, 1.0, v42, 1.0
	v_mul_f32_e32 v53, v52, v51
	v_fma_f32 v55, -v50, v53, v52
	v_fmac_f32_e32 v53, v55, v51
	v_fma_f32 v50, -v50, v53, v52
	v_div_fmas_f32 v50, v50, v51, v53
	v_pk_add_f32 v[44:45], v[44:45], 1.0 op_sel_hi:[1,0]
	v_div_fixup_f32 v42, v50, v42, 1.0
	v_div_scale_f32 v50, s[2:3], v45, v45, 1.0
	v_rcp_f32_e32 v51, v50
	v_fma_f32 v38, v38, v54, v18
	v_fma_f32 v39, v39, v54, v19
	v_mul_f32_e32 v38, 0xbfb8aa3b, v38
	v_fma_f32 v52, -v50, v51, 1.0
	v_fmac_f32_e32 v51, v52, v51
	v_div_scale_f32 v52, vcc, 1.0, v45, 1.0
	v_mul_f32_e32 v53, v52, v51
	v_fma_f32 v55, -v50, v53, v52
	v_fmac_f32_e32 v53, v55, v51
	v_fma_f32 v50, -v50, v53, v52
	v_div_fmas_f32 v50, v50, v51, v53
	v_div_fixup_f32 v45, v50, v45, 1.0
	v_div_scale_f32 v50, s[2:3], v44, v44, 1.0
	v_rcp_f32_e32 v51, v50
	v_mul_f32_e32 v39, 0xbfb8aa3b, v39
	v_exp_f32_e32 v38, v38
	v_exp_f32_e32 v39, v39
	v_fma_f32 v52, -v50, v51, 1.0
	v_fmac_f32_e32 v51, v52, v51
	v_div_scale_f32 v52, vcc, 1.0, v44, 1.0
	v_mul_f32_e32 v53, v52, v51
	v_fma_f32 v55, -v50, v53, v52
	v_fmac_f32_e32 v53, v55, v51
	v_fma_f32 v50, -v50, v53, v52
	v_cvt_pk_bf16_f32 v158, v46, v47
	v_cvt_pk_bf16_f32 v159, v48, v49
	v_lshlrev_b32_e32 v46, 16, v195
	v_lshlrev_b32_e32 v48, 16, v160
	v_and_b32_e32 v47, 0xffff0000, v195
	v_and_b32_e32 v49, 0xffff0000, v160
	v_div_fmas_f32 v50, v50, v51, v53
	v_pk_fma_f32 v[42:43], v[42:43], v[46:47], v[48:49]
	v_lshlrev_b32_e32 v46, 16, v194
; template <int MI>
; DI void merge_tile(const Params& p, int layer, int rowbase, int nt, unsigned char* smem) {
;     ...
;       const float rs = rsqrtf(rowss[m0 + mi * 16] * (1.f / DM) + EPS);
; #pragma unroll
;       for (int ni = 0; ni < 4; ++ni) {
;         const float4 b4 = *(const float4*)(bg + br * DM + n0 + ni * 16);
;         const float bb[4] = {b4.x, b4.y, b4.z, b4.w};
;         float mv[4];
; #pragma unroll
;         for (int r = 0; r < 4; ++r) {
;           const float gv = acc[ni][mi][r] * rs + bb[r];
;           const float sg = 1.f / (1.f + __expf(-gv));
;           const u32 w = brp[ni][mi][r >> 1], mw = mp[ni][mi][r >> 1];
;           const float bv = __uint_as_float((r & 1) ? (w & 0xffff0000u) : (w << 16));
;           const float mo = __uint_as_float((r & 1) ? (mw & 0xffff0000u) : (mw << 16));
;           mv[r] = mo + sg * bv;
;         }
;         mp[ni][mi][0] = pack2bf(mv[0], mv[1]);
;         mp[ni][mi][1] = pack2bf(mv[2], mv[3]);
;       }
	v_lshlrev_b32_e32 v48, 16, v161
	v_and_b32_e32 v47, 0xffff0000, v194
	v_and_b32_e32 v49, 0xffff0000, v161
	v_div_fixup_f32 v44, v50, v44, 1.0
	v_pk_add_f32 v[38:39], v[38:39], 1.0 op_sel_hi:[1,0]
	v_pk_fma_f32 v[44:45], v[44:45], v[46:47], v[48:49]
	v_div_scale_f32 v46, s[2:3], v39, v39, 1.0
	v_rcp_f32_e32 v47, v46
	v_fma_f32 v40, v40, v54, v20
	v_fma_f32 v41, v41, v54, v21
	v_mul_f32_e32 v40, 0xbfb8aa3b, v40
	v_fma_f32 v48, -v46, v47, 1.0
	v_fmac_f32_e32 v47, v48, v47
	v_div_scale_f32 v48, vcc, 1.0, v39, 1.0
	v_mul_f32_e32 v49, v48, v47
	v_fma_f32 v50, -v46, v49, v48
	v_fmac_f32_e32 v49, v50, v47
	v_fma_f32 v46, -v46, v49, v48
	v_div_fmas_f32 v46, v46, v47, v49
	v_div_fixup_f32 v39, v46, v39, 1.0
	v_div_scale_f32 v46, s[2:3], v38, v38, 1.0
	v_rcp_f32_e32 v47, v46
	v_mul_f32_e32 v41, 0xbfb8aa3b, v41
	v_exp_f32_e32 v40, v40
	v_exp_f32_e32 v41, v41
	v_fma_f32 v48, -v46, v47, 1.0
	v_fmac_f32_e32 v47, v48, v47
	v_div_scale_f32 v48, vcc, 1.0, v38, 1.0
	v_mul_f32_e32 v49, v48, v47
	v_fma_f32 v50, -v46, v49, v48
	v_fmac_f32_e32 v49, v50, v47
	v_fma_f32 v46, -v46, v49, v48
	v_div_fmas_f32 v46, v46, v47, v49
	v_pk_add_f32 v[40:41], v[40:41], 1.0 op_sel_hi:[1,0]
	v_div_fixup_f32 v38, v46, v38, 1.0
	v_div_scale_f32 v46, s[2:3], v41, v41, 1.0
	v_rcp_f32_e32 v47, v46
	v_fma_f32 v34, v34, v54, v10
	v_fma_f32 v35, v35, v54, v11
	v_mul_f32_e32 v34, 0xbfb8aa3b, v34
	v_fma_f32 v48, -v46, v47, 1.0
	v_fmac_f32_e32 v47, v48, v47
	v_div_scale_f32 v48, vcc, 1.0, v41, 1.0
	v_mul_f32_e32 v49, v48, v47
	v_fma_f32 v50, -v46, v49, v48
	v_fmac_f32_e32 v49, v50, v47
	v_fma_f32 v46, -v46, v49, v48
	v_div_fmas_f32 v46, v46, v47, v49
	v_div_fixup_f32 v41, v46, v41, 1.0
	v_div_scale_f32 v46, s[2:3], v40, v40, 1.0
	v_rcp_f32_e32 v47, v46
	v_mul_f32_e32 v35, 0xbfb8aa3b, v35
	v_exp_f32_e32 v34, v34
	v_exp_f32_e32 v35, v35
	v_fma_f32 v48, -v46, v47, 1.0
	v_fmac_f32_e32 v47, v48, v47
	v_div_scale_f32 v48, vcc, 1.0, v40, 1.0
	v_mul_f32_e32 v49, v48, v47
	v_fma_f32 v50, -v46, v49, v48
	v_fmac_f32_e32 v49, v50, v47
	v_fma_f32 v46, -v46, v49, v48
	v_cvt_pk_bf16_f32 v160, v42, v43
	v_cvt_pk_bf16_f32 v161, v44, v45
	v_lshlrev_b32_e32 v42, 16, v89
	v_lshlrev_b32_e32 v44, 16, v162
	v_and_b32_e32 v43, 0xffff0000, v89
	v_and_b32_e32 v45, 0xffff0000, v162
	v_div_fmas_f32 v46, v46, v47, v49
	v_pk_fma_f32 v[38:39], v[38:39], v[42:43], v[44:45]
	v_lshlrev_b32_e32 v42, 16, v88
	v_lshlrev_b32_e32 v44, 16, v163
	v_and_b32_e32 v43, 0xffff0000, v88
	v_and_b32_e32 v45, 0xffff0000, v163
	v_div_fixup_f32 v40, v46, v40, 1.0
	v_pk_add_f32 v[34:35], v[34:35], 1.0 op_sel_hi:[1,0]
	v_pk_fma_f32 v[40:41], v[40:41], v[42:43], v[44:45]
	v_div_scale_f32 v42, s[2:3], v35, v35, 1.0
	v_rcp_f32_e32 v43, v42
	v_cvt_pk_bf16_f32 v162, v38, v39
	v_cvt_pk_bf16_f32 v163, v40, v41
	v_lshlrev_b32_e32 v38, 16, v87
	v_fma_f32 v44, -v42, v43, 1.0
	v_fmac_f32_e32 v43, v44, v43
	v_div_scale_f32 v44, vcc, 1.0, v35, 1.0
	v_mul_f32_e32 v45, v44, v43
	v_fma_f32 v46, -v42, v45, v44
	v_fmac_f32_e32 v45, v46, v43
	v_fma_f32 v42, -v42, v45, v44
	v_div_fmas_f32 v42, v42, v43, v45
	v_div_fixup_f32 v35, v42, v35, 1.0
	v_div_scale_f32 v42, s[2:3], v34, v34, 1.0
	v_rcp_f32_e32 v43, v42
	v_lshlrev_b32_e32 v40, 16, v164
	v_and_b32_e32 v39, 0xffff0000, v87
	v_and_b32_e32 v41, 0xffff0000, v164
	v_fma_f32 v44, -v42, v43, 1.0
	v_fmac_f32_e32 v43, v44, v43
	v_div_scale_f32 v44, vcc, 1.0, v34, 1.0
	v_mul_f32_e32 v45, v44, v43
	v_fma_f32 v46, -v42, v45, v44
	v_fmac_f32_e32 v45, v46, v43
	v_fma_f32 v42, -v42, v45, v44
	v_div_fmas_f32 v42, v42, v43, v45
	v_div_fixup_f32 v34, v42, v34, 1.0
	v_pk_fma_f32 v[34:35], v[34:35], v[38:39], v[40:41]
	v_fma_f32 v36, v36, v54, v12
	v_cvt_pk_bf16_f32 v164, v34, v35
	global_load_dword v34, v[70:71], off offset:192
	v_fma_f32 v37, v37, v54, v13
	v_mul_f32_e32 v36, 0xbfb8aa3b, v36
	v_mul_f32_e32 v37, 0xbfb8aa3b, v37
	v_exp_f32_e32 v36, v36
	v_exp_f32_e32 v37, v37
	v_lshlrev_b32_e32 v38, 16, v86
	v_lshlrev_b32_e32 v40, 16, v165
	v_and_b32_e32 v39, 0xffff0000, v86
	v_pk_add_f32 v[36:37], v[36:37], 1.0 op_sel_hi:[1,0]
	v_and_b32_e32 v41, 0xffff0000, v165
	v_div_scale_f32 v42, s[2:3], v37, v37, 1.0
	v_rcp_f32_e32 v43, v42
	s_waitcnt vmcnt(0)
	v_fmamk_f32 v34, v34, 0x3a800000, v199
	v_fma_f32 v44, -v42, v43, 1.0
	v_fmac_f32_e32 v43, v44, v43
	v_div_scale_f32 v44, vcc, 1.0, v37, 1.0
	v_mul_f32_e32 v45, v44, v43
	v_fma_f32 v46, -v42, v45, v44
	v_fmac_f32_e32 v45, v46, v43
	v_fma_f32 v42, -v42, v45, v44
	v_div_fmas_f32 v42, v42, v43, v45
	v_div_fixup_f32 v37, v42, v37, 1.0
	v_div_scale_f32 v42, s[2:3], v36, v36, 1.0
	v_rcp_f32_e32 v43, v42
	v_mul_f32_e32 v35, 0x4b800000, v34
	v_fma_f32 v44, -v42, v43, 1.0
	v_fmac_f32_e32 v43, v44, v43
	v_div_scale_f32 v44, vcc, 1.0, v36, 1.0
	v_mul_f32_e32 v45, v44, v43
	v_fma_f32 v46, -v42, v45, v44
	v_fmac_f32_e32 v45, v46, v43
	v_fma_f32 v42, -v42, v45, v44
	v_div_fmas_f32 v42, v42, v43, v45
	v_cmp_gt_f32_e32 vcc, s14, v34
	v_div_fixup_f32 v36, v42, v36, 1.0
	v_pk_fma_f32 v[36:37], v[36:37], v[38:39], v[40:41]
	v_cndmask_b32_e32 v34, v34, v35, vcc
	v_rsq_f32_e32 v34, v34
	v_cvt_pk_bf16_f32 v165, v36, v37
	v_lshlrev_b32_e32 v36, 16, v178
	v_and_b32_e32 v37, 0xffff0000, v178
	v_mul_f32_e32 v35, 0x45800000, v34
	v_cndmask_b32_e32 v34, v34, v35, vcc
	v_fma_f32 v22, v22, v34, v30
	v_fma_f32 v23, v23, v34, v31
	v_mul_f32_e32 v22, 0xbfb8aa3b, v22
	v_mul_f32_e32 v23, 0xbfb8aa3b, v23
	v_exp_f32_e32 v22, v22
	v_exp_f32_e32 v23, v23
	v_fma_f32 v24, v24, v34, v32
	v_fmac_f32_e32 v33, v25, v34
	v_mul_f32_e32 v24, 0xbfb8aa3b, v24
	v_pk_add_f32 v[22:23], v[22:23], 1.0 op_sel_hi:[1,0]
	v_mul_f32_e32 v25, 0xbfb8aa3b, v33
	v_div_scale_f32 v35, s[2:3], v23, v23, 1.0
	v_rcp_f32_e32 v38, v35
; template <int MI>
; DI void merge_tile(const Params& p, int layer, int rowbase, int nt, unsigned char* smem) {
;     ...
;       const float rs = rsqrtf(rowss[m0 + mi * 16] * (1.f / DM) + EPS);
; #pragma unroll
;       for (int ni = 0; ni < 4; ++ni) {
;         const float4 b4 = *(const float4*)(bg + br * DM + n0 + ni * 16);
;         const float bb[4] = {b4.x, b4.y, b4.z, b4.w};
;         float mv[4];
; #pragma unroll
;         for (int r = 0; r < 4; ++r) {
;           const float gv = acc[ni][mi][r] * rs + bb[r];
;           const float sg = 1.f / (1.f + __expf(-gv));
;           const u32 w = brp[ni][mi][r >> 1], mw = mp[ni][mi][r >> 1];
;           const float bv = __uint_as_float((r & 1) ? (w & 0xffff0000u) : (w << 16));
;           const float mo = __uint_as_float((r & 1) ? (mw & 0xffff0000u) : (mw << 16));
;           mv[r] = mo + sg * bv;
;         }
;         mp[ni][mi][0] = pack2bf(mv[0], mv[1]);
;         mp[ni][mi][1] = pack2bf(mv[2], mv[3]);
;       }
	v_exp_f32_e32 v24, v24
	v_exp_f32_e32 v25, v25
	v_lshlrev_b32_e32 v30, 16, v193
	v_fma_f32 v39, -v35, v38, 1.0
	v_fmac_f32_e32 v38, v39, v38
	v_div_scale_f32 v39, vcc, 1.0, v23, 1.0
	v_mul_f32_e32 v40, v39, v38
	v_fma_f32 v41, -v35, v40, v39
	v_fmac_f32_e32 v40, v41, v38
	v_fma_f32 v35, -v35, v40, v39
	v_div_fmas_f32 v35, v35, v38, v40
	v_div_fixup_f32 v23, v35, v23, 1.0
	v_div_scale_f32 v35, s[2:3], v22, v22, 1.0
	v_rcp_f32_e32 v38, v35
	v_pk_add_f32 v[24:25], v[24:25], 1.0 op_sel_hi:[1,0]
	v_and_b32_e32 v31, 0xffff0000, v193
	v_fma_f32 v14, v14, v34, v26
	v_fma_f32 v39, -v35, v38, 1.0
	v_fmac_f32_e32 v38, v39, v38
	v_div_scale_f32 v39, vcc, 1.0, v22, 1.0
	v_mul_f32_e32 v40, v39, v38
	v_fma_f32 v41, -v35, v40, v39
	v_fmac_f32_e32 v40, v41, v38
	v_fma_f32 v35, -v35, v40, v39
	v_div_fmas_f32 v35, v35, v38, v40
	v_div_fixup_f32 v22, v35, v22, 1.0
	v_div_scale_f32 v35, s[2:3], v25, v25, 1.0
	v_pk_fma_f32 v[22:23], v[22:23], v[30:31], v[36:37]
	v_rcp_f32_e32 v36, v35
	v_fma_f32 v15, v15, v34, v27
	v_mul_f32_e32 v14, 0xbfb8aa3b, v14
	v_mul_f32_e32 v15, 0xbfb8aa3b, v15
	v_fma_f32 v37, -v35, v36, 1.0
	v_fmac_f32_e32 v36, v37, v36
	v_div_scale_f32 v37, vcc, 1.0, v25, 1.0
	v_mul_f32_e32 v38, v37, v36
	v_fma_f32 v39, -v35, v38, v37
	v_fmac_f32_e32 v38, v39, v36
	v_fma_f32 v35, -v35, v38, v37
	v_div_fmas_f32 v35, v35, v36, v38
	v_div_fixup_f32 v25, v35, v25, 1.0
	v_div_scale_f32 v35, s[2:3], v24, v24, 1.0
	v_rcp_f32_e32 v36, v35
	v_exp_f32_e32 v14, v14
	v_exp_f32_e32 v15, v15
	v_lshlrev_b32_e32 v30, 16, v192
	v_fma_f32 v37, -v35, v36, 1.0
	v_fmac_f32_e32 v36, v37, v36
	v_div_scale_f32 v37, vcc, 1.0, v24, 1.0
	v_mul_f32_e32 v38, v37, v36
	v_pk_add_f32 v[14:15], v[14:15], 1.0 op_sel_hi:[1,0]
	v_fma_f32 v39, -v35, v38, v37
	v_div_scale_f32 v26, s[2:3], v15, v15, 1.0
	v_fmac_f32_e32 v38, v39, v36
	v_rcp_f32_e32 v27, v26
	v_fma_f32 v35, -v35, v38, v37
	v_div_fmas_f32 v35, v35, v36, v38
	v_lshlrev_b32_e32 v32, 16, v179
	v_and_b32_e32 v31, 0xffff0000, v192
	v_and_b32_e32 v33, 0xffff0000, v179
	v_div_fixup_f32 v24, v35, v24, 1.0
	v_pk_fma_f32 v[24:25], v[24:25], v[30:31], v[32:33]
	v_fma_f32 v30, -v26, v27, 1.0
	v_fmac_f32_e32 v27, v30, v27
	v_div_scale_f32 v30, vcc, 1.0, v15, 1.0
	v_mul_f32_e32 v31, v30, v27
	v_fma_f32 v32, -v26, v31, v30
	v_fmac_f32_e32 v31, v32, v27
	v_fma_f32 v26, -v26, v31, v30
	v_div_fmas_f32 v26, v26, v27, v31
	v_div_fixup_f32 v15, v26, v15, 1.0
	v_div_scale_f32 v26, s[2:3], v14, v14, 1.0
	v_rcp_f32_e32 v27, v26
	v_fma_f32 v16, v16, v34, v28
	v_fmac_f32_e32 v29, v17, v34
	v_mul_f32_e32 v16, 0xbfb8aa3b, v16
	v_fma_f32 v30, -v26, v27, 1.0
	v_fmac_f32_e32 v27, v30, v27
	v_div_scale_f32 v30, vcc, 1.0, v14, 1.0
	v_mul_f32_e32 v17, 0xbfb8aa3b, v29
	v_mul_f32_e32 v31, v30, v27
	v_exp_f32_e32 v16, v16
	v_exp_f32_e32 v17, v17
	v_fma_f32 v32, -v26, v31, v30
	v_fmac_f32_e32 v31, v32, v27
	v_fma_f32 v26, -v26, v31, v30
	v_div_fmas_f32 v26, v26, v27, v31
	v_pk_add_f32 v[16:17], v[16:17], 1.0 op_sel_hi:[1,0]
	v_div_fixup_f32 v14, v26, v14, 1.0
	v_div_scale_f32 v26, s[2:3], v17, v17, 1.0
	v_rcp_f32_e32 v27, v26
	v_fma_f32 v6, v6, v34, v18
	v_fma_f32 v7, v7, v34, v19
	v_mul_f32_e32 v6, 0xbfb8aa3b, v6
	v_fma_f32 v28, -v26, v27, 1.0
	v_fmac_f32_e32 v27, v28, v27
	v_div_scale_f32 v28, vcc, 1.0, v17, 1.0
	v_mul_f32_e32 v29, v28, v27
	v_fma_f32 v30, -v26, v29, v28
	v_fmac_f32_e32 v29, v30, v27
	v_fma_f32 v26, -v26, v29, v28
	v_div_fmas_f32 v26, v26, v27, v29
	v_div_fixup_f32 v17, v26, v17, 1.0
	v_div_scale_f32 v26, s[2:3], v16, v16, 1.0
	v_rcp_f32_e32 v27, v26
	v_mul_f32_e32 v7, 0xbfb8aa3b, v7
	v_exp_f32_e32 v6, v6
	v_exp_f32_e32 v7, v7
	v_fma_f32 v28, -v26, v27, 1.0
	v_fmac_f32_e32 v27, v28, v27
	v_div_scale_f32 v28, vcc, 1.0, v16, 1.0
	v_mul_f32_e32 v29, v28, v27
	v_pk_add_f32 v[6:7], v[6:7], 1.0 op_sel_hi:[1,0]
	v_fma_f32 v30, -v26, v29, v28
	v_div_scale_f32 v18, s[2:3], v7, v7, 1.0
	v_fmac_f32_e32 v29, v30, v27
	v_rcp_f32_e32 v19, v18
	v_fma_f32 v26, -v26, v29, v28
	v_cvt_pk_bf16_f32 v178, v22, v23
	v_cvt_pk_bf16_f32 v179, v24, v25
	v_lshlrev_b32_e32 v22, 16, v157
	v_lshlrev_b32_e32 v24, 16, v182
	v_and_b32_e32 v23, 0xffff0000, v157
	v_and_b32_e32 v25, 0xffff0000, v182
	v_div_fmas_f32 v26, v26, v27, v29
	v_pk_fma_f32 v[14:15], v[14:15], v[22:23], v[24:25]
	v_lshlrev_b32_e32 v22, 16, v155
	v_lshlrev_b32_e32 v24, 16, v183
	v_and_b32_e32 v23, 0xffff0000, v155
	v_and_b32_e32 v25, 0xffff0000, v183
	v_div_fixup_f32 v16, v26, v16, 1.0
	v_pk_fma_f32 v[16:17], v[16:17], v[22:23], v[24:25]
	v_fma_f32 v22, -v18, v19, 1.0
	v_fmac_f32_e32 v19, v22, v19
	v_div_scale_f32 v22, vcc, 1.0, v7, 1.0
	v_mul_f32_e32 v23, v22, v19
	v_fma_f32 v24, -v18, v23, v22
	v_fmac_f32_e32 v23, v24, v19
	v_fma_f32 v18, -v18, v23, v22
	v_div_fmas_f32 v18, v18, v19, v23
	v_div_fixup_f32 v7, v18, v7, 1.0
	v_div_scale_f32 v18, s[2:3], v6, v6, 1.0
	v_rcp_f32_e32 v19, v18
	v_fma_f32 v8, v8, v34, v20
	v_fmac_f32_e32 v21, v9, v34
	v_mul_f32_e32 v8, 0xbfb8aa3b, v8
	v_fma_f32 v22, -v18, v19, 1.0
	v_fmac_f32_e32 v19, v22, v19
	v_div_scale_f32 v22, vcc, 1.0, v6, 1.0
	v_mul_f32_e32 v9, 0xbfb8aa3b, v21
	v_mul_f32_e32 v23, v22, v19
	v_exp_f32_e32 v8, v8
	v_exp_f32_e32 v9, v9
	v_fma_f32 v24, -v18, v23, v22
	v_fmac_f32_e32 v23, v24, v19
	v_fma_f32 v18, -v18, v23, v22
	v_div_fmas_f32 v18, v18, v19, v23
	v_pk_add_f32 v[8:9], v[8:9], 1.0 op_sel_hi:[1,0]
; template <int MI>
; DI void merge_tile(const Params& p, int layer, int rowbase, int nt, unsigned char* smem) {
;     ...
;       const float rs = rsqrtf(rowss[m0 + mi * 16] * (1.f / DM) + EPS);
; #pragma unroll
;       for (int ni = 0; ni < 4; ++ni) {
;         const float4 b4 = *(const float4*)(bg + br * DM + n0 + ni * 16);
;         const float bb[4] = {b4.x, b4.y, b4.z, b4.w};
;         float mv[4];
; #pragma unroll
;         for (int r = 0; r < 4; ++r) {
;           const float gv = acc[ni][mi][r] * rs + bb[r];
;           const float sg = 1.f / (1.f + __expf(-gv));
;           const u32 w = brp[ni][mi][r >> 1], mw = mp[ni][mi][r >> 1];
;           const float bv = __uint_as_float((r & 1) ? (w & 0xffff0000u) : (w << 16));
;           const float mo = __uint_as_float((r & 1) ? (mw & 0xffff0000u) : (mw << 16));
;           mv[r] = mo + sg * bv;
;         }
;         mp[ni][mi][0] = pack2bf(mv[0], mv[1]);
;         mp[ni][mi][1] = pack2bf(mv[2], mv[3]);
;       }
;     }
;   }
;   int m0 = rowbase + wm * 16 * MI + lm, n0 = nt * 128 + wn * 64 + lg * 4;
;   asm volatile("" : "+v"(m0), "+v"(n0));
; #pragma unroll
;   for (int mi = 0; mi < MI; ++mi)
; #pragma unroll
;     for (int ni = 0; ni < 4; ++ni) {
;       u32x2 pk = {mp[ni][mi][0], mp[ni][mi][1]};
;       *(u32x2*)(p.merged + (size_t)(m0 + mi * 16) * DM + n0 + ni * 16) = pk;
;     }
	v_div_fixup_f32 v6, v18, v6, 1.0
	v_div_scale_f32 v18, s[2:3], v9, v9, 1.0
	v_rcp_f32_e32 v19, v18
	v_fma_f32 v2, v2, v34, v10
	v_fma_f32 v3, v3, v34, v11
	v_mul_f32_e32 v2, 0xbfb8aa3b, v2
	v_fma_f32 v20, -v18, v19, 1.0
	v_fmac_f32_e32 v19, v20, v19
	v_div_scale_f32 v20, vcc, 1.0, v9, 1.0
	v_mul_f32_e32 v21, v20, v19
	v_fma_f32 v22, -v18, v21, v20
	v_fmac_f32_e32 v21, v22, v19
	v_fma_f32 v18, -v18, v21, v20
	v_div_fmas_f32 v18, v18, v19, v21
	v_div_fixup_f32 v9, v18, v9, 1.0
	v_div_scale_f32 v18, s[2:3], v8, v8, 1.0
	v_rcp_f32_e32 v19, v18
	v_mul_f32_e32 v3, 0xbfb8aa3b, v3
	v_exp_f32_e32 v2, v2
	v_exp_f32_e32 v3, v3
	v_fma_f32 v20, -v18, v19, 1.0
	v_fmac_f32_e32 v19, v20, v19
	v_div_scale_f32 v20, vcc, 1.0, v8, 1.0
	v_mul_f32_e32 v21, v20, v19
	v_pk_add_f32 v[2:3], v[2:3], 1.0 op_sel_hi:[1,0]
	v_fma_f32 v22, -v18, v21, v20
	v_div_scale_f32 v10, s[2:3], v3, v3, 1.0
	v_fmac_f32_e32 v21, v22, v19
	v_rcp_f32_e32 v11, v10
	v_fma_f32 v18, -v18, v21, v20
	v_cvt_pk_bf16_f32 v182, v14, v15
	v_cvt_pk_bf16_f32 v183, v16, v17
	v_lshlrev_b32_e32 v14, 16, v81
	v_lshlrev_b32_e32 v16, 16, v188
	v_and_b32_e32 v15, 0xffff0000, v81
	v_and_b32_e32 v17, 0xffff0000, v188
	v_div_fmas_f32 v18, v18, v19, v21
	v_pk_fma_f32 v[6:7], v[6:7], v[14:15], v[16:17]
	v_lshlrev_b32_e32 v14, 16, v80
	v_lshlrev_b32_e32 v16, 16, v189
	v_and_b32_e32 v15, 0xffff0000, v80
	v_and_b32_e32 v17, 0xffff0000, v189
	v_div_fixup_f32 v8, v18, v8, 1.0
	v_pk_fma_f32 v[8:9], v[8:9], v[14:15], v[16:17]
	v_fma_f32 v14, -v10, v11, 1.0
	v_fmac_f32_e32 v11, v14, v11
	v_div_scale_f32 v14, vcc, 1.0, v3, 1.0
	v_mul_f32_e32 v15, v14, v11
	v_fma_f32 v16, -v10, v15, v14
	v_fmac_f32_e32 v15, v16, v11
	v_fma_f32 v10, -v10, v15, v14
	v_div_fmas_f32 v10, v10, v11, v15
	v_div_fixup_f32 v3, v10, v3, 1.0
	v_div_scale_f32 v10, s[2:3], v2, v2, 1.0
	v_rcp_f32_e32 v11, v10
	v_fma_f32 v4, v4, v34, v12
	v_fmac_f32_e32 v13, v5, v34
	v_mul_f32_e32 v4, 0xbfb8aa3b, v4
	v_fma_f32 v14, -v10, v11, 1.0
	v_fmac_f32_e32 v11, v14, v11
	v_div_scale_f32 v14, vcc, 1.0, v2, 1.0
	v_mul_f32_e32 v5, 0xbfb8aa3b, v13
	v_mul_f32_e32 v15, v14, v11
	v_exp_f32_e32 v4, v4
	v_exp_f32_e32 v5, v5
	v_fma_f32 v16, -v10, v15, v14
	v_fmac_f32_e32 v15, v16, v11
	v_fma_f32 v10, -v10, v15, v14
	v_div_fmas_f32 v10, v10, v11, v15
	v_pk_add_f32 v[4:5], v[4:5], 1.0 op_sel_hi:[1,0]
	v_div_fixup_f32 v2, v10, v2, 1.0
	v_div_scale_f32 v10, s[2:3], v5, v5, 1.0
	v_rcp_f32_e32 v11, v10
	v_cvt_pk_bf16_f32 v188, v6, v7
	v_cvt_pk_bf16_f32 v189, v8, v9
	v_lshlrev_b32_e32 v6, 16, v79
	v_fma_f32 v12, -v10, v11, 1.0
	v_fmac_f32_e32 v11, v12, v11
	v_div_scale_f32 v12, vcc, 1.0, v5, 1.0
	v_mul_f32_e32 v13, v12, v11
	v_fma_f32 v14, -v10, v13, v12
	v_fmac_f32_e32 v13, v14, v11
	v_fma_f32 v10, -v10, v13, v12
	v_div_fmas_f32 v10, v10, v11, v13
	v_div_fixup_f32 v5, v10, v5, 1.0
	v_div_scale_f32 v10, s[2:3], v4, v4, 1.0
	v_rcp_f32_e32 v11, v10
	v_lshlrev_b32_e32 v8, 16, v186
	v_and_b32_e32 v7, 0xffff0000, v79
	v_and_b32_e32 v9, 0xffff0000, v186
	v_fma_f32 v12, -v10, v11, 1.0
	v_fmac_f32_e32 v11, v12, v11
	v_div_scale_f32 v12, vcc, 1.0, v4, 1.0
	v_mul_f32_e32 v13, v12, v11
	v_fma_f32 v14, -v10, v13, v12
	v_fmac_f32_e32 v13, v14, v11
	v_fma_f32 v10, -v10, v13, v12
	v_div_fmas_f32 v10, v10, v11, v13
	v_pk_fma_f32 v[2:3], v[2:3], v[6:7], v[8:9]
	v_lshlrev_b32_e32 v6, 16, v78
	v_lshlrev_b32_e32 v8, 16, v187
	v_and_b32_e32 v7, 0xffff0000, v78
	v_and_b32_e32 v9, 0xffff0000, v187
	v_div_fixup_f32 v4, v10, v4, 1.0
	v_pk_fma_f32 v[4:5], v[4:5], v[6:7], v[8:9]
	v_cvt_pk_bf16_f32 v186, v2, v3
	v_cvt_pk_bf16_f32 v187, v4, v5
	s_cbranch_scc0 .LBB0_281
	s_mov_b64 s[2:3], 0x8000
	v_ashrrev_i32_e32 v157, 31, v156
	v_lshlrev_b64 v[2:3], 11, v[156:157]
	v_ashrrev_i32_e32 v155, 31, v154
	v_lshl_add_u64 v[2:3], s[84:85], 0, v[2:3]
	v_lshl_add_u64 v[2:3], v[154:155], 1, v[2:3]
	v_lshl_add_u64 v[4:5], v[2:3], 0, s[2:3]
	s_mov_b32 s2, 0x8000
	v_add_co_u32_e32 v6, vcc, s2, v2
	s_mov_b64 s[2:3], 0x10000
	s_nop 0
	v_addc_co_u32_e32 v7, vcc, 0, v3, vcc
	global_store_dwordx2 v[2:3], v[176:177], off
	global_store_dwordx2 v[2:3], v[180:181], off offset:32
	global_store_dwordx2 v[2:3], v[184:185], off offset:64
	global_store_dwordx2 v[2:3], v[190:191], off offset:96
	global_store_dwordx2 v[6:7], v[168:169], off
	global_store_dwordx2 v[4:5], v[170:171], off offset:32
	global_store_dwordx2 v[4:5], v[172:173], off offset:64
	global_store_dwordx2 v[4:5], v[174:175], off offset:96
	v_lshl_add_u64 v[4:5], v[2:3], 0, s[2:3]
	s_mov_b32 s2, 0x10000
	v_add_co_u32_e32 v6, vcc, s2, v2
	s_mov_b64 s[2:3], 0x18000
	s_nop 0
	v_addc_co_u32_e32 v7, vcc, 0, v3, vcc
	global_store_dwordx2 v[6:7], v[158:159], off
	global_store_dwordx2 v[4:5], v[160:161], off offset:32
	global_store_dwordx2 v[4:5], v[162:163], off offset:64
	global_store_dwordx2 v[4:5], v[164:165], off offset:96
	v_lshl_add_u64 v[4:5], v[2:3], 0, s[2:3]
	s_mov_b32 s2, 0x18000
	v_add_co_u32_e32 v2, vcc, s2, v2
	s_add_i32 s58, s58, s34
	s_add_i32 s62, s62, s63
	s_add_i32 s64, s64, s65
	v_addc_co_u32_e32 v3, vcc, 0, v3, vcc
	s_cmp_ge_i32 s58, s35
	global_store_dwordx2 v[2:3], v[178:179], off
	global_store_dwordx2 v[4:5], v[182:183], off offset:32
	global_store_dwordx2 v[4:5], v[188:189], off offset:64
	global_store_dwordx2 v[4:5], v[186:187], off offset:96
	s_cbranch_scc0 .LBB0_280

; DI f32x4 mfma16(bf16x8 a, bf16x8 b, f32x4 c) { return __builtin_amdgcn_mfma_f32_16x16x32_bf16(a, b, c, 0, 0, 0); }
; template <int MI, int NI>
; DI void gemm_kloop(const u16* Au, int lda, const u16* Bu, int ldb, int K, f32x4 (&acc)[NI][MI], unsigned char* smem) {
;     ...
;   for (int kt = 0; kt < nk; ++kt) {
;     __syncthreads();
;     if (kt + 1 < nk) {
;       SWRITE((kt + 1) & 1);
;       if (kt + 2 < nk) GLOAD((kt + 2) << 6);
;     }
;     {
;       const unsigned char* sa = smem + (kt & 1) * 65536;
;       const unsigned char* sb = sa + 32768;
; #pragma unroll
;       for (int ks = 0; ks < 2; ++ks) {
;         const int fo = ks ? fro1 : fro0;
;         bf16x8 af[MI];
; #pragma unroll
;         for (int i = 0; i < MI; ++i) af[i] = *(const bf16x8*)(sa + (wm * 16 * MI + i * 16) * 128 + fo);
; #pragma unroll
;         for (int nh = 0; nh < NI; nh += 4) {
;           bf16x8 wf[4];
; #pragma unroll
;           for (int i = 0; i < 4; ++i) wf[i] = *(const bf16x8*)(sb + (wn * 16 * NI + (nh + i) * 16) * 128 + fo);
; #pragma unroll
;           for (int ni = 0; ni < 4; ++ni)
; #pragma unroll
;             for (int mi = 0; mi < MI; ++mi) acc[nh + ni][mi] = mfma16(wf[ni], af[mi], acc[nh + ni][mi]);
;         }
.Lk_down:
	s_waitcnt vmcnt(0) lgkmcnt(0)
	s_barrier
	ds_read_b128 v[122:125], v183
	ds_read_b128 v[126:129], v183 offset:2048
	ds_read_b128 v[130:133], v183 offset:4096
	ds_read_b128 v[134:137], v183 offset:6144
	ds_read_b128 v[162:165], v227 offset:32768
	ds_read_b128 v[184:187], v227 offset:34816
	ds_read_b128 v[188:191], v227 offset:36864
	s_and_b32 s92, s95, 1
	s_xor_b32 s92, s92, 1
	s_lshl_b32 s92, s92, 16
	s_waitcnt lgkmcnt(2)
	v_mfma_f32_16x16x32_bf16 v[150:153], v[162:165], v[122:125], v[150:153]
	ds_read_b128 v[192:195], v227 offset:38912
	v_mfma_f32_16x16x32_bf16 v[118:121], v[162:165], v[126:129], v[118:121]
	v_mfma_f32_16x16x32_bf16 v[114:117], v[162:165], v[130:133], v[114:117]
	s_add_u32 m0, s92, s94
	s_nop 0
	global_load_lds_dwordx4 v255, s[88:89]
	v_mfma_f32_16x16x32_bf16 v[110:113], v[162:165], v[134:137], v[110:113]
	s_waitcnt lgkmcnt(2)
	v_mfma_f32_16x16x32_bf16 v[106:109], v[184:187], v[122:125], v[106:109]
	ds_read_b128 v[162:165], v227 offset:40960
	v_mfma_f32_16x16x32_bf16 v[102:105], v[184:187], v[126:129], v[102:105]
	ds_read_b128 v[138:141], v226
	v_mfma_f32_16x16x32_bf16 v[98:101], v[184:187], v[130:133], v[98:101]
	s_add_u32 m0, m0, 0x2000
	s_add_u32 s92, s88, 0x58000
	s_addc_u32 s93, s89, 0
	global_load_lds_dwordx4 v255, s[92:93]
	v_mfma_f32_16x16x32_bf16 v[94:97], v[184:187], v[134:137], v[94:97]
	s_waitcnt lgkmcnt(3)
	v_mfma_f32_16x16x32_bf16 v[90:93], v[188:191], v[122:125], v[90:93]
	ds_read_b128 v[184:187], v227 offset:43008
	v_mfma_f32_16x16x32_bf16 v[86:89], v[188:191], v[126:129], v[86:89]
	ds_read_b128 v[142:145], v226 offset:2048
	v_mfma_f32_16x16x32_bf16 v[82:85], v[188:191], v[130:133], v[82:85]
	s_add_u32 m0, m0, 0x2000
	s_add_u32 s92, s88, 0xb0000
	s_addc_u32 s93, s89, 0
	global_load_lds_dwordx4 v255, s[92:93]
	v_mfma_f32_16x16x32_bf16 v[70:73], v[188:191], v[134:137], v[70:73]
	s_waitcnt lgkmcnt(4)
	v_mfma_f32_16x16x32_bf16 v[66:69], v[192:195], v[122:125], v[66:69]
	ds_read_b128 v[188:191], v227 offset:45056
	v_mfma_f32_16x16x32_bf16 v[54:57], v[192:195], v[126:129], v[54:57]
	ds_read_b128 v[146:149], v226 offset:4096
	v_mfma_f32_16x16x32_bf16 v[50:53], v[192:195], v[130:133], v[50:53]
	s_add_u32 m0, m0, 0x2000
	s_add_u32 s92, s88, 0x108000
	s_addc_u32 s93, s89, 0
	global_load_lds_dwordx4 v255, s[92:93]
	v_mfma_f32_16x16x32_bf16 v[46:49], v[192:195], v[134:137], v[46:49]
	s_waitcnt lgkmcnt(5)
	v_mfma_f32_16x16x32_bf16 v[42:45], v[162:165], v[122:125], v[42:45]
	ds_read_b128 v[192:195], v227 offset:47104
	v_mfma_f32_16x16x32_bf16 v[34:37], v[162:165], v[126:129], v[34:37]
	ds_read_b128 v[154:157], v226 offset:6144
	v_mfma_f32_16x16x32_bf16 v[30:33], v[162:165], v[130:133], v[30:33]
	s_add_u32 m0, m0, 0x2000
	s_nop 0
	global_load_lds_dwordx4 v255, s[90:91]
	v_mfma_f32_16x16x32_bf16 v[26:29], v[162:165], v[134:137], v[26:29]
	s_waitcnt lgkmcnt(5)
	v_mfma_f32_16x16x32_bf16 v[22:25], v[184:187], v[122:125], v[22:25]
	ds_read_b128 v[162:165], v254 offset:32768
	v_mfma_f32_16x16x32_bf16 v[18:21], v[184:187], v[126:129], v[18:21]
	v_mfma_f32_16x16x32_bf16 v[14:17], v[184:187], v[130:133], v[14:17]
	s_add_u32 m0, m0, 0x2000
	s_add_u32 s92, s90, 0x58000
	s_addc_u32 s93, s91, 0
	global_load_lds_dwordx4 v255, s[92:93]
	v_mfma_f32_16x16x32_bf16 v[10:13], v[184:187], v[134:137], v[10:13]
	s_waitcnt lgkmcnt(4)
	v_mfma_f32_16x16x32_bf16 v[6:9], v[188:191], v[122:125], v[6:9]
	ds_read_b128 v[184:187], v254 offset:34816
	v_mfma_f32_16x16x32_bf16 v[2:5], v[188:191], v[126:129], v[2:5]
	v_mfma_f32_16x16x32_bf16 v[38:41], v[188:191], v[130:133], v[38:41]
	s_add_u32 m0, m0, 0x2000
	s_add_u32 s92, s90, 0xb0000
	s_addc_u32 s93, s91, 0
	global_load_lds_dwordx4 v255, s[92:93]
	v_mfma_f32_16x16x32_bf16 v[62:65], v[188:191], v[134:137], v[62:65]
	s_waitcnt lgkmcnt(3)
	v_mfma_f32_16x16x32_bf16 v[78:81], v[192:195], v[122:125], v[78:81]
	ds_read_b128 v[188:191], v254 offset:36864
	v_mfma_f32_16x16x32_bf16 v[74:77], v[192:195], v[126:129], v[74:77]
	v_mfma_f32_16x16x32_bf16 v[58:61], v[192:195], v[130:133], v[58:61]
	s_add_u32 m0, m0, 0x2000
	s_add_u32 s92, s90, 0x108000
	s_addc_u32 s93, s91, 0
	global_load_lds_dwordx4 v255, s[92:93]
	v_mfma_f32_16x16x32_bf16 v[158:161], v[192:195], v[134:137], v[158:161]
	s_waitcnt lgkmcnt(2)
	v_mfma_f32_16x16x32_bf16 v[150:153], v[162:165], v[138:141], v[150:153]
	ds_read_b128 v[192:195], v254 offset:38912
	v_mfma_f32_16x16x32_bf16 v[118:121], v[162:165], v[142:145], v[118:121]
	v_mfma_f32_16x16x32_bf16 v[114:117], v[162:165], v[146:149], v[114:117]
	v_mfma_f32_16x16x32_bf16 v[110:113], v[162:165], v[154:157], v[110:113]
	s_waitcnt lgkmcnt(2)
	v_mfma_f32_16x16x32_bf16 v[106:109], v[184:187], v[138:141], v[106:109]
	ds_read_b128 v[162:165], v254 offset:40960
	v_mfma_f32_16x16x32_bf16 v[102:105], v[184:187], v[142:145], v[102:105]
	v_mfma_f32_16x16x32_bf16 v[98:101], v[184:187], v[146:149], v[98:101]
	v_mfma_f32_16x16x32_bf16 v[94:97], v[184:187], v[154:157], v[94:97]
	s_waitcnt lgkmcnt(2)
	v_mfma_f32_16x16x32_bf16 v[90:93], v[188:191], v[138:141], v[90:93]
	ds_read_b128 v[184:187], v254 offset:43008
	v_mfma_f32_16x16x32_bf16 v[86:89], v[188:191], v[142:145], v[86:89]
	v_mfma_f32_16x16x32_bf16 v[82:85], v[188:191], v[146:149], v[82:85]
	v_mfma_f32_16x16x32_bf16 v[70:73], v[188:191], v[154:157], v[70:73]
	s_waitcnt lgkmcnt(2)
	v_mfma_f32_16x16x32_bf16 v[66:69], v[192:195], v[138:141], v[66:69]
	ds_read_b128 v[188:191], v254 offset:45056
	v_mfma_f32_16x16x32_bf16 v[54:57], v[192:195], v[142:145], v[54:57]
	v_mfma_f32_16x16x32_bf16 v[50:53], v[192:195], v[146:149], v[50:53]
	v_mfma_f32_16x16x32_bf16 v[46:49], v[192:195], v[154:157], v[46:49]
	s_waitcnt lgkmcnt(2)
; DI f32x4 mfma16(bf16x8 a, bf16x8 b, f32x4 c) { return __builtin_amdgcn_mfma_f32_16x16x32_bf16(a, b, c, 0, 0, 0); }
; template <int MI, int NI>
; DI void gemm_kloop(const u16* Au, int lda, const u16* Bu, int ldb, int K, f32x4 (&acc)[NI][MI], unsigned char* smem) {
;     ...
;   for (int kt = 0; kt < nk; ++kt) {
;     __syncthreads();
;     if (kt + 1 < nk) {
;       SWRITE((kt + 1) & 1);
;       if (kt + 2 < nk) GLOAD((kt + 2) << 6);
;     }
;     {
;       const unsigned char* sa = smem + (kt & 1) * 65536;
;       const unsigned char* sb = sa + 32768;
; #pragma unroll
;       for (int ks = 0; ks < 2; ++ks) {
;         const int fo = ks ? fro1 : fro0;
;         bf16x8 af[MI];
; #pragma unroll
;         for (int i = 0; i < MI; ++i) af[i] = *(const bf16x8*)(sa + (wm * 16 * MI + i * 16) * 128 + fo);
; #pragma unroll
;         for (int nh = 0; nh < NI; nh += 4) {
;           bf16x8 wf[4];
; #pragma unroll
;           for (int i = 0; i < 4; ++i) wf[i] = *(const bf16x8*)(sb + (wn * 16 * NI + (nh + i) * 16) * 128 + fo);
; #pragma unroll
;           for (int ni = 0; ni < 4; ++ni)
; #pragma unroll
;             for (int mi = 0; mi < MI; ++mi) acc[nh + ni][mi] = mfma16(wf[ni], af[mi], acc[nh + ni][mi]);
;         }
;       }
;     }
;   }
	v_mfma_f32_16x16x32_bf16 v[42:45], v[162:165], v[138:141], v[42:45]
	ds_read_b128 v[192:195], v254 offset:47104
	v_mfma_f32_16x16x32_bf16 v[34:37], v[162:165], v[142:145], v[34:37]
	v_mfma_f32_16x16x32_bf16 v[30:33], v[162:165], v[146:149], v[30:33]
	v_mfma_f32_16x16x32_bf16 v[26:29], v[162:165], v[154:157], v[26:29]
	s_waitcnt lgkmcnt(2)
	v_mfma_f32_16x16x32_bf16 v[22:25], v[184:187], v[138:141], v[22:25]
	v_mfma_f32_16x16x32_bf16 v[18:21], v[184:187], v[142:145], v[18:21]
	v_mfma_f32_16x16x32_bf16 v[14:17], v[184:187], v[146:149], v[14:17]
	v_mfma_f32_16x16x32_bf16 v[10:13], v[184:187], v[154:157], v[10:13]
	s_waitcnt lgkmcnt(1)
	v_mfma_f32_16x16x32_bf16 v[6:9], v[188:191], v[138:141], v[6:9]
	v_mfma_f32_16x16x32_bf16 v[2:5], v[188:191], v[142:145], v[2:5]
	v_mfma_f32_16x16x32_bf16 v[38:41], v[188:191], v[146:149], v[38:41]
	v_mfma_f32_16x16x32_bf16 v[62:65], v[188:191], v[154:157], v[62:65]
	s_waitcnt lgkmcnt(0)
	v_mfma_f32_16x16x32_bf16 v[78:81], v[192:195], v[138:141], v[78:81]
	v_mfma_f32_16x16x32_bf16 v[74:77], v[192:195], v[142:145], v[74:77]
	v_mfma_f32_16x16x32_bf16 v[58:61], v[192:195], v[146:149], v[58:61]
	v_mfma_f32_16x16x32_bf16 v[158:161], v[192:195], v[154:157], v[158:161]
	v_xor_b32_e32 v183, 0x10000, v183
	v_xor_b32_e32 v226, 0x10000, v226
	v_xor_b32_e32 v227, 0x10000, v227
	v_xor_b32_e32 v254, 0x10000, v254
	s_add_u32 s88, s88, 0x80
	s_addc_u32 s89, s89, 0
	s_add_u32 s90, s90, 0x80
	s_addc_u32 s91, s91, 0
	s_add_u32 s95, s95, 1
	s_cmp_lg_u32 s95, 42
	s_cbranch_scc1 .Lk_down
	s_waitcnt vmcnt(0)
	s_barrier
	s_add_u32 m0, s94, 0x10000
	s_nop 0
	global_load_lds_dwordx4 v255, s[88:89]
	s_add_u32 m0, m0, 0x2000
	s_add_u32 s92, s88, 0x58000
	s_addc_u32 s93, s89, 0
	global_load_lds_dwordx4 v255, s[92:93]
	s_add_u32 m0, m0, 0x2000
	s_add_u32 s92, s88, 0xb0000
	s_addc_u32 s93, s89, 0
	global_load_lds_dwordx4 v255, s[92:93]
	s_add_u32 m0, m0, 0x2000
	s_add_u32 s92, s88, 0x108000
	s_addc_u32 s93, s89, 0
	global_load_lds_dwordx4 v255, s[92:93]
	s_add_u32 m0, m0, 0x2000
	s_nop 0
	global_load_lds_dwordx4 v255, s[90:91]
	s_add_u32 m0, m0, 0x2000
	s_add_u32 s92, s90, 0x58000
	s_addc_u32 s93, s91, 0
	global_load_lds_dwordx4 v255, s[92:93]
	s_add_u32 m0, m0, 0x2000
	s_add_u32 s92, s90, 0xb0000
	s_addc_u32 s93, s91, 0
	global_load_lds_dwordx4 v255, s[92:93]
	s_add_u32 m0, m0, 0x2000
	s_add_u32 s92, s90, 0x108000
	s_addc_u32 s93, s91, 0
	global_load_lds_dwordx4 v255, s[92:93]
	v_add_u32_e32 v154, v181, v180
	ds_read_b128 v[122:125], v154 offset:32768
	v_add_u32_e32 v146, v179, v180
	ds_read_b128 v[126:129], v146
	ds_read_b128 v[130:133], v146 offset:2048
	ds_read_b128 v[134:137], v154 offset:34816
	ds_read_b128 v[142:145], v146 offset:4096
	ds_read_b128 v[146:149], v146 offset:6144
	s_waitcnt lgkmcnt(4)
	v_mfma_f32_16x16x32_bf16 v[138:141], v[122:125], v[126:129], v[150:153]
	s_nop 2
	v_add_u32_e32 v150, v179, v178
	v_or_b32_e32 v225, 0x18000, v181
	v_add_u32_e32 v192, v225, v180
	s_waitcnt lgkmcnt(3)
	v_mfma_f32_16x16x32_bf16 v[118:121], v[122:125], v[130:133], v[118:121]
	v_add_u32_e32 v179, 0x10000, v179
	v_add_u32_e32 v225, v225, v178
	s_waitcnt lgkmcnt(1)
	v_mfma_f32_16x16x32_bf16 v[114:117], v[122:125], v[142:145], v[114:117]
	s_waitcnt lgkmcnt(0)
	v_mfma_f32_16x16x32_bf16 v[110:113], v[122:125], v[146:149], v[110:113]
	v_mfma_f32_16x16x32_bf16 v[106:109], v[134:137], v[126:129], v[106:109]
	v_mfma_f32_16x16x32_bf16 v[102:105], v[134:137], v[130:133], v[102:105]
	v_mfma_f32_16x16x32_bf16 v[98:101], v[134:137], v[142:145], v[98:101]
	v_mfma_f32_16x16x32_bf16 v[94:97], v[134:137], v[146:149], v[94:97]
	ds_read_b128 v[122:125], v154 offset:36864
	ds_read_b128 v[134:137], v154 offset:38912
	s_waitcnt lgkmcnt(1)
	v_mfma_f32_16x16x32_bf16 v[90:93], v[122:125], v[126:129], v[90:93]
	v_mfma_f32_16x16x32_bf16 v[86:89], v[122:125], v[130:133], v[86:89]
	v_mfma_f32_16x16x32_bf16 v[82:85], v[122:125], v[142:145], v[82:85]
	v_mfma_f32_16x16x32_bf16 v[70:73], v[122:125], v[146:149], v[70:73]
	s_waitcnt lgkmcnt(0)
	v_mfma_f32_16x16x32_bf16 v[66:69], v[134:137], v[126:129], v[66:69]
	v_mfma_f32_16x16x32_bf16 v[54:57], v[134:137], v[130:133], v[54:57]
	v_mfma_f32_16x16x32_bf16 v[50:53], v[134:137], v[142:145], v[50:53]
	v_mfma_f32_16x16x32_bf16 v[46:49], v[134:137], v[146:149], v[46:49]
	ds_read_b128 v[122:125], v154 offset:40960
	ds_read_b128 v[134:137], v154 offset:43008
	s_waitcnt lgkmcnt(1)
	v_mfma_f32_16x16x32_bf16 v[42:45], v[122:125], v[126:129], v[42:45]
	v_mfma_f32_16x16x32_bf16 v[34:37], v[122:125], v[130:133], v[34:37]
	v_mfma_f32_16x16x32_bf16 v[30:33], v[122:125], v[142:145], v[30:33]
	v_mfma_f32_16x16x32_bf16 v[26:29], v[122:125], v[146:149], v[26:29]
	s_waitcnt lgkmcnt(0)
	v_mfma_f32_16x16x32_bf16 v[22:25], v[134:137], v[126:129], v[22:25]
	v_mfma_f32_16x16x32_bf16 v[18:21], v[134:137], v[130:133], v[18:21]
	v_mfma_f32_16x16x32_bf16 v[14:17], v[134:137], v[142:145], v[14:17]
	v_mfma_f32_16x16x32_bf16 v[10:13], v[134:137], v[146:149], v[10:13]
	ds_read_b128 v[122:125], v154 offset:45056
	ds_read_b128 v[134:137], v154 offset:47104
	v_add_u32_e32 v154, v181, v178
	s_waitcnt lgkmcnt(1)
	v_mfma_f32_16x16x32_bf16 v[6:9], v[122:125], v[126:129], v[6:9]
	v_mfma_f32_16x16x32_bf16 v[2:5], v[122:125], v[130:133], v[2:5]
	v_mfma_f32_16x16x32_bf16 v[38:41], v[122:125], v[142:145], v[38:41]
	v_mfma_f32_16x16x32_bf16 v[62:65], v[122:125], v[146:149], v[62:65]
	ds_read_b128 v[122:125], v154 offset:32768
	s_waitcnt lgkmcnt(1)
; DI f32x4 mfma16(bf16x8 a, bf16x8 b, f32x4 c) { return __builtin_amdgcn_mfma_f32_16x16x32_bf16(a, b, c, 0, 0, 0); }
; template <int MI, int NI>
; DI void gemm_kloop(const u16* Au, int lda, const u16* Bu, int ldb, int K, f32x4 (&acc)[NI][MI], unsigned char* smem) {
;     ...
;       const unsigned char* sa = smem + (kt & 1) * 65536;
;       const unsigned char* sb = sa + 32768;
; #pragma unroll
;       for (int ks = 0; ks < 2; ++ks) {
;         const int fo = ks ? fro1 : fro0;
;         bf16x8 af[MI];
; #pragma unroll
;         for (int i = 0; i < MI; ++i) af[i] = *(const bf16x8*)(sa + (wm * 16 * MI + i * 16) * 128 + fo);
; #pragma unroll
;         for (int nh = 0; nh < NI; nh += 4) {
;           bf16x8 wf[4];
; #pragma unroll
;           for (int i = 0; i < 4; ++i) wf[i] = *(const bf16x8*)(sb + (wn * 16 * NI + (nh + i) * 16) * 128 + fo);
; #pragma unroll
;           for (int ni = 0; ni < 4; ++ni)
; #pragma unroll
;             for (int mi = 0; mi < MI; ++mi) acc[nh + ni][mi] = mfma16(wf[ni], af[mi], acc[nh + ni][mi]);
;         }
;       }
;     }
;   }
	v_mfma_f32_16x16x32_bf16 v[78:81], v[134:137], v[126:129], v[78:81]
	v_mfma_f32_16x16x32_bf16 v[74:77], v[134:137], v[130:133], v[74:77]
	v_mfma_f32_16x16x32_bf16 v[58:61], v[134:137], v[142:145], v[58:61]
	v_mfma_f32_16x16x32_bf16 v[126:129], v[134:137], v[146:149], v[158:161]
	ds_read_b128 v[130:133], v150
	ds_read_b128 v[134:137], v150 offset:2048
	ds_read_b128 v[142:145], v154 offset:34816
	ds_read_b128 v[146:149], v150 offset:4096
	ds_read_b128 v[150:153], v150 offset:6144
	s_waitcnt lgkmcnt(4)
	v_mfma_f32_16x16x32_bf16 v[138:141], v[122:125], v[130:133], v[138:141]
	s_waitcnt lgkmcnt(3)
	v_mfma_f32_16x16x32_bf16 v[118:121], v[122:125], v[134:137], v[118:121]
	s_waitcnt lgkmcnt(1)
	v_mfma_f32_16x16x32_bf16 v[114:117], v[122:125], v[146:149], v[114:117]
	s_waitcnt lgkmcnt(0)
	v_mfma_f32_16x16x32_bf16 v[110:113], v[122:125], v[150:153], v[110:113]
	v_mfma_f32_16x16x32_bf16 v[106:109], v[142:145], v[130:133], v[106:109]
	v_mfma_f32_16x16x32_bf16 v[102:105], v[142:145], v[134:137], v[102:105]
	v_mfma_f32_16x16x32_bf16 v[98:101], v[142:145], v[146:149], v[98:101]
	v_mfma_f32_16x16x32_bf16 v[94:97], v[142:145], v[150:153], v[94:97]
	ds_read_b128 v[122:125], v154 offset:36864
	ds_read_b128 v[142:145], v154 offset:38912
	s_waitcnt lgkmcnt(1)
	v_mfma_f32_16x16x32_bf16 v[90:93], v[122:125], v[130:133], v[90:93]
	v_mfma_f32_16x16x32_bf16 v[86:89], v[122:125], v[134:137], v[86:89]
	v_mfma_f32_16x16x32_bf16 v[82:85], v[122:125], v[146:149], v[82:85]
	v_mfma_f32_16x16x32_bf16 v[70:73], v[122:125], v[150:153], v[70:73]
	s_waitcnt lgkmcnt(0)
	v_mfma_f32_16x16x32_bf16 v[66:69], v[142:145], v[130:133], v[66:69]
	v_mfma_f32_16x16x32_bf16 v[54:57], v[142:145], v[134:137], v[54:57]
	v_mfma_f32_16x16x32_bf16 v[50:53], v[142:145], v[146:149], v[50:53]
	v_mfma_f32_16x16x32_bf16 v[46:49], v[142:145], v[150:153], v[46:49]
	ds_read_b128 v[122:125], v154 offset:40960
	ds_read_b128 v[142:145], v154 offset:43008
	s_waitcnt lgkmcnt(1)
	v_mfma_f32_16x16x32_bf16 v[42:45], v[122:125], v[130:133], v[42:45]
	v_mfma_f32_16x16x32_bf16 v[34:37], v[122:125], v[134:137], v[34:37]
	v_mfma_f32_16x16x32_bf16 v[30:33], v[122:125], v[146:149], v[30:33]
	v_mfma_f32_16x16x32_bf16 v[26:29], v[122:125], v[150:153], v[26:29]
	s_waitcnt lgkmcnt(0)
	v_mfma_f32_16x16x32_bf16 v[22:25], v[142:145], v[130:133], v[22:25]
	v_mfma_f32_16x16x32_bf16 v[18:21], v[142:145], v[134:137], v[18:21]
	v_mfma_f32_16x16x32_bf16 v[14:17], v[142:145], v[146:149], v[14:17]
	v_mfma_f32_16x16x32_bf16 v[10:13], v[142:145], v[150:153], v[10:13]
	ds_read_b128 v[122:125], v154 offset:45056
	ds_read_b128 v[142:145], v154 offset:47104
	s_waitcnt vmcnt(0) lgkmcnt(0)
	s_barrier
	v_mfma_f32_16x16x32_bf16 v[6:9], v[122:125], v[130:133], v[6:9]
	v_mfma_f32_16x16x32_bf16 v[2:5], v[122:125], v[134:137], v[2:5]
	v_mfma_f32_16x16x32_bf16 v[38:41], v[122:125], v[146:149], v[38:41]
	v_mfma_f32_16x16x32_bf16 v[62:65], v[122:125], v[150:153], v[62:65]
	ds_read_b128 v[122:125], v192
	v_mfma_f32_16x16x32_bf16 v[126:129], v[142:145], v[150:153], v[126:129]
	v_add_u32_e32 v150, v179, v180
	v_mfma_f32_16x16x32_bf16 v[78:81], v[142:145], v[130:133], v[78:81]
	v_mfma_f32_16x16x32_bf16 v[74:77], v[142:145], v[134:137], v[74:77]
	v_mfma_f32_16x16x32_bf16 v[58:61], v[142:145], v[146:149], v[58:61]
	ds_read_b128 v[130:133], v150
	ds_read_b128 v[134:137], v150 offset:2048
	ds_read_b128 v[142:145], v192 offset:2048
	ds_read_b128 v[146:149], v150 offset:4096
	ds_read_b128 v[150:153], v150 offset:6144
	s_waitcnt lgkmcnt(4)
	v_mfma_f32_16x16x32_bf16 v[138:141], v[122:125], v[130:133], v[138:141]
	s_waitcnt lgkmcnt(3)
	v_mfma_f32_16x16x32_bf16 v[118:121], v[122:125], v[134:137], v[118:121]
	s_waitcnt lgkmcnt(1)
	v_mfma_f32_16x16x32_bf16 v[114:117], v[122:125], v[146:149], v[114:117]
	s_waitcnt lgkmcnt(0)
	v_mfma_f32_16x16x32_bf16 v[110:113], v[122:125], v[150:153], v[110:113]
	v_mfma_f32_16x16x32_bf16 v[106:109], v[142:145], v[130:133], v[106:109]
	v_mfma_f32_16x16x32_bf16 v[102:105], v[142:145], v[134:137], v[102:105]
	v_mfma_f32_16x16x32_bf16 v[98:101], v[142:145], v[146:149], v[98:101]
	v_mfma_f32_16x16x32_bf16 v[142:145], v[142:145], v[150:153], v[94:97]
	s_nop 2
	ds_read_b128 v[94:97], v192 offset:4096
	ds_read_b128 v[122:125], v192 offset:6144
	s_waitcnt lgkmcnt(1)
	v_mfma_f32_16x16x32_bf16 v[154:157], v[94:97], v[130:133], v[90:93]
	s_waitcnt lgkmcnt(0)
	v_mfma_f32_16x16x32_bf16 v[158:161], v[122:125], v[134:137], v[54:57]
	s_nop 2
	ds_read_b128 v[54:57], v192 offset:8192
	ds_read_b128 v[90:93], v192 offset:10240
	s_waitcnt lgkmcnt(0)
	v_mfma_f32_16x16x32_bf16 v[184:187], v[90:93], v[134:137], v[18:21]
	v_mfma_f32_16x16x32_bf16 v[188:191], v[90:93], v[146:149], v[14:17]
	s_nop 2
	ds_read_b128 v[14:17], v192 offset:12288
	ds_read_b128 v[18:21], v192 offset:14336
	s_waitcnt lgkmcnt(1)
	v_mfma_f32_16x16x32_bf16 v[6:9], v[14:17], v[130:133], v[6:9]
	v_mfma_f32_16x16x32_bf16 v[2:5], v[14:17], v[134:137], v[2:5]
	v_mfma_f32_16x16x32_bf16 v[38:41], v[14:17], v[146:149], v[38:41]
	v_mfma_f32_16x16x32_bf16 v[192:195], v[14:17], v[150:153], v[62:65]
	ds_read_b128 v[14:17], v225
	v_mfma_f32_16x16x32_bf16 v[180:183], v[90:93], v[130:133], v[22:25]
	s_nop 2
	v_add_u32_e32 v22, v179, v178
	v_mfma_f32_16x16x32_bf16 v[86:89], v[94:97], v[134:137], v[86:89]
	v_mfma_f32_16x16x32_bf16 v[82:85], v[94:97], v[146:149], v[82:85]
	v_mfma_f32_16x16x32_bf16 v[70:73], v[94:97], v[150:153], v[70:73]
	v_mfma_f32_16x16x32_bf16 v[66:69], v[122:125], v[130:133], v[66:69]
	v_mfma_f32_16x16x32_bf16 v[50:53], v[122:125], v[146:149], v[50:53]
	v_mfma_f32_16x16x32_bf16 v[46:49], v[122:125], v[150:153], v[46:49]
	v_mfma_f32_16x16x32_bf16 v[42:45], v[54:57], v[130:133], v[42:45]
	v_mfma_f32_16x16x32_bf16 v[34:37], v[54:57], v[134:137], v[34:37]
	v_mfma_f32_16x16x32_bf16 v[162:165], v[54:57], v[146:149], v[30:33]
	v_mfma_f32_16x16x32_bf16 v[168:171], v[54:57], v[150:153], v[26:29]
	v_mfma_f32_16x16x32_bf16 v[10:13], v[90:93], v[150:153], v[10:13]
	s_waitcnt lgkmcnt(1)
; DI float* hrow_w(const Params& p, int gr) {
;   int b = gr / TP, t = gr - b * TP;
;   if (t >= NMETA && t < TREAL) return p.out + ((size_t)(b * SEQ + t - NMETA)) * DM;
;   int s = t < NMETA ? t : t - TREAL + NMETA;
;   return p.side + ((size_t)(b * 128 + s)) * DM;
; }
; template <int MI, int NI>
; DI void resid_epilogue(const Params& p, int from_x, const f32x4 (&acc)[NI][MI], int row0, int n0, float* rowss_next, bool last, int lm, int lg) {
; #pragma unroll
;   for (int mi = 0; mi < MI; ++mi) {
;     const int m = row0 + mi * 16 + lm;
;     const float* hr = hrow_r(p, from_x == 1 ? 0 : 1, m);
;     float* hw = hrow_w(p, m);
;     u16* hbr = p.hb + (size_t)m * DM;
;     float ss = 0.f;
; #pragma unroll
;     for (int ni = 0; ni < NI; ++ni) {
;       const int n = n0 + ni * 16 + lg * 4;
;       float4 h;
;       if (from_x >= 2) {
;         const u32x2 pk = *(const u32x2*)(hbr + n);
;         h = make_float4(__uint_as_float(pk[0] << 16), __uint_as_float(pk[0] & 0xffff0000u), __uint_as_float(pk[1] << 16), __uint_as_float(pk[1] & 0xffff0000u));
;       } else h = *(const float4*)(hr + n);
;       h.x += acc[ni][mi][0]; h.y += acc[ni][mi][1]; h.z += acc[ni][mi][2]; h.w += acc[ni][mi][3];
;       if (last) *(float4*)(hw + n) = h;
	v_mfma_f32_16x16x32_bf16 v[130:133], v[18:21], v[130:133], v[78:81]
	v_mfma_f32_16x16x32_bf16 v[134:137], v[18:21], v[134:137], v[74:77]
	v_mfma_f32_16x16x32_bf16 v[146:149], v[18:21], v[146:149], v[58:61]
	v_mfma_f32_16x16x32_bf16 v[150:153], v[18:21], v[150:153], v[126:129]
	ds_read_b128 v[226:229], v22
	ds_read_b128 v[230:233], v22 offset:2048
	ds_read_b128 v[18:21], v225 offset:2048
	s_waitcnt lgkmcnt(2)
	v_mfma_f32_16x16x32_bf16 v[126:129], v[14:17], v[226:229], v[138:141]
	s_nop 2
	ds_read_b128 v[138:141], v22 offset:4096
	ds_read_b128 v[234:237], v22 offset:6144
	s_waitcnt lgkmcnt(3)
	v_mfma_f32_16x16x32_bf16 v[94:97], v[14:17], v[230:233], v[118:121]
	s_waitcnt lgkmcnt(1)
	v_mfma_f32_16x16x32_bf16 v[62:65], v[14:17], v[138:141], v[114:117]
	s_waitcnt lgkmcnt(0)
	v_mfma_f32_16x16x32_bf16 v[30:33], v[14:17], v[234:237], v[110:113]
	v_mfma_f32_16x16x32_bf16 v[122:125], v[18:21], v[226:229], v[106:109]
	v_mfma_f32_16x16x32_bf16 v[90:93], v[18:21], v[230:233], v[102:105]
	v_mfma_f32_16x16x32_bf16 v[58:61], v[18:21], v[138:141], v[98:101]
	v_mfma_f32_16x16x32_bf16 v[26:29], v[18:21], v[234:237], v[142:145]
	ds_read_b128 v[14:17], v225 offset:4096
	ds_read_b128 v[18:21], v225 offset:6144
	s_waitcnt lgkmcnt(1)
	v_mfma_f32_16x16x32_bf16 v[118:121], v[14:17], v[226:229], v[154:157]
	v_mfma_f32_16x16x32_bf16 v[86:89], v[14:17], v[230:233], v[86:89]
	v_mfma_f32_16x16x32_bf16 v[54:57], v[14:17], v[138:141], v[82:85]
	v_mfma_f32_16x16x32_bf16 v[22:25], v[14:17], v[234:237], v[70:73]
	s_waitcnt lgkmcnt(0)
	v_mfma_f32_16x16x32_bf16 v[114:117], v[18:21], v[226:229], v[66:69]
	ds_read_b128 v[14:17], v225 offset:8192
	s_nop 1
	ds_read_b128 v[66:69], v225 offset:10240
	s_waitcnt lgkmcnt(1)
	v_mfma_f32_16x16x32_bf16 v[78:81], v[14:17], v[230:233], v[34:37]
	s_nop 2
	ds_read_b128 v[34:37], v225 offset:12288
	ds_read_b128 v[142:145], v225 offset:14336
	s_waitcnt lgkmcnt(0)
	s_barrier
	v_mfma_f32_16x16x32_bf16 v[98:101], v[142:145], v[226:229], v[130:133]
	s_nop 2
	v_add_u32_e32 v130, s43, v176
	v_mfma_f32_16x16x32_bf16 v[70:73], v[34:37], v[230:233], v[2:5]
	s_nop 2
	v_mul_hi_i32 v2, v130, s81
	v_lshrrev_b32_e32 v3, 31, v2
	v_ashrrev_i32_e32 v2, 10, v2
	v_mfma_f32_16x16x32_bf16 v[82:85], v[18:21], v[230:233], v[158:161]
	v_add_u32_e32 v131, v2, v3
	v_mad_i32_i24 v133, v131, s82, v130
	v_add_u32_e32 v132, -16, v133
	v_mfma_f32_16x16x32_bf16 v[50:53], v[18:21], v[138:141], v[50:53]
	v_cmp_lt_u32_e32 vcc, s83, v132
	v_mfma_f32_16x16x32_bf16 v[18:21], v[18:21], v[234:237], v[46:49]
	v_mfma_f32_16x16x32_bf16 v[110:113], v[14:17], v[226:229], v[42:45]
	v_mfma_f32_16x16x32_bf16 v[46:49], v[14:17], v[138:141], v[162:165]
	v_mfma_f32_16x16x32_bf16 v[14:17], v[14:17], v[234:237], v[168:171]
	v_mfma_f32_16x16x32_bf16 v[106:109], v[66:69], v[226:229], v[180:183]
	v_mfma_f32_16x16x32_bf16 v[74:77], v[66:69], v[230:233], v[184:187]
	v_mfma_f32_16x16x32_bf16 v[42:45], v[66:69], v[138:141], v[188:191]
	v_mfma_f32_16x16x32_bf16 v[10:13], v[66:69], v[234:237], v[10:13]
	v_mfma_f32_16x16x32_bf16 v[102:105], v[34:37], v[226:229], v[6:9]
	v_mfma_f32_16x16x32_bf16 v[38:41], v[34:37], v[138:141], v[38:41]
	v_mfma_f32_16x16x32_bf16 v[6:9], v[34:37], v[234:237], v[192:195]
	v_mfma_f32_16x16x32_bf16 v[66:69], v[142:145], v[230:233], v[134:137]
	v_mfma_f32_16x16x32_bf16 v[34:37], v[142:145], v[138:141], v[146:149]
	v_mfma_f32_16x16x32_bf16 v[2:5], v[142:145], v[234:237], v[150:153]
	s_load_dwordx2 s[56:57], s[0:1], 0xc8
	s_load_dwordx2 s[58:59], s[0:1], 0xd8
	s_lshr_b32 s2, s31, 4
	s_lshl_b32 s2, s2, 2
	s_and_b32 s3, s31, 3
	s_or_b32 s2, s2, s3
	s_lshl_b32 s2, s2, 8
	s_lshr_b32 s3, s31, 2
	s_and_b32 s3, s3, 3
	s_lshl_b32 s3, s3, 8
	v_add_u32_e32 v130, s2, v176
	v_or_b32_e32 v131, s3, v177
	s_and_b64 vcc, exec, s[6:7]
	s_cbranch_vccnz .Lre_down_T
	s_load_dwordx2 s[60:61], s[0:1], 0xc0
	s_waitcnt lgkmcnt(0)
	v_add_u32_e32 v168, 0, v130
	v_lshlrev_b32_e32 v168, 11, v168
	v_lshl_add_u32 v242, v131, 1, v168
	v_add_u32_e32 v168, 0, v130
	v_mul_hi_i32 v169, v168, s81
	v_lshrrev_b32_e32 v170, 31, v169
	v_ashrrev_i32_e32 v169, 10, v169
	v_add_u32_e32 v169, v169, v170
	v_mad_i32_i24 v170, v169, s82, v168
	v_add_u32_e32 v171, -16, v170
	v_cmp_lt_u32_e32 vcc, s83, v171
	v_lshl_add_u32 v171, v169, 12, v171
	v_add_u32_e32 v168, 0xfffff000, v170
	v_cmp_gt_i32_e64 s[2:3], 16, v170
	s_nop 1
	v_cndmask_b32_e64 v168, v168, v170, s[2:3]
	v_lshl_add_u32 v168, v169, 7, v168
	v_cndmask_b32_e32 v168, v171, v168, vcc
	v_mov_b32_e32 v169, s60
	v_mov_b32_e32 v170, s58
	v_cndmask_b32_e32 v248, v169, v170, vcc
	v_mov_b32_e32 v169, s61
	v_mov_b32_e32 v170, s59
	v_cndmask_b32_e32 v249, v169, v170, vcc
	v_lshlrev_b32_e32 v168, 12, v168
	v_lshl_add_u32 v168, v131, 2, v168
	v_add_co_u32_e32 v248, vcc, v248, v168
	s_nop 1
	v_addc_co_u32_e32 v249, vcc, 0, v249, vcc
	global_load_dwordx2 v[132:133], v242, s[56:57] offset:0
	global_load_dwordx2 v[134:135], v242, s[56:57] offset:32
	global_load_dwordx2 v[136:137], v242, s[56:57] offset:64
	global_load_dwordx2 v[138:139], v242, s[56:57] offset:96
	global_load_dwordx2 v[140:141], v242, s[56:57] offset:128
	global_load_dwordx2 v[142:143], v242, s[56:57] offset:160
	global_load_dwordx2 v[144:145], v242, s[56:57] offset:192
	global_load_dwordx2 v[146:147], v242, s[56:57] offset:224
	v_add_u32_e32 v168, 16, v130
	v_lshlrev_b32_e32 v168, 11, v168
	v_lshl_add_u32 v243, v131, 1, v168
	v_add_u32_e32 v168, 16, v130
	v_mul_hi_i32 v169, v168, s81
	v_lshrrev_b32_e32 v170, 31, v169
	v_ashrrev_i32_e32 v169, 10, v169
	v_add_u32_e32 v169, v169, v170
	v_mad_i32_i24 v170, v169, s82, v168
	v_add_u32_e32 v171, -16, v170
	v_cmp_lt_u32_e32 vcc, s83, v171
	v_lshl_add_u32 v171, v169, 12, v171
	v_add_u32_e32 v168, 0xfffff000, v170
	v_cmp_gt_i32_e64 s[2:3], 16, v170
	s_nop 1
	v_cndmask_b32_e64 v168, v168, v170, s[2:3]
	v_lshl_add_u32 v168, v169, 7, v168
	v_cndmask_b32_e32 v168, v171, v168, vcc
	v_mov_b32_e32 v169, s60
	v_mov_b32_e32 v170, s58
	v_cndmask_b32_e32 v250, v169, v170, vcc
	v_mov_b32_e32 v169, s61
	v_mov_b32_e32 v170, s59
	v_cndmask_b32_e32 v251, v169, v170, vcc
	v_lshlrev_b32_e32 v168, 12, v168
	v_lshl_add_u32 v168, v131, 2, v168
	v_add_co_u32_e32 v250, vcc, v250, v168
	s_nop 1
	v_addc_co_u32_e32 v251, vcc, 0, v251, vcc
	global_load_dwordx2 v[148:149], v243, s[56:57] offset:0
	global_load_dwordx2 v[150:151], v243, s[56:57] offset:32
	global_load_dwordx2 v[152:153], v243, s[56:57] offset:64
	global_load_dwordx2 v[154:155], v243, s[56:57] offset:96
	global_load_dwordx2 v[156:157], v243, s[56:57] offset:128
	global_load_dwordx2 v[158:159], v243, s[56:57] offset:160
	global_load_dwordx2 v[160:161], v243, s[56:57] offset:192
	global_load_dwordx2 v[162:163], v243, s[56:57] offset:224
	s_waitcnt vmcnt(15)
; template <int MI, int NI>
; DI void resid_epilogue(const Params& p, int from_x, const f32x4 (&acc)[NI][MI], int row0, int n0, float* rowss_next, bool last, int lm, int lg) {
;     ...
;     for (int ni = 0; ni < NI; ++ni) {
;       const int n = n0 + ni * 16 + lg * 4;
;       float4 h;
;       if (from_x >= 2) {
;         const u32x2 pk = *(const u32x2*)(hbr + n);
;         h = make_float4(__uint_as_float(pk[0] << 16), __uint_as_float(pk[0] & 0xffff0000u), __uint_as_float(pk[1] << 16), __uint_as_float(pk[1] & 0xffff0000u));
;       } else h = *(const float4*)(hr + n);
;       h.x += acc[ni][mi][0]; h.y += acc[ni][mi][1]; h.z += acc[ni][mi][2]; h.w += acc[ni][mi][3];
;       if (last) *(float4*)(hw + n) = h;
	v_lshlrev_b32_e32 v168, 16, v132
	v_and_b32_e32 v169, 0xffff0000, v132
	v_lshlrev_b32_e32 v170, 16, v133
	v_and_b32_e32 v171, 0xffff0000, v133
	v_pk_add_f32 v[192:193], v[126:127], v[168:169]
	v_pk_add_f32 v[194:195], v[128:129], v[170:171]
	s_nop 0
	global_store_dwordx4 v[248:249], v[192:195], off offset:0
	s_nop 1
	s_waitcnt vmcnt(15)
	v_lshlrev_b32_e32 v168, 16, v134
	v_and_b32_e32 v169, 0xffff0000, v134
	v_lshlrev_b32_e32 v170, 16, v135
	v_and_b32_e32 v171, 0xffff0000, v135
	v_pk_add_f32 v[192:193], v[122:123], v[168:169]
	v_pk_add_f32 v[194:195], v[124:125], v[170:171]
	s_nop 0
	global_store_dwordx4 v[248:249], v[192:195], off offset:64
	s_nop 1
	s_waitcnt vmcnt(15)
	v_lshlrev_b32_e32 v168, 16, v136
	v_and_b32_e32 v169, 0xffff0000, v136
	v_lshlrev_b32_e32 v170, 16, v137
	v_and_b32_e32 v171, 0xffff0000, v137
	v_pk_add_f32 v[192:193], v[118:119], v[168:169]
	v_pk_add_f32 v[194:195], v[120:121], v[170:171]
	s_nop 0
	global_store_dwordx4 v[248:249], v[192:195], off offset:128
	s_nop 1
	s_waitcnt vmcnt(15)
	v_lshlrev_b32_e32 v168, 16, v138
	v_and_b32_e32 v169, 0xffff0000, v138
	v_lshlrev_b32_e32 v170, 16, v139
	v_and_b32_e32 v171, 0xffff0000, v139
	v_pk_add_f32 v[192:193], v[114:115], v[168:169]
	v_pk_add_f32 v[194:195], v[116:117], v[170:171]
	s_nop 0
	global_store_dwordx4 v[248:249], v[192:195], off offset:192
	s_nop 1
	s_waitcnt vmcnt(15)
	v_lshlrev_b32_e32 v168, 16, v140
	v_and_b32_e32 v169, 0xffff0000, v140
	v_lshlrev_b32_e32 v170, 16, v141
	v_and_b32_e32 v171, 0xffff0000, v141
	v_pk_add_f32 v[192:193], v[110:111], v[168:169]
	v_pk_add_f32 v[194:195], v[112:113], v[170:171]
	s_nop 0
	global_store_dwordx4 v[248:249], v[192:195], off offset:256
	s_nop 1
	s_waitcnt vmcnt(15)
	v_lshlrev_b32_e32 v168, 16, v142
	v_and_b32_e32 v169, 0xffff0000, v142
	v_lshlrev_b32_e32 v170, 16, v143
	v_and_b32_e32 v171, 0xffff0000, v143
	v_pk_add_f32 v[192:193], v[106:107], v[168:169]
	v_pk_add_f32 v[194:195], v[108:109], v[170:171]
	s_nop 0
	global_store_dwordx4 v[248:249], v[192:195], off offset:320
	s_nop 1
	s_waitcnt vmcnt(15)
	v_lshlrev_b32_e32 v168, 16, v144
	v_and_b32_e32 v169, 0xffff0000, v144
	v_lshlrev_b32_e32 v170, 16, v145
	v_and_b32_e32 v171, 0xffff0000, v145
	v_pk_add_f32 v[192:193], v[102:103], v[168:169]
	v_pk_add_f32 v[194:195], v[104:105], v[170:171]
	s_nop 0
	global_store_dwordx4 v[248:249], v[192:195], off offset:384
	s_nop 1
	s_waitcnt vmcnt(15)
	v_lshlrev_b32_e32 v168, 16, v146
	v_and_b32_e32 v169, 0xffff0000, v146
	v_lshlrev_b32_e32 v170, 16, v147
	v_and_b32_e32 v171, 0xffff0000, v147
	v_pk_add_f32 v[192:193], v[98:99], v[168:169]
	v_pk_add_f32 v[194:195], v[100:101], v[170:171]
	s_nop 0
	global_store_dwordx4 v[248:249], v[192:195], off offset:448
	s_nop 1
	v_add_u32_e32 v168, 32, v130
	v_lshlrev_b32_e32 v168, 11, v168
	v_lshl_add_u32 v242, v131, 1, v168
	v_add_u32_e32 v168, 32, v130
	v_mul_hi_i32 v169, v168, s81
	v_lshrrev_b32_e32 v170, 31, v169
	v_ashrrev_i32_e32 v169, 10, v169
	v_add_u32_e32 v169, v169, v170
	v_mad_i32_i24 v170, v169, s82, v168
	v_add_u32_e32 v171, -16, v170
	v_cmp_lt_u32_e32 vcc, s83, v171
	v_lshl_add_u32 v171, v169, 12, v171
	v_add_u32_e32 v168, 0xfffff000, v170
	v_cmp_gt_i32_e64 s[2:3], 16, v170
	s_nop 1
	v_cndmask_b32_e64 v168, v168, v170, s[2:3]
	v_lshl_add_u32 v168, v169, 7, v168
	v_cndmask_b32_e32 v168, v171, v168, vcc
	v_mov_b32_e32 v169, s60
	v_mov_b32_e32 v170, s58
	v_cndmask_b32_e32 v248, v169, v170, vcc
	v_mov_b32_e32 v169, s61
	v_mov_b32_e32 v170, s59
	v_cndmask_b32_e32 v249, v169, v170, vcc
	v_lshlrev_b32_e32 v168, 12, v168
	v_lshl_add_u32 v168, v131, 2, v168
	v_add_co_u32_e32 v248, vcc, v248, v168
	s_nop 1
	v_addc_co_u32_e32 v249, vcc, 0, v249, vcc
	global_load_dwordx2 v[132:133], v242, s[56:57] offset:0
	global_load_dwordx2 v[134:135], v242, s[56:57] offset:32
	global_load_dwordx2 v[136:137], v242, s[56:57] offset:64
	global_load_dwordx2 v[138:139], v242, s[56:57] offset:96
	global_load_dwordx2 v[140:141], v242, s[56:57] offset:128
	global_load_dwordx2 v[142:143], v242, s[56:57] offset:160
	global_load_dwordx2 v[144:145], v242, s[56:57] offset:192
	global_load_dwordx2 v[146:147], v242, s[56:57] offset:224
	s_waitcnt vmcnt(23)
	v_lshlrev_b32_e32 v168, 16, v148
	v_and_b32_e32 v169, 0xffff0000, v148
	v_lshlrev_b32_e32 v170, 16, v149
	v_and_b32_e32 v171, 0xffff0000, v149
	v_pk_add_f32 v[192:193], v[94:95], v[168:169]
	v_pk_add_f32 v[194:195], v[96:97], v[170:171]
	s_nop 0
	global_store_dwordx4 v[250:251], v[192:195], off offset:0
	s_nop 1
	s_waitcnt vmcnt(23)
	v_lshlrev_b32_e32 v168, 16, v150
	v_and_b32_e32 v169, 0xffff0000, v150
	v_lshlrev_b32_e32 v170, 16, v151
	v_and_b32_e32 v171, 0xffff0000, v151
	v_pk_add_f32 v[192:193], v[90:91], v[168:169]
	v_pk_add_f32 v[194:195], v[92:93], v[170:171]
	s_nop 0
	global_store_dwordx4 v[250:251], v[192:195], off offset:64
	s_nop 1
	s_waitcnt vmcnt(23)
	v_lshlrev_b32_e32 v168, 16, v152
	v_and_b32_e32 v169, 0xffff0000, v152
	v_lshlrev_b32_e32 v170, 16, v153
	v_and_b32_e32 v171, 0xffff0000, v153
	v_pk_add_f32 v[192:193], v[86:87], v[168:169]
	v_pk_add_f32 v[194:195], v[88:89], v[170:171]
	s_nop 0
	global_store_dwordx4 v[250:251], v[192:195], off offset:128
	s_nop 1
	s_waitcnt vmcnt(23)
	v_lshlrev_b32_e32 v168, 16, v154
	v_and_b32_e32 v169, 0xffff0000, v154
	v_lshlrev_b32_e32 v170, 16, v155
	v_and_b32_e32 v171, 0xffff0000, v155
	v_pk_add_f32 v[192:193], v[82:83], v[168:169]
	v_pk_add_f32 v[194:195], v[84:85], v[170:171]
	s_nop 0
	global_store_dwordx4 v[250:251], v[192:195], off offset:192
	s_nop 1
	s_waitcnt vmcnt(23)
; DI float* hrow_w(const Params& p, int gr) {
;   int b = gr / TP, t = gr - b * TP;
;   if (t >= NMETA && t < TREAL) return p.out + ((size_t)(b * SEQ + t - NMETA)) * DM;
;   int s = t < NMETA ? t : t - TREAL + NMETA;
;   return p.side + ((size_t)(b * 128 + s)) * DM;
; template <int MI, int NI>
; DI void resid_epilogue(const Params& p, int from_x, const f32x4 (&acc)[NI][MI], int row0, int n0, float* rowss_next, bool last, int lm, int lg) {
;     ...
;     for (int ni = 0; ni < NI; ++ni) {
;       const int n = n0 + ni * 16 + lg * 4;
;       float4 h;
;       if (from_x >= 2) {
;         const u32x2 pk = *(const u32x2*)(hbr + n);
;         h = make_float4(__uint_as_float(pk[0] << 16), __uint_as_float(pk[0] & 0xffff0000u), __uint_as_float(pk[1] << 16), __uint_as_float(pk[1] & 0xffff0000u));
;       } else h = *(const float4*)(hr + n);
;       h.x += acc[ni][mi][0]; h.y += acc[ni][mi][1]; h.z += acc[ni][mi][2]; h.w += acc[ni][mi][3];
;       if (last) *(float4*)(hw + n) = h;
	v_lshlrev_b32_e32 v168, 16, v156
	v_and_b32_e32 v169, 0xffff0000, v156
	v_lshlrev_b32_e32 v170, 16, v157
	v_and_b32_e32 v171, 0xffff0000, v157
	v_pk_add_f32 v[192:193], v[78:79], v[168:169]
	v_pk_add_f32 v[194:195], v[80:81], v[170:171]
	s_nop 0
	global_store_dwordx4 v[250:251], v[192:195], off offset:256
	s_nop 1
	s_waitcnt vmcnt(23)
	v_lshlrev_b32_e32 v168, 16, v158
	v_and_b32_e32 v169, 0xffff0000, v158
	v_lshlrev_b32_e32 v170, 16, v159
	v_and_b32_e32 v171, 0xffff0000, v159
	v_pk_add_f32 v[192:193], v[74:75], v[168:169]
	v_pk_add_f32 v[194:195], v[76:77], v[170:171]
	s_nop 0
	global_store_dwordx4 v[250:251], v[192:195], off offset:320
	s_nop 1
	s_waitcnt vmcnt(23)
	v_lshlrev_b32_e32 v168, 16, v160
	v_and_b32_e32 v169, 0xffff0000, v160
	v_lshlrev_b32_e32 v170, 16, v161
	v_and_b32_e32 v171, 0xffff0000, v161
	v_pk_add_f32 v[192:193], v[70:71], v[168:169]
	v_pk_add_f32 v[194:195], v[72:73], v[170:171]
	s_nop 0
	global_store_dwordx4 v[250:251], v[192:195], off offset:384
	s_nop 1
	s_waitcnt vmcnt(23)
	v_lshlrev_b32_e32 v168, 16, v162
	v_and_b32_e32 v169, 0xffff0000, v162
	v_lshlrev_b32_e32 v170, 16, v163
	v_and_b32_e32 v171, 0xffff0000, v163
	v_pk_add_f32 v[192:193], v[66:67], v[168:169]
	v_pk_add_f32 v[194:195], v[68:69], v[170:171]
	s_nop 0
	global_store_dwordx4 v[250:251], v[192:195], off offset:448
	s_nop 1
	v_add_u32_e32 v168, 48, v130
	v_lshlrev_b32_e32 v168, 11, v168
	v_lshl_add_u32 v243, v131, 1, v168
	v_add_u32_e32 v168, 48, v130
	v_mul_hi_i32 v169, v168, s81
	v_lshrrev_b32_e32 v170, 31, v169
	v_ashrrev_i32_e32 v169, 10, v169
	v_add_u32_e32 v169, v169, v170
	v_mad_i32_i24 v170, v169, s82, v168
	v_add_u32_e32 v171, -16, v170
	v_cmp_lt_u32_e32 vcc, s83, v171
	v_lshl_add_u32 v171, v169, 12, v171
	v_add_u32_e32 v168, 0xfffff000, v170
	v_cmp_gt_i32_e64 s[2:3], 16, v170
	s_nop 1
	v_cndmask_b32_e64 v168, v168, v170, s[2:3]
	v_lshl_add_u32 v168, v169, 7, v168
	v_cndmask_b32_e32 v168, v171, v168, vcc
	v_mov_b32_e32 v169, s60
	v_mov_b32_e32 v170, s58
	v_cndmask_b32_e32 v250, v169, v170, vcc
	v_mov_b32_e32 v169, s61
	v_mov_b32_e32 v170, s59
	v_cndmask_b32_e32 v251, v169, v170, vcc
	v_lshlrev_b32_e32 v168, 12, v168
	v_lshl_add_u32 v168, v131, 2, v168
	v_add_co_u32_e32 v250, vcc, v250, v168
	s_nop 1
	v_addc_co_u32_e32 v251, vcc, 0, v251, vcc
	global_load_dwordx2 v[148:149], v243, s[56:57] offset:0
	global_load_dwordx2 v[150:151], v243, s[56:57] offset:32
	global_load_dwordx2 v[152:153], v243, s[56:57] offset:64
	global_load_dwordx2 v[154:155], v243, s[56:57] offset:96
	global_load_dwordx2 v[156:157], v243, s[56:57] offset:128
	global_load_dwordx2 v[158:159], v243, s[56:57] offset:160
	global_load_dwordx2 v[160:161], v243, s[56:57] offset:192
	global_load_dwordx2 v[162:163], v243, s[56:57] offset:224
	s_waitcnt vmcnt(23)
	v_lshlrev_b32_e32 v168, 16, v132
	v_and_b32_e32 v169, 0xffff0000, v132
	v_lshlrev_b32_e32 v170, 16, v133
	v_and_b32_e32 v171, 0xffff0000, v133
	v_pk_add_f32 v[192:193], v[62:63], v[168:169]
	v_pk_add_f32 v[194:195], v[64:65], v[170:171]
	s_nop 0
	global_store_dwordx4 v[248:249], v[192:195], off offset:0
	s_nop 1
	s_waitcnt vmcnt(23)
	v_lshlrev_b32_e32 v168, 16, v134
	v_and_b32_e32 v169, 0xffff0000, v134
	v_lshlrev_b32_e32 v170, 16, v135
	v_and_b32_e32 v171, 0xffff0000, v135
	v_pk_add_f32 v[192:193], v[58:59], v[168:169]
	v_pk_add_f32 v[194:195], v[60:61], v[170:171]
	s_nop 0
	global_store_dwordx4 v[248:249], v[192:195], off offset:64
	s_nop 1
	s_waitcnt vmcnt(23)
	v_lshlrev_b32_e32 v168, 16, v136
	v_and_b32_e32 v169, 0xffff0000, v136
	v_lshlrev_b32_e32 v170, 16, v137
	v_and_b32_e32 v171, 0xffff0000, v137
	v_pk_add_f32 v[192:193], v[54:55], v[168:169]
	v_pk_add_f32 v[194:195], v[56:57], v[170:171]
	s_nop 0
	global_store_dwordx4 v[248:249], v[192:195], off offset:128
	s_nop 1
	s_waitcnt vmcnt(23)
	v_lshlrev_b32_e32 v168, 16, v138
	v_and_b32_e32 v169, 0xffff0000, v138
	v_lshlrev_b32_e32 v170, 16, v139
	v_and_b32_e32 v171, 0xffff0000, v139
	v_pk_add_f32 v[192:193], v[50:51], v[168:169]
	v_pk_add_f32 v[194:195], v[52:53], v[170:171]
	s_nop 0
	global_store_dwordx4 v[248:249], v[192:195], off offset:192
	s_nop 1
	s_waitcnt vmcnt(23)
	v_lshlrev_b32_e32 v168, 16, v140
	v_and_b32_e32 v169, 0xffff0000, v140
	v_lshlrev_b32_e32 v170, 16, v141
	v_and_b32_e32 v171, 0xffff0000, v141
	v_pk_add_f32 v[192:193], v[46:47], v[168:169]
	v_pk_add_f32 v[194:195], v[48:49], v[170:171]
	s_nop 0
	global_store_dwordx4 v[248:249], v[192:195], off offset:256
	s_nop 1
	s_waitcnt vmcnt(23)
	v_lshlrev_b32_e32 v168, 16, v142
	v_and_b32_e32 v169, 0xffff0000, v142
	v_lshlrev_b32_e32 v170, 16, v143
	v_and_b32_e32 v171, 0xffff0000, v143
	v_pk_add_f32 v[192:193], v[42:43], v[168:169]
	v_pk_add_f32 v[194:195], v[44:45], v[170:171]
	s_nop 0
	global_store_dwordx4 v[248:249], v[192:195], off offset:320
	s_nop 1
	s_waitcnt vmcnt(23)
	v_lshlrev_b32_e32 v168, 16, v144
	v_and_b32_e32 v169, 0xffff0000, v144
	v_lshlrev_b32_e32 v170, 16, v145
	v_and_b32_e32 v171, 0xffff0000, v145
	v_pk_add_f32 v[192:193], v[38:39], v[168:169]
	v_pk_add_f32 v[194:195], v[40:41], v[170:171]
	s_nop 0
	global_store_dwordx4 v[248:249], v[192:195], off offset:384
	s_nop 1
	s_waitcnt vmcnt(23)
	v_lshlrev_b32_e32 v168, 16, v146
	v_and_b32_e32 v169, 0xffff0000, v146
	v_lshlrev_b32_e32 v170, 16, v147
	v_and_b32_e32 v171, 0xffff0000, v147
	v_pk_add_f32 v[192:193], v[34:35], v[168:169]
	v_pk_add_f32 v[194:195], v[36:37], v[170:171]
	s_nop 0
	global_store_dwordx4 v[248:249], v[192:195], off offset:448
	s_nop 1
	s_waitcnt vmcnt(15)
	v_lshlrev_b32_e32 v168, 16, v148
	v_and_b32_e32 v169, 0xffff0000, v148
	v_lshlrev_b32_e32 v170, 16, v149
	v_and_b32_e32 v171, 0xffff0000, v149
	v_pk_add_f32 v[192:193], v[30:31], v[168:169]
	v_pk_add_f32 v[194:195], v[32:33], v[170:171]
	s_nop 0
	global_store_dwordx4 v[250:251], v[192:195], off offset:0
	s_nop 1
	s_waitcnt vmcnt(15)
; template <int MI, int NI>
; DI void resid_epilogue(const Params& p, int from_x, const f32x4 (&acc)[NI][MI], int row0, int n0, float* rowss_next, bool last, int lm, int lg) {
;     ...
;     for (int ni = 0; ni < NI; ++ni) {
;       const int n = n0 + ni * 16 + lg * 4;
;       float4 h;
;       if (from_x >= 2) {
;         const u32x2 pk = *(const u32x2*)(hbr + n);
;         h = make_float4(__uint_as_float(pk[0] << 16), __uint_as_float(pk[0] & 0xffff0000u), __uint_as_float(pk[1] << 16), __uint_as_float(pk[1] & 0xffff0000u));
;       } else h = *(const float4*)(hr + n);
;       h.x += acc[ni][mi][0]; h.y += acc[ni][mi][1]; h.z += acc[ni][mi][2]; h.w += acc[ni][mi][3];
;       if (last) *(float4*)(hw + n) = h;
;       if (!last) {
;         u32x2 pk = {pack2bf(h.x, h.y), pack2bf(h.z, h.w)};
;         *(u32x2*)(hbr + n) = pk;
;         ss += h.x * h.x + h.y * h.y + h.z * h.z + h.w * h.w;
;       }
	v_lshlrev_b32_e32 v168, 16, v150
	v_and_b32_e32 v169, 0xffff0000, v150
	v_lshlrev_b32_e32 v170, 16, v151
	v_and_b32_e32 v171, 0xffff0000, v151
	v_pk_add_f32 v[192:193], v[26:27], v[168:169]
	v_pk_add_f32 v[194:195], v[28:29], v[170:171]
	s_nop 0
	global_store_dwordx4 v[250:251], v[192:195], off offset:64
	s_nop 1
	s_waitcnt vmcnt(15)
	v_lshlrev_b32_e32 v168, 16, v152
	v_and_b32_e32 v169, 0xffff0000, v152
	v_lshlrev_b32_e32 v170, 16, v153
	v_and_b32_e32 v171, 0xffff0000, v153
	v_pk_add_f32 v[192:193], v[22:23], v[168:169]
	v_pk_add_f32 v[194:195], v[24:25], v[170:171]
	s_nop 0
	global_store_dwordx4 v[250:251], v[192:195], off offset:128
	s_nop 1
	s_waitcnt vmcnt(15)
	v_lshlrev_b32_e32 v168, 16, v154
	v_and_b32_e32 v169, 0xffff0000, v154
	v_lshlrev_b32_e32 v170, 16, v155
	v_and_b32_e32 v171, 0xffff0000, v155
	v_pk_add_f32 v[192:193], v[18:19], v[168:169]
	v_pk_add_f32 v[194:195], v[20:21], v[170:171]
	s_nop 0
	global_store_dwordx4 v[250:251], v[192:195], off offset:192
	s_nop 1
	s_waitcnt vmcnt(15)
	v_lshlrev_b32_e32 v168, 16, v156
	v_and_b32_e32 v169, 0xffff0000, v156
	v_lshlrev_b32_e32 v170, 16, v157
	v_and_b32_e32 v171, 0xffff0000, v157
	v_pk_add_f32 v[192:193], v[14:15], v[168:169]
	v_pk_add_f32 v[194:195], v[16:17], v[170:171]
	s_nop 0
	global_store_dwordx4 v[250:251], v[192:195], off offset:256
	s_nop 1
	s_waitcnt vmcnt(15)
	v_lshlrev_b32_e32 v168, 16, v158
	v_and_b32_e32 v169, 0xffff0000, v158
	v_lshlrev_b32_e32 v170, 16, v159
	v_and_b32_e32 v171, 0xffff0000, v159
	v_pk_add_f32 v[192:193], v[10:11], v[168:169]
	v_pk_add_f32 v[194:195], v[12:13], v[170:171]
	s_nop 0
	global_store_dwordx4 v[250:251], v[192:195], off offset:320
	s_nop 1
	s_waitcnt vmcnt(15)
	v_lshlrev_b32_e32 v168, 16, v160
	v_and_b32_e32 v169, 0xffff0000, v160
	v_lshlrev_b32_e32 v170, 16, v161
	v_and_b32_e32 v171, 0xffff0000, v161
	v_pk_add_f32 v[192:193], v[6:7], v[168:169]
	v_pk_add_f32 v[194:195], v[8:9], v[170:171]
	s_nop 0
	global_store_dwordx4 v[250:251], v[192:195], off offset:384
	s_nop 1
	s_waitcnt vmcnt(15)
	v_lshlrev_b32_e32 v168, 16, v162
	v_and_b32_e32 v169, 0xffff0000, v162
	v_lshlrev_b32_e32 v170, 16, v163
	v_and_b32_e32 v171, 0xffff0000, v163
	v_pk_add_f32 v[192:193], v[2:3], v[168:169]
	v_pk_add_f32 v[194:195], v[4:5], v[170:171]
	s_nop 0
	global_store_dwordx4 v[250:251], v[192:195], off offset:448
	s_nop 1
	s_branch .LBB0_958
.Lre_down_T:
	s_waitcnt lgkmcnt(0)
	v_add_u32_e32 v168, 0, v130
	v_lshlrev_b32_e32 v168, 11, v168
	v_lshl_add_u32 v242, v131, 1, v168
	global_load_dwordx2 v[132:133], v242, s[56:57] offset:0
	global_load_dwordx2 v[134:135], v242, s[56:57] offset:32
	global_load_dwordx2 v[136:137], v242, s[56:57] offset:64
	global_load_dwordx2 v[138:139], v242, s[56:57] offset:96
	global_load_dwordx2 v[140:141], v242, s[56:57] offset:128
	global_load_dwordx2 v[142:143], v242, s[56:57] offset:160
	global_load_dwordx2 v[144:145], v242, s[56:57] offset:192
	global_load_dwordx2 v[146:147], v242, s[56:57] offset:224
	v_add_u32_e32 v168, 16, v130
	v_lshlrev_b32_e32 v168, 11, v168
	v_lshl_add_u32 v243, v131, 1, v168
	global_load_dwordx2 v[148:149], v243, s[56:57] offset:0
	global_load_dwordx2 v[150:151], v243, s[56:57] offset:32
	global_load_dwordx2 v[152:153], v243, s[56:57] offset:64
	global_load_dwordx2 v[154:155], v243, s[56:57] offset:96
	global_load_dwordx2 v[156:157], v243, s[56:57] offset:128
	global_load_dwordx2 v[158:159], v243, s[56:57] offset:160
	global_load_dwordx2 v[160:161], v243, s[56:57] offset:192
	global_load_dwordx2 v[162:163], v243, s[56:57] offset:224
	s_waitcnt vmcnt(15)
	v_lshlrev_b32_e32 v168, 16, v132
	v_and_b32_e32 v169, 0xffff0000, v132
	v_lshlrev_b32_e32 v170, 16, v133
	v_and_b32_e32 v171, 0xffff0000, v133
	v_pk_add_f32 v[192:193], v[126:127], v[168:169]
	v_pk_add_f32 v[194:195], v[128:129], v[170:171]
	v_cvt_pk_bf16_f32 v168, v192, v193
	v_cvt_pk_bf16_f32 v169, v194, v195
	global_store_dwordx2 v242, v[168:169], s[56:57] offset:0
	v_pk_mul_f32 v[192:193], v[192:193], v[192:193]
	v_pk_mul_f32 v[194:195], v[194:195], v[194:195]
	v_add_f32_e32 v170, v193, v192
	v_add_f32_e32 v170, v194, v170
	v_add_f32_e32 v170, v195, v170
	v_mov_b32_e32 v164, v170
	s_waitcnt vmcnt(15)
	v_lshlrev_b32_e32 v168, 16, v134
	v_and_b32_e32 v169, 0xffff0000, v134
	v_lshlrev_b32_e32 v170, 16, v135
	v_and_b32_e32 v171, 0xffff0000, v135
	v_pk_add_f32 v[192:193], v[122:123], v[168:169]
	v_pk_add_f32 v[194:195], v[124:125], v[170:171]
	v_cvt_pk_bf16_f32 v168, v192, v193
	v_cvt_pk_bf16_f32 v169, v194, v195
	global_store_dwordx2 v242, v[168:169], s[56:57] offset:32
	v_pk_mul_f32 v[192:193], v[192:193], v[192:193]
	v_pk_mul_f32 v[194:195], v[194:195], v[194:195]
	v_add_f32_e32 v170, v193, v192
	v_add_f32_e32 v170, v194, v170
	v_add_f32_e32 v170, v195, v170
	v_add_f32_e32 v164, v164, v170
	s_waitcnt vmcnt(15)
	v_lshlrev_b32_e32 v168, 16, v136
	v_and_b32_e32 v169, 0xffff0000, v136
	v_lshlrev_b32_e32 v170, 16, v137
	v_and_b32_e32 v171, 0xffff0000, v137
	v_pk_add_f32 v[192:193], v[118:119], v[168:169]
	v_pk_add_f32 v[194:195], v[120:121], v[170:171]
	v_cvt_pk_bf16_f32 v168, v192, v193
	v_cvt_pk_bf16_f32 v169, v194, v195
	global_store_dwordx2 v242, v[168:169], s[56:57] offset:64
	v_pk_mul_f32 v[192:193], v[192:193], v[192:193]
	v_pk_mul_f32 v[194:195], v[194:195], v[194:195]
	v_add_f32_e32 v170, v193, v192
	v_add_f32_e32 v170, v194, v170
	v_add_f32_e32 v170, v195, v170
	v_add_f32_e32 v164, v164, v170
	s_waitcnt vmcnt(15)
; template <int MI, int NI>
; DI void resid_epilogue(const Params& p, int from_x, const f32x4 (&acc)[NI][MI], int row0, int n0, float* rowss_next, bool last, int lm, int lg) {
;     ...
;     for (int ni = 0; ni < NI; ++ni) {
;       const int n = n0 + ni * 16 + lg * 4;
;       float4 h;
;       if (from_x >= 2) {
;         const u32x2 pk = *(const u32x2*)(hbr + n);
;         h = make_float4(__uint_as_float(pk[0] << 16), __uint_as_float(pk[0] & 0xffff0000u), __uint_as_float(pk[1] << 16), __uint_as_float(pk[1] & 0xffff0000u));
;       } else h = *(const float4*)(hr + n);
;       h.x += acc[ni][mi][0]; h.y += acc[ni][mi][1]; h.z += acc[ni][mi][2]; h.w += acc[ni][mi][3];
;       if (last) *(float4*)(hw + n) = h;
;       if (!last) {
;         u32x2 pk = {pack2bf(h.x, h.y), pack2bf(h.z, h.w)};
;         *(u32x2*)(hbr + n) = pk;
;         ss += h.x * h.x + h.y * h.y + h.z * h.z + h.w * h.w;
;       }
;     }
;     if (!last) {
;       ss += __shfl_xor(ss, 16);
;       ss += __shfl_xor(ss, 32);
;       if (lg == 0) atomicAdd(rowss_next + m, ss);
	v_lshlrev_b32_e32 v168, 16, v138
	v_and_b32_e32 v169, 0xffff0000, v138
	v_lshlrev_b32_e32 v170, 16, v139
	v_and_b32_e32 v171, 0xffff0000, v139
	v_pk_add_f32 v[192:193], v[114:115], v[168:169]
	v_pk_add_f32 v[194:195], v[116:117], v[170:171]
	v_cvt_pk_bf16_f32 v168, v192, v193
	v_cvt_pk_bf16_f32 v169, v194, v195
	global_store_dwordx2 v242, v[168:169], s[56:57] offset:96
	v_pk_mul_f32 v[192:193], v[192:193], v[192:193]
	v_pk_mul_f32 v[194:195], v[194:195], v[194:195]
	v_add_f32_e32 v170, v193, v192
	v_add_f32_e32 v170, v194, v170
	v_add_f32_e32 v170, v195, v170
	v_add_f32_e32 v164, v164, v170
	s_waitcnt vmcnt(15)
	v_lshlrev_b32_e32 v168, 16, v140
	v_and_b32_e32 v169, 0xffff0000, v140
	v_lshlrev_b32_e32 v170, 16, v141
	v_and_b32_e32 v171, 0xffff0000, v141
	v_pk_add_f32 v[192:193], v[110:111], v[168:169]
	v_pk_add_f32 v[194:195], v[112:113], v[170:171]
	v_cvt_pk_bf16_f32 v168, v192, v193
	v_cvt_pk_bf16_f32 v169, v194, v195
	global_store_dwordx2 v242, v[168:169], s[56:57] offset:128
	v_pk_mul_f32 v[192:193], v[192:193], v[192:193]
	v_pk_mul_f32 v[194:195], v[194:195], v[194:195]
	v_add_f32_e32 v170, v193, v192
	v_add_f32_e32 v170, v194, v170
	v_add_f32_e32 v170, v195, v170
	v_add_f32_e32 v164, v164, v170
	s_waitcnt vmcnt(15)
	v_lshlrev_b32_e32 v168, 16, v142
	v_and_b32_e32 v169, 0xffff0000, v142
	v_lshlrev_b32_e32 v170, 16, v143
	v_and_b32_e32 v171, 0xffff0000, v143
	v_pk_add_f32 v[192:193], v[106:107], v[168:169]
	v_pk_add_f32 v[194:195], v[108:109], v[170:171]
	v_cvt_pk_bf16_f32 v168, v192, v193
	v_cvt_pk_bf16_f32 v169, v194, v195
	global_store_dwordx2 v242, v[168:169], s[56:57] offset:160
	v_pk_mul_f32 v[192:193], v[192:193], v[192:193]
	v_pk_mul_f32 v[194:195], v[194:195], v[194:195]
	v_add_f32_e32 v170, v193, v192
	v_add_f32_e32 v170, v194, v170
	v_add_f32_e32 v170, v195, v170
	v_add_f32_e32 v164, v164, v170
	s_waitcnt vmcnt(15)
	v_lshlrev_b32_e32 v168, 16, v144
	v_and_b32_e32 v169, 0xffff0000, v144
	v_lshlrev_b32_e32 v170, 16, v145
	v_and_b32_e32 v171, 0xffff0000, v145
	v_pk_add_f32 v[192:193], v[102:103], v[168:169]
	v_pk_add_f32 v[194:195], v[104:105], v[170:171]
	v_cvt_pk_bf16_f32 v168, v192, v193
	v_cvt_pk_bf16_f32 v169, v194, v195
	global_store_dwordx2 v242, v[168:169], s[56:57] offset:192
	v_pk_mul_f32 v[192:193], v[192:193], v[192:193]
	v_pk_mul_f32 v[194:195], v[194:195], v[194:195]
	v_add_f32_e32 v170, v193, v192
	v_add_f32_e32 v170, v194, v170
	v_add_f32_e32 v170, v195, v170
	v_add_f32_e32 v164, v164, v170
	s_waitcnt vmcnt(15)
	v_lshlrev_b32_e32 v168, 16, v146
	v_and_b32_e32 v169, 0xffff0000, v146
	v_lshlrev_b32_e32 v170, 16, v147
	v_and_b32_e32 v171, 0xffff0000, v147
	v_pk_add_f32 v[192:193], v[98:99], v[168:169]
	v_pk_add_f32 v[194:195], v[100:101], v[170:171]
	v_cvt_pk_bf16_f32 v168, v192, v193
	v_cvt_pk_bf16_f32 v169, v194, v195
	global_store_dwordx2 v242, v[168:169], s[56:57] offset:224
	v_pk_mul_f32 v[192:193], v[192:193], v[192:193]
	v_pk_mul_f32 v[194:195], v[194:195], v[194:195]
	v_add_f32_e32 v170, v193, v192
	v_add_f32_e32 v170, v194, v170
	v_add_f32_e32 v170, v195, v170
	v_add_f32_e32 v164, v164, v170
	v_xor_b32_e32 v168, 16, v207
	v_lshlrev_b32_e32 v168, 2, v168
	ds_bpermute_b32 v169, v168, v164
	v_xor_b32_e32 v168, 32, v207
	v_lshlrev_b32_e32 v168, 2, v168
	s_waitcnt lgkmcnt(0)
	v_add_f32_e32 v164, v164, v169
	ds_bpermute_b32 v169, v168, v164
	v_add_u32_e32 v170, 0, v130
	v_lshlrev_b32_e32 v170, 2, v170
	v_and_b32_e32 v171, 63, v207
	v_cmp_gt_u32_e32 vcc, 16, v171
	s_waitcnt lgkmcnt(0)
	v_add_f32_e32 v164, v164, v169
	s_and_saveexec_b64 s[2:3], vcc
	global_atomic_add_f32 v170, v164, s[4:5]
	s_or_b64 exec, exec, s[2:3]
	v_add_u32_e32 v168, 32, v130
	v_lshlrev_b32_e32 v168, 11, v168
	v_lshl_add_u32 v242, v131, 1, v168
	global_load_dwordx2 v[132:133], v242, s[56:57] offset:0
	global_load_dwordx2 v[134:135], v242, s[56:57] offset:32
	global_load_dwordx2 v[136:137], v242, s[56:57] offset:64
	global_load_dwordx2 v[138:139], v242, s[56:57] offset:96
	global_load_dwordx2 v[140:141], v242, s[56:57] offset:128
	global_load_dwordx2 v[142:143], v242, s[56:57] offset:160
	global_load_dwordx2 v[144:145], v242, s[56:57] offset:192
	global_load_dwordx2 v[146:147], v242, s[56:57] offset:224
	s_waitcnt vmcnt(24)
	v_lshlrev_b32_e32 v168, 16, v148
	v_and_b32_e32 v169, 0xffff0000, v148
	v_lshlrev_b32_e32 v170, 16, v149
	v_and_b32_e32 v171, 0xffff0000, v149
	v_pk_add_f32 v[192:193], v[94:95], v[168:169]
	v_pk_add_f32 v[194:195], v[96:97], v[170:171]
	v_cvt_pk_bf16_f32 v168, v192, v193
	v_cvt_pk_bf16_f32 v169, v194, v195
	global_store_dwordx2 v243, v[168:169], s[56:57] offset:0
	v_pk_mul_f32 v[192:193], v[192:193], v[192:193]
	v_pk_mul_f32 v[194:195], v[194:195], v[194:195]
	v_add_f32_e32 v170, v193, v192
	v_add_f32_e32 v170, v194, v170
	v_add_f32_e32 v170, v195, v170
	v_mov_b32_e32 v164, v170
	s_waitcnt vmcnt(24)
	v_lshlrev_b32_e32 v168, 16, v150
	v_and_b32_e32 v169, 0xffff0000, v150
	v_lshlrev_b32_e32 v170, 16, v151
	v_and_b32_e32 v171, 0xffff0000, v151
	v_pk_add_f32 v[192:193], v[90:91], v[168:169]
	v_pk_add_f32 v[194:195], v[92:93], v[170:171]
	v_cvt_pk_bf16_f32 v168, v192, v193
	v_cvt_pk_bf16_f32 v169, v194, v195
	global_store_dwordx2 v243, v[168:169], s[56:57] offset:32
	v_pk_mul_f32 v[192:193], v[192:193], v[192:193]
	v_pk_mul_f32 v[194:195], v[194:195], v[194:195]
	v_add_f32_e32 v170, v193, v192
	v_add_f32_e32 v170, v194, v170
	v_add_f32_e32 v170, v195, v170
	v_add_f32_e32 v164, v164, v170
	s_waitcnt vmcnt(24)
; template <int MI, int NI>
; DI void resid_epilogue(const Params& p, int from_x, const f32x4 (&acc)[NI][MI], int row0, int n0, float* rowss_next, bool last, int lm, int lg) {
;     ...
;     for (int ni = 0; ni < NI; ++ni) {
;       const int n = n0 + ni * 16 + lg * 4;
;       float4 h;
;       if (from_x >= 2) {
;         const u32x2 pk = *(const u32x2*)(hbr + n);
;         h = make_float4(__uint_as_float(pk[0] << 16), __uint_as_float(pk[0] & 0xffff0000u), __uint_as_float(pk[1] << 16), __uint_as_float(pk[1] & 0xffff0000u));
;       } else h = *(const float4*)(hr + n);
;       h.x += acc[ni][mi][0]; h.y += acc[ni][mi][1]; h.z += acc[ni][mi][2]; h.w += acc[ni][mi][3];
;       if (last) *(float4*)(hw + n) = h;
;       if (!last) {
;         u32x2 pk = {pack2bf(h.x, h.y), pack2bf(h.z, h.w)};
;         *(u32x2*)(hbr + n) = pk;
;         ss += h.x * h.x + h.y * h.y + h.z * h.z + h.w * h.w;
;       }
;     }
;     if (!last) {
;       ss += __shfl_xor(ss, 16);
;       ss += __shfl_xor(ss, 32);
;       if (lg == 0) atomicAdd(rowss_next + m, ss);
	v_lshlrev_b32_e32 v168, 16, v152
	v_and_b32_e32 v169, 0xffff0000, v152
	v_lshlrev_b32_e32 v170, 16, v153
	v_and_b32_e32 v171, 0xffff0000, v153
	v_pk_add_f32 v[192:193], v[86:87], v[168:169]
	v_pk_add_f32 v[194:195], v[88:89], v[170:171]
	v_cvt_pk_bf16_f32 v168, v192, v193
	v_cvt_pk_bf16_f32 v169, v194, v195
	global_store_dwordx2 v243, v[168:169], s[56:57] offset:64
	v_pk_mul_f32 v[192:193], v[192:193], v[192:193]
	v_pk_mul_f32 v[194:195], v[194:195], v[194:195]
	v_add_f32_e32 v170, v193, v192
	v_add_f32_e32 v170, v194, v170
	v_add_f32_e32 v170, v195, v170
	v_add_f32_e32 v164, v164, v170
	s_waitcnt vmcnt(24)
	v_lshlrev_b32_e32 v168, 16, v154
	v_and_b32_e32 v169, 0xffff0000, v154
	v_lshlrev_b32_e32 v170, 16, v155
	v_and_b32_e32 v171, 0xffff0000, v155
	v_pk_add_f32 v[192:193], v[82:83], v[168:169]
	v_pk_add_f32 v[194:195], v[84:85], v[170:171]
	v_cvt_pk_bf16_f32 v168, v192, v193
	v_cvt_pk_bf16_f32 v169, v194, v195
	global_store_dwordx2 v243, v[168:169], s[56:57] offset:96
	v_pk_mul_f32 v[192:193], v[192:193], v[192:193]
	v_pk_mul_f32 v[194:195], v[194:195], v[194:195]
	v_add_f32_e32 v170, v193, v192
	v_add_f32_e32 v170, v194, v170
	v_add_f32_e32 v170, v195, v170
	v_add_f32_e32 v164, v164, v170
	s_waitcnt vmcnt(24)
	v_lshlrev_b32_e32 v168, 16, v156
	v_and_b32_e32 v169, 0xffff0000, v156
	v_lshlrev_b32_e32 v170, 16, v157
	v_and_b32_e32 v171, 0xffff0000, v157
	v_pk_add_f32 v[192:193], v[78:79], v[168:169]
	v_pk_add_f32 v[194:195], v[80:81], v[170:171]
	v_cvt_pk_bf16_f32 v168, v192, v193
	v_cvt_pk_bf16_f32 v169, v194, v195
	global_store_dwordx2 v243, v[168:169], s[56:57] offset:128
	v_pk_mul_f32 v[192:193], v[192:193], v[192:193]
	v_pk_mul_f32 v[194:195], v[194:195], v[194:195]
	v_add_f32_e32 v170, v193, v192
	v_add_f32_e32 v170, v194, v170
	v_add_f32_e32 v170, v195, v170
	v_add_f32_e32 v164, v164, v170
	s_waitcnt vmcnt(24)
	v_lshlrev_b32_e32 v168, 16, v158
	v_and_b32_e32 v169, 0xffff0000, v158
	v_lshlrev_b32_e32 v170, 16, v159
	v_and_b32_e32 v171, 0xffff0000, v159
	v_pk_add_f32 v[192:193], v[74:75], v[168:169]
	v_pk_add_f32 v[194:195], v[76:77], v[170:171]
	v_cvt_pk_bf16_f32 v168, v192, v193
	v_cvt_pk_bf16_f32 v169, v194, v195
	global_store_dwordx2 v243, v[168:169], s[56:57] offset:160
	v_pk_mul_f32 v[192:193], v[192:193], v[192:193]
	v_pk_mul_f32 v[194:195], v[194:195], v[194:195]
	v_add_f32_e32 v170, v193, v192
	v_add_f32_e32 v170, v194, v170
	v_add_f32_e32 v170, v195, v170
	v_add_f32_e32 v164, v164, v170
	s_waitcnt vmcnt(24)
	v_lshlrev_b32_e32 v168, 16, v160
	v_and_b32_e32 v169, 0xffff0000, v160
	v_lshlrev_b32_e32 v170, 16, v161
	v_and_b32_e32 v171, 0xffff0000, v161
	v_pk_add_f32 v[192:193], v[70:71], v[168:169]
	v_pk_add_f32 v[194:195], v[72:73], v[170:171]
	v_cvt_pk_bf16_f32 v168, v192, v193
	v_cvt_pk_bf16_f32 v169, v194, v195
	global_store_dwordx2 v243, v[168:169], s[56:57] offset:192
	v_pk_mul_f32 v[192:193], v[192:193], v[192:193]
	v_pk_mul_f32 v[194:195], v[194:195], v[194:195]
	v_add_f32_e32 v170, v193, v192
	v_add_f32_e32 v170, v194, v170
	v_add_f32_e32 v170, v195, v170
	v_add_f32_e32 v164, v164, v170
	s_waitcnt vmcnt(24)
	v_lshlrev_b32_e32 v168, 16, v162
	v_and_b32_e32 v169, 0xffff0000, v162
	v_lshlrev_b32_e32 v170, 16, v163
	v_and_b32_e32 v171, 0xffff0000, v163
	v_pk_add_f32 v[192:193], v[66:67], v[168:169]
	v_pk_add_f32 v[194:195], v[68:69], v[170:171]
	v_cvt_pk_bf16_f32 v168, v192, v193
	v_cvt_pk_bf16_f32 v169, v194, v195
	global_store_dwordx2 v243, v[168:169], s[56:57] offset:224
	v_pk_mul_f32 v[192:193], v[192:193], v[192:193]
	v_pk_mul_f32 v[194:195], v[194:195], v[194:195]
	v_add_f32_e32 v170, v193, v192
	v_add_f32_e32 v170, v194, v170
	v_add_f32_e32 v170, v195, v170
	v_add_f32_e32 v164, v164, v170
	v_xor_b32_e32 v168, 16, v207
	v_lshlrev_b32_e32 v168, 2, v168
	ds_bpermute_b32 v169, v168, v164
	v_xor_b32_e32 v168, 32, v207
	v_lshlrev_b32_e32 v168, 2, v168
	s_waitcnt lgkmcnt(0)
	v_add_f32_e32 v164, v164, v169
	ds_bpermute_b32 v169, v168, v164
	v_add_u32_e32 v170, 16, v130
	v_lshlrev_b32_e32 v170, 2, v170
	v_and_b32_e32 v171, 63, v207
	v_cmp_gt_u32_e32 vcc, 16, v171
	s_waitcnt lgkmcnt(0)
	v_add_f32_e32 v164, v164, v169
	s_and_saveexec_b64 s[2:3], vcc
	global_atomic_add_f32 v170, v164, s[4:5]
	s_or_b64 exec, exec, s[2:3]
	v_add_u32_e32 v168, 48, v130
	v_lshlrev_b32_e32 v168, 11, v168
	v_lshl_add_u32 v243, v131, 1, v168
	global_load_dwordx2 v[148:149], v243, s[56:57] offset:0
	global_load_dwordx2 v[150:151], v243, s[56:57] offset:32
	global_load_dwordx2 v[152:153], v243, s[56:57] offset:64
	global_load_dwordx2 v[154:155], v243, s[56:57] offset:96
	global_load_dwordx2 v[156:157], v243, s[56:57] offset:128
	global_load_dwordx2 v[158:159], v243, s[56:57] offset:160
	global_load_dwordx2 v[160:161], v243, s[56:57] offset:192
	global_load_dwordx2 v[162:163], v243, s[56:57] offset:224
	s_waitcnt vmcnt(24)
	v_lshlrev_b32_e32 v168, 16, v132
	v_and_b32_e32 v169, 0xffff0000, v132
	v_lshlrev_b32_e32 v170, 16, v133
	v_and_b32_e32 v171, 0xffff0000, v133
	v_pk_add_f32 v[192:193], v[62:63], v[168:169]
	v_pk_add_f32 v[194:195], v[64:65], v[170:171]
	v_cvt_pk_bf16_f32 v168, v192, v193
	v_cvt_pk_bf16_f32 v169, v194, v195
	global_store_dwordx2 v242, v[168:169], s[56:57] offset:0
	v_pk_mul_f32 v[192:193], v[192:193], v[192:193]
	v_pk_mul_f32 v[194:195], v[194:195], v[194:195]
	v_add_f32_e32 v170, v193, v192
	v_add_f32_e32 v170, v194, v170
	v_add_f32_e32 v170, v195, v170
	v_mov_b32_e32 v164, v170
	s_waitcnt vmcnt(24)
; template <int MI, int NI>
; DI void resid_epilogue(const Params& p, int from_x, const f32x4 (&acc)[NI][MI], int row0, int n0, float* rowss_next, bool last, int lm, int lg) {
;     ...
;     for (int ni = 0; ni < NI; ++ni) {
;       const int n = n0 + ni * 16 + lg * 4;
;       float4 h;
;       if (from_x >= 2) {
;         const u32x2 pk = *(const u32x2*)(hbr + n);
;         h = make_float4(__uint_as_float(pk[0] << 16), __uint_as_float(pk[0] & 0xffff0000u), __uint_as_float(pk[1] << 16), __uint_as_float(pk[1] & 0xffff0000u));
;       } else h = *(const float4*)(hr + n);
;       h.x += acc[ni][mi][0]; h.y += acc[ni][mi][1]; h.z += acc[ni][mi][2]; h.w += acc[ni][mi][3];
;       if (last) *(float4*)(hw + n) = h;
;       if (!last) {
;         u32x2 pk = {pack2bf(h.x, h.y), pack2bf(h.z, h.w)};
;         *(u32x2*)(hbr + n) = pk;
;         ss += h.x * h.x + h.y * h.y + h.z * h.z + h.w * h.w;
;       }
;     }
;     if (!last) {
;       ss += __shfl_xor(ss, 16);
;       ss += __shfl_xor(ss, 32);
;       if (lg == 0) atomicAdd(rowss_next + m, ss);
	v_lshlrev_b32_e32 v168, 16, v134
	v_and_b32_e32 v169, 0xffff0000, v134
	v_lshlrev_b32_e32 v170, 16, v135
	v_and_b32_e32 v171, 0xffff0000, v135
	v_pk_add_f32 v[192:193], v[58:59], v[168:169]
	v_pk_add_f32 v[194:195], v[60:61], v[170:171]
	v_cvt_pk_bf16_f32 v168, v192, v193
	v_cvt_pk_bf16_f32 v169, v194, v195
	global_store_dwordx2 v242, v[168:169], s[56:57] offset:32
	v_pk_mul_f32 v[192:193], v[192:193], v[192:193]
	v_pk_mul_f32 v[194:195], v[194:195], v[194:195]
	v_add_f32_e32 v170, v193, v192
	v_add_f32_e32 v170, v194, v170
	v_add_f32_e32 v170, v195, v170
	v_add_f32_e32 v164, v164, v170
	s_waitcnt vmcnt(24)
	v_lshlrev_b32_e32 v168, 16, v136
	v_and_b32_e32 v169, 0xffff0000, v136
	v_lshlrev_b32_e32 v170, 16, v137
	v_and_b32_e32 v171, 0xffff0000, v137
	v_pk_add_f32 v[192:193], v[54:55], v[168:169]
	v_pk_add_f32 v[194:195], v[56:57], v[170:171]
	v_cvt_pk_bf16_f32 v168, v192, v193
	v_cvt_pk_bf16_f32 v169, v194, v195
	global_store_dwordx2 v242, v[168:169], s[56:57] offset:64
	v_pk_mul_f32 v[192:193], v[192:193], v[192:193]
	v_pk_mul_f32 v[194:195], v[194:195], v[194:195]
	v_add_f32_e32 v170, v193, v192
	v_add_f32_e32 v170, v194, v170
	v_add_f32_e32 v170, v195, v170
	v_add_f32_e32 v164, v164, v170
	s_waitcnt vmcnt(24)
	v_lshlrev_b32_e32 v168, 16, v138
	v_and_b32_e32 v169, 0xffff0000, v138
	v_lshlrev_b32_e32 v170, 16, v139
	v_and_b32_e32 v171, 0xffff0000, v139
	v_pk_add_f32 v[192:193], v[50:51], v[168:169]
	v_pk_add_f32 v[194:195], v[52:53], v[170:171]
	v_cvt_pk_bf16_f32 v168, v192, v193
	v_cvt_pk_bf16_f32 v169, v194, v195
	global_store_dwordx2 v242, v[168:169], s[56:57] offset:96
	v_pk_mul_f32 v[192:193], v[192:193], v[192:193]
	v_pk_mul_f32 v[194:195], v[194:195], v[194:195]
	v_add_f32_e32 v170, v193, v192
	v_add_f32_e32 v170, v194, v170
	v_add_f32_e32 v170, v195, v170
	v_add_f32_e32 v164, v164, v170
	s_waitcnt vmcnt(24)
	v_lshlrev_b32_e32 v168, 16, v140
	v_and_b32_e32 v169, 0xffff0000, v140
	v_lshlrev_b32_e32 v170, 16, v141
	v_and_b32_e32 v171, 0xffff0000, v141
	v_pk_add_f32 v[192:193], v[46:47], v[168:169]
	v_pk_add_f32 v[194:195], v[48:49], v[170:171]
	v_cvt_pk_bf16_f32 v168, v192, v193
	v_cvt_pk_bf16_f32 v169, v194, v195
	global_store_dwordx2 v242, v[168:169], s[56:57] offset:128
	v_pk_mul_f32 v[192:193], v[192:193], v[192:193]
	v_pk_mul_f32 v[194:195], v[194:195], v[194:195]
	v_add_f32_e32 v170, v193, v192
	v_add_f32_e32 v170, v194, v170
	v_add_f32_e32 v170, v195, v170
	v_add_f32_e32 v164, v164, v170
	s_waitcnt vmcnt(24)
	v_lshlrev_b32_e32 v168, 16, v142
	v_and_b32_e32 v169, 0xffff0000, v142
	v_lshlrev_b32_e32 v170, 16, v143
	v_and_b32_e32 v171, 0xffff0000, v143
	v_pk_add_f32 v[192:193], v[42:43], v[168:169]
	v_pk_add_f32 v[194:195], v[44:45], v[170:171]
	v_cvt_pk_bf16_f32 v168, v192, v193
	v_cvt_pk_bf16_f32 v169, v194, v195
	global_store_dwordx2 v242, v[168:169], s[56:57] offset:160
	v_pk_mul_f32 v[192:193], v[192:193], v[192:193]
	v_pk_mul_f32 v[194:195], v[194:195], v[194:195]
	v_add_f32_e32 v170, v193, v192
	v_add_f32_e32 v170, v194, v170
	v_add_f32_e32 v170, v195, v170
	v_add_f32_e32 v164, v164, v170
	s_waitcnt vmcnt(24)
	v_lshlrev_b32_e32 v168, 16, v144
	v_and_b32_e32 v169, 0xffff0000, v144
	v_lshlrev_b32_e32 v170, 16, v145
	v_and_b32_e32 v171, 0xffff0000, v145
	v_pk_add_f32 v[192:193], v[38:39], v[168:169]
	v_pk_add_f32 v[194:195], v[40:41], v[170:171]
	v_cvt_pk_bf16_f32 v168, v192, v193
	v_cvt_pk_bf16_f32 v169, v194, v195
	global_store_dwordx2 v242, v[168:169], s[56:57] offset:192
	v_pk_mul_f32 v[192:193], v[192:193], v[192:193]
	v_pk_mul_f32 v[194:195], v[194:195], v[194:195]
	v_add_f32_e32 v170, v193, v192
	v_add_f32_e32 v170, v194, v170
	v_add_f32_e32 v170, v195, v170
	v_add_f32_e32 v164, v164, v170
	s_waitcnt vmcnt(24)
	v_lshlrev_b32_e32 v168, 16, v146
	v_and_b32_e32 v169, 0xffff0000, v146
	v_lshlrev_b32_e32 v170, 16, v147
	v_and_b32_e32 v171, 0xffff0000, v147
	v_pk_add_f32 v[192:193], v[34:35], v[168:169]
	v_pk_add_f32 v[194:195], v[36:37], v[170:171]
	v_cvt_pk_bf16_f32 v168, v192, v193
	v_cvt_pk_bf16_f32 v169, v194, v195
	global_store_dwordx2 v242, v[168:169], s[56:57] offset:224
	v_pk_mul_f32 v[192:193], v[192:193], v[192:193]
	v_pk_mul_f32 v[194:195], v[194:195], v[194:195]
	v_add_f32_e32 v170, v193, v192
	v_add_f32_e32 v170, v194, v170
	v_add_f32_e32 v170, v195, v170
	v_add_f32_e32 v164, v164, v170
	v_xor_b32_e32 v168, 16, v207
	v_lshlrev_b32_e32 v168, 2, v168
	ds_bpermute_b32 v169, v168, v164
	v_xor_b32_e32 v168, 32, v207
	v_lshlrev_b32_e32 v168, 2, v168
	s_waitcnt lgkmcnt(0)
	v_add_f32_e32 v164, v164, v169
	ds_bpermute_b32 v169, v168, v164
	v_add_u32_e32 v170, 32, v130
	v_lshlrev_b32_e32 v170, 2, v170
	v_and_b32_e32 v171, 63, v207
	v_cmp_gt_u32_e32 vcc, 16, v171
	s_waitcnt lgkmcnt(0)
	v_add_f32_e32 v164, v164, v169
	s_and_saveexec_b64 s[2:3], vcc
	global_atomic_add_f32 v170, v164, s[4:5]
	s_or_b64 exec, exec, s[2:3]
	s_waitcnt vmcnt(16)
; template <int MI, int NI>
; DI void resid_epilogue(const Params& p, int from_x, const f32x4 (&acc)[NI][MI], int row0, int n0, float* rowss_next, bool last, int lm, int lg) {
;     ...
;     for (int ni = 0; ni < NI; ++ni) {
;       const int n = n0 + ni * 16 + lg * 4;
;       float4 h;
;       if (from_x >= 2) {
;         const u32x2 pk = *(const u32x2*)(hbr + n);
;         h = make_float4(__uint_as_float(pk[0] << 16), __uint_as_float(pk[0] & 0xffff0000u), __uint_as_float(pk[1] << 16), __uint_as_float(pk[1] & 0xffff0000u));
;       } else h = *(const float4*)(hr + n);
;       h.x += acc[ni][mi][0]; h.y += acc[ni][mi][1]; h.z += acc[ni][mi][2]; h.w += acc[ni][mi][3];
;       if (last) *(float4*)(hw + n) = h;
;       if (!last) {
;         u32x2 pk = {pack2bf(h.x, h.y), pack2bf(h.z, h.w)};
;         *(u32x2*)(hbr + n) = pk;
;         ss += h.x * h.x + h.y * h.y + h.z * h.z + h.w * h.w;
;       }
;     }
;     if (!last) {
;       ss += __shfl_xor(ss, 16);
;       ss += __shfl_xor(ss, 32);
;       if (lg == 0) atomicAdd(rowss_next + m, ss);
	v_lshlrev_b32_e32 v168, 16, v148
	v_and_b32_e32 v169, 0xffff0000, v148
	v_lshlrev_b32_e32 v170, 16, v149
	v_and_b32_e32 v171, 0xffff0000, v149
	v_pk_add_f32 v[192:193], v[30:31], v[168:169]
	v_pk_add_f32 v[194:195], v[32:33], v[170:171]
	v_cvt_pk_bf16_f32 v168, v192, v193
	v_cvt_pk_bf16_f32 v169, v194, v195
	global_store_dwordx2 v243, v[168:169], s[56:57] offset:0
	v_pk_mul_f32 v[192:193], v[192:193], v[192:193]
	v_pk_mul_f32 v[194:195], v[194:195], v[194:195]
	v_add_f32_e32 v170, v193, v192
	v_add_f32_e32 v170, v194, v170
	v_add_f32_e32 v170, v195, v170
	v_mov_b32_e32 v164, v170
	s_waitcnt vmcnt(16)
	v_lshlrev_b32_e32 v168, 16, v150
	v_and_b32_e32 v169, 0xffff0000, v150
	v_lshlrev_b32_e32 v170, 16, v151
	v_and_b32_e32 v171, 0xffff0000, v151
	v_pk_add_f32 v[192:193], v[26:27], v[168:169]
	v_pk_add_f32 v[194:195], v[28:29], v[170:171]
	v_cvt_pk_bf16_f32 v168, v192, v193
	v_cvt_pk_bf16_f32 v169, v194, v195
	global_store_dwordx2 v243, v[168:169], s[56:57] offset:32
	v_pk_mul_f32 v[192:193], v[192:193], v[192:193]
	v_pk_mul_f32 v[194:195], v[194:195], v[194:195]
	v_add_f32_e32 v170, v193, v192
	v_add_f32_e32 v170, v194, v170
	v_add_f32_e32 v170, v195, v170
	v_add_f32_e32 v164, v164, v170
	s_waitcnt vmcnt(16)
	v_lshlrev_b32_e32 v168, 16, v152
	v_and_b32_e32 v169, 0xffff0000, v152
	v_lshlrev_b32_e32 v170, 16, v153
	v_and_b32_e32 v171, 0xffff0000, v153
	v_pk_add_f32 v[192:193], v[22:23], v[168:169]
	v_pk_add_f32 v[194:195], v[24:25], v[170:171]
	v_cvt_pk_bf16_f32 v168, v192, v193
	v_cvt_pk_bf16_f32 v169, v194, v195
	global_store_dwordx2 v243, v[168:169], s[56:57] offset:64
	v_pk_mul_f32 v[192:193], v[192:193], v[192:193]
	v_pk_mul_f32 v[194:195], v[194:195], v[194:195]
	v_add_f32_e32 v170, v193, v192
	v_add_f32_e32 v170, v194, v170
	v_add_f32_e32 v170, v195, v170
	v_add_f32_e32 v164, v164, v170
	s_waitcnt vmcnt(16)
	v_lshlrev_b32_e32 v168, 16, v154
	v_and_b32_e32 v169, 0xffff0000, v154
	v_lshlrev_b32_e32 v170, 16, v155
	v_and_b32_e32 v171, 0xffff0000, v155
	v_pk_add_f32 v[192:193], v[18:19], v[168:169]
	v_pk_add_f32 v[194:195], v[20:21], v[170:171]
	v_cvt_pk_bf16_f32 v168, v192, v193
	v_cvt_pk_bf16_f32 v169, v194, v195
	global_store_dwordx2 v243, v[168:169], s[56:57] offset:96
	v_pk_mul_f32 v[192:193], v[192:193], v[192:193]
	v_pk_mul_f32 v[194:195], v[194:195], v[194:195]
	v_add_f32_e32 v170, v193, v192
	v_add_f32_e32 v170, v194, v170
	v_add_f32_e32 v170, v195, v170
	v_add_f32_e32 v164, v164, v170
	s_waitcnt vmcnt(16)
	v_lshlrev_b32_e32 v168, 16, v156
	v_and_b32_e32 v169, 0xffff0000, v156
	v_lshlrev_b32_e32 v170, 16, v157
	v_and_b32_e32 v171, 0xffff0000, v157
	v_pk_add_f32 v[192:193], v[14:15], v[168:169]
	v_pk_add_f32 v[194:195], v[16:17], v[170:171]
	v_cvt_pk_bf16_f32 v168, v192, v193
	v_cvt_pk_bf16_f32 v169, v194, v195
	global_store_dwordx2 v243, v[168:169], s[56:57] offset:128
	v_pk_mul_f32 v[192:193], v[192:193], v[192:193]
	v_pk_mul_f32 v[194:195], v[194:195], v[194:195]
	v_add_f32_e32 v170, v193, v192
	v_add_f32_e32 v170, v194, v170
	v_add_f32_e32 v170, v195, v170
	v_add_f32_e32 v164, v164, v170
	s_waitcnt vmcnt(16)
	v_lshlrev_b32_e32 v168, 16, v158
	v_and_b32_e32 v169, 0xffff0000, v158
	v_lshlrev_b32_e32 v170, 16, v159
	v_and_b32_e32 v171, 0xffff0000, v159
	v_pk_add_f32 v[192:193], v[10:11], v[168:169]
	v_pk_add_f32 v[194:195], v[12:13], v[170:171]
	v_cvt_pk_bf16_f32 v168, v192, v193
	v_cvt_pk_bf16_f32 v169, v194, v195
	global_store_dwordx2 v243, v[168:169], s[56:57] offset:160
	v_pk_mul_f32 v[192:193], v[192:193], v[192:193]
	v_pk_mul_f32 v[194:195], v[194:195], v[194:195]
	v_add_f32_e32 v170, v193, v192
	v_add_f32_e32 v170, v194, v170
	v_add_f32_e32 v170, v195, v170
	v_add_f32_e32 v164, v164, v170
	s_waitcnt vmcnt(16)
	v_lshlrev_b32_e32 v168, 16, v160
	v_and_b32_e32 v169, 0xffff0000, v160
	v_lshlrev_b32_e32 v170, 16, v161
	v_and_b32_e32 v171, 0xffff0000, v161
	v_pk_add_f32 v[192:193], v[6:7], v[168:169]
	v_pk_add_f32 v[194:195], v[8:9], v[170:171]
	v_cvt_pk_bf16_f32 v168, v192, v193
	v_cvt_pk_bf16_f32 v169, v194, v195
	global_store_dwordx2 v243, v[168:169], s[56:57] offset:192
	v_pk_mul_f32 v[192:193], v[192:193], v[192:193]
	v_pk_mul_f32 v[194:195], v[194:195], v[194:195]
	v_add_f32_e32 v170, v193, v192
	v_add_f32_e32 v170, v194, v170
	v_add_f32_e32 v170, v195, v170
	v_add_f32_e32 v164, v164, v170
	s_waitcnt vmcnt(16)
	v_lshlrev_b32_e32 v168, 16, v162
	v_and_b32_e32 v169, 0xffff0000, v162
	v_lshlrev_b32_e32 v170, 16, v163
	v_and_b32_e32 v171, 0xffff0000, v163
	v_pk_add_f32 v[192:193], v[2:3], v[168:169]
	v_pk_add_f32 v[194:195], v[4:5], v[170:171]
	v_cvt_pk_bf16_f32 v168, v192, v193
	v_cvt_pk_bf16_f32 v169, v194, v195
	global_store_dwordx2 v243, v[168:169], s[56:57] offset:224
	v_pk_mul_f32 v[192:193], v[192:193], v[192:193]
	v_pk_mul_f32 v[194:195], v[194:195], v[194:195]
	v_add_f32_e32 v170, v193, v192
	v_add_f32_e32 v170, v194, v170
	v_add_f32_e32 v170, v195, v170
	v_add_f32_e32 v164, v164, v170
	v_xor_b32_e32 v168, 16, v207
	v_lshlrev_b32_e32 v168, 2, v168
	ds_bpermute_b32 v169, v168, v164
	v_xor_b32_e32 v168, 32, v207
	v_lshlrev_b32_e32 v168, 2, v168
	s_waitcnt lgkmcnt(0)
	v_add_f32_e32 v164, v164, v169
	ds_bpermute_b32 v169, v168, v164
	v_add_u32_e32 v170, 48, v130
	v_lshlrev_b32_e32 v170, 2, v170
	v_and_b32_e32 v171, 63, v207
	v_cmp_gt_u32_e32 vcc, 16, v171
	s_waitcnt lgkmcnt(0)
	v_add_f32_e32 v164, v164, v169
	s_and_saveexec_b64 s[2:3], vcc
	global_atomic_add_f32 v170, v164, s[4:5]
	s_or_b64 exec, exec, s[2:3]
	s_branch .LBB0_958
